# first K-loop trip after each GEMM epilogue skips its two counted DMA waits (pieces already retired by the epilogue) so the stores drain under MFMA work; permlane swaps replace bpermute in P4/P6 row su
# baseline (speedup 1.0000x reference)
; __device__ __forceinline__ int lane_now() { int l; asm volatile("v_mbcnt_lo_u32_b32 %0, -1, 0\n\tv_mbcnt_hi_u32_b32 %0, -1, %0" : "=v"(l)); return l; }
;     __host__ __device__ bool next(int i, Unit& u) const {
;         const long L = (long)i * G + c; if (L >= nwg) return false;
;         int wgid = (int)L; { const int q = nwg / NXCD, r = nwg % NXCD, xcd = wgid % NXCD, off = wgid / NXCD; wgid = (xcd < r ? xcd * (q + 1) : r * (q + 1) + (xcd - r) * q) + off; }
;         const int nig = WGM * nN, gid = wgid / nig, fm = gid * WGM, gsz = (nM - fm) < WGM ? (nM - fm) : WGM;
;         u.pm = fm + ((wgid % nig) % gsz); u.pn = (wgid % nig) / gsz; if (rev) u.pm = nM - 1 - u.pm; return true;
; template <class Epi, class Sched, bool ALIGN_EPI = false, bool SP2 = false>
; __device__ __forceinline__ void gemm_phase(PG8_LAS unsigned char* lds, const Gemm g, const Sched& S, const Epi& E, const int wave_s) {
;     int tid_ = (wave_s << 6) | lane_now(); asm volatile("" : "+v"(tid_));
;     const int tid = tid_, wid = __builtin_amdgcn_readfirstlane(tid >> 6), lane = tid & 63, wr = wid >> 2, wc = wid & 3, fr = lane & 15, fq = lane >> 4;
.LBB0_193:
	v_writelane_b32 v255, s82, 5
	s_waitcnt lgkmcnt(0)
	s_barrier
	s_mov_b64 s[100:101], 0
	v_mbcnt_lo_u32_b32 v0, -1, 0
	v_mbcnt_hi_u32_b32 v0, -1, v0
	s_cmpk_lt_i32 s10, 0x1980
	v_or_b32_e32 v8, s84, v0
	v_writelane_b32 v255, s83, 6
	s_cselect_b64 s[2:3], -1, 0
	s_cmpk_gt_i32 s10, 0x197f
	v_readfirstlane_b32 s8, v8
	s_cbranch_scc1 .LBB0_195
	s_ashr_i32 s4, s10, 31
	s_lshr_b32 s4, s4, 29
	s_add_i32 s4, s10, s4
	s_ashr_i32 s5, s4, 3
	s_and_b32 s4, s4, -8
	s_sub_i32 s4, s10, s4
	s_cmp_lt_i32 s4, 0
	s_movk_i32 s6, 0x331
	s_cselect_b32 s6, s6, 0x330
	s_mul_i32 s4, s4, s6
	s_add_i32 s4, s4, s5
	s_mul_hi_i32 s5, s4, 0x87878787
	s_lshr_b32 s6, s5, 31
	s_ashr_i32 s5, s5, 6
	s_add_i32 s5, s5, s6
	s_mul_hi_i32 s6, s4, 0x78787879
	s_lshr_b32 s7, s6, 31
	s_ashr_i32 s6, s6, 6
	s_add_i32 s6, s6, s7
	s_mulk_i32 s6, 0x88
	s_sub_i32 s4, s4, s6
	s_sext_i32_i16 s6, s4
	s_bfe_u32 s6, s6, 0x3001c
	s_add_i32 s6, s4, s6
	s_sext_i32_i16 s7, s6
	s_and_b32 s6, s6, 0xfff8
	s_sub_i32 s4, s6, s4
	s_lshl_b32 s5, s5, 3
	s_sext_i32_i16 s4, s4
	s_add_i32 s4, s5, s4
	s_ashr_i32 s70, s7, 3
	s_addk_i32 s4, 0x17f

; #define PG8_STAGE(bufoff, gbase, voff) do { _Pragma("unroll") for (int _i = 0; _i < 2; ++_i) \
;         __builtin_amdgcn_global_load_lds((const unsigned*)((const char*)(gbase) + (voff)[_i]), (PG8_LAS unsigned*)(lds + (bufoff) + ldsw + _i * 8192), 16, 0, 0); } while (0)
; #define PG8_LDA(dst, b, h) do { _Pragma("unroll") for (int m = 0; m < 4; ++m) _Pragma("unroll") for (int k = 0; k < 2; ++k) dst[m][k] = *(const PG8_LAS bf16x8*)(lds + PG8_SA(b, h) + aoff + m * 2048 + k * 1024); } while (0)
; #define PG8_LDB(dst, b, h) do { _Pragma("unroll") for (int n = 0; n < 2; ++n) _Pragma("unroll") for (int k = 0; k < 2; ++k) dst[n][k] = *(const PG8_LAS bf16x8*)(lds + PG8_SB(b, h) + boff + n * 2048 + k * 1024); } while (0)
; #define PG8_MMA(ai, bj, At, Bt) do { __builtin_amdgcn_s_setprio(1); _Pragma("unroll") for (int m = 0; m < 4; ++m) _Pragma("unroll") for (int n = 0; n < 2; ++n) _Pragma("unroll") for (int k = 0; k < 2; ++k) \
;         acc[ai][bj][m][n] = __builtin_amdgcn_mfma_f32_16x16x32_bf16(Bt[n][k], At[m][k], acc[ai][bj][m][n], 0, 0, 0); __builtin_amdgcn_s_setprio(0); } while (0)
; #define PG8_WAIT_V(n) asm volatile("s_waitcnt vmcnt(" #n ")" ::: "memory")
; #define PG8_WAIT_L(n) asm volatile("s_waitcnt lgkmcnt(" #n ")" ::: "memory")
; #define PG8_BAR __builtin_amdgcn_s_barrier()
; #define PG8_SCHED __builtin_amdgcn_sched_barrier(0)
; template <class Epi, class Sched, bool ALIGN_EPI = false, bool SP2 = false>
; __device__ __forceinline__ void gemm_phase(PG8_LAS unsigned char* lds, const Gemm g, const Sched& S, const Epi& E, const int wave_s) {
;     ...
;             PG8_LDB(B0, 0, 0); PG8_LDB(B1, 0, 1); PG8_SCHED; PG8_LDA(At, 0, 0); PG8_STAGE(PG8_SA(1, 1), a1 + hA, voffA);
;             PG8_WAIT_V(8); PG8_WAIT_L(0); PG8_BAR; PG8_MMA(0, 0, At, B0); PG8_MMA(0, 1, At, B1); PG8_BAR; PG8_SCHED;
;             PG8_LDA(At, 0, 1); PG8_STAGE(PG8_SB(0, 0), b2, voffB); PG8_STAGE(PG8_SB(0, 1), b2 + hB, voffB); PG8_STAGE(PG8_SA(0, 0), a2, voffA);
;             PG8_WAIT_V(8); PG8_WAIT_L(0); PG8_BAR; PG8_MMA(1, 0, At, B0); PG8_MMA(1, 1, At, B1); PG8_BAR; PG8_SCHED;
.LBB0_204:
	v_add_u32_e32 v126, s93, v185
	ds_read_b128 v[114:117], v126
	ds_read_b128 v[118:121], v126 offset:1024
	ds_read_b128 v[122:125], v126 offset:2048
	ds_read_b128 v[144:147], v126 offset:3072
	v_add_u32_e32 v126, s94, v185
	ds_read_b128 v[148:151], v126
	ds_read_b128 v[176:179], v126 offset:1024
	ds_read_b128 v[202:205], v126 offset:2048
	ds_read_b128 v[206:209], v126 offset:3072
	s_add_u32 s63, s6, 0xfffc0080
	s_addc_u32 s65, s7, -1
	s_and_b64 s[72:73], s[72:73], exec
	s_cselect_b32 s75, s5, s65
	s_cselect_b32 s74, s8, s63
	s_cselect_b32 s73, s9, s34
	s_cselect_b32 s72, s12, s13
	v_lshl_add_u64 v[126:127], s[6:7], 0, v[168:169]
	s_add_i32 m0, s71, 0xc000
	ds_read_b128 v[210:213], v189
	ds_read_b128 v[214:217], v189 offset:1024
	ds_read_b128 v[218:221], v189 offset:2048
	ds_read_b128 v[222:225], v189 offset:3072
	ds_read_b128 v[226:229], v189 offset:4096
	ds_read_b128 v[230:233], v189 offset:5120
	ds_read_b128 v[234:237], v189 offset:6144
	ds_read_b128 v[238:241], v189 offset:7168
	global_load_lds_dwordx4 v[126:127], off
	v_lshl_add_u64 v[126:127], s[6:7], 0, v[170:171]
	s_add_i32 m0, s71, 0xe000
	s_nop 0
	global_load_lds_dwordx4 v[126:127], off
	s_mov_b64 vcc, s[100:101]
	s_cbranch_vccnz .Lrlx_P1_0
	s_waitcnt vmcnt(8)
.Lrlx_P1_0:
	s_waitcnt lgkmcnt(0)
	s_barrier
	s_setprio 1
	s_waitcnt lgkmcnt(0)
	v_mfma_f32_16x16x32_bf16 v[140:143], v[114:117], v[210:213], v[140:143]
	v_mfma_f32_16x16x32_bf16 v[136:139], v[122:125], v[210:213], v[136:139]
	v_mfma_f32_16x16x32_bf16 v[108:111], v[114:117], v[218:221], v[108:111]
	v_mfma_f32_16x16x32_bf16 v[104:107], v[122:125], v[218:221], v[104:107]
	v_mfma_f32_16x16x32_bf16 v[92:95], v[114:117], v[226:229], v[92:95]
	v_mfma_f32_16x16x32_bf16 v[88:91], v[122:125], v[226:229], v[88:91]
	v_mfma_f32_16x16x32_bf16 v[76:79], v[114:117], v[234:237], v[76:79]
	v_mfma_f32_16x16x32_bf16 v[72:75], v[122:125], v[234:237], v[72:75]
	v_mfma_f32_16x16x32_bf16 v[140:143], v[118:121], v[214:217], v[140:143]
	v_mfma_f32_16x16x32_bf16 v[136:139], v[144:147], v[214:217], v[136:139]
	v_mfma_f32_16x16x32_bf16 v[108:111], v[118:121], v[222:225], v[108:111]
	v_mfma_f32_16x16x32_bf16 v[104:107], v[144:147], v[222:225], v[104:107]
	v_mfma_f32_16x16x32_bf16 v[92:95], v[118:121], v[230:233], v[92:95]
	v_mfma_f32_16x16x32_bf16 v[88:91], v[144:147], v[230:233], v[88:91]
	v_mfma_f32_16x16x32_bf16 v[76:79], v[118:121], v[238:241], v[76:79]
	v_mfma_f32_16x16x32_bf16 v[72:75], v[144:147], v[238:241], v[72:75]
	s_setprio 0
	s_setprio 1
	v_mfma_f32_16x16x32_bf16 v[132:135], v[148:151], v[210:213], v[132:135]
	v_mfma_f32_16x16x32_bf16 v[126:129], v[202:205], v[210:213], v[128:131]
	v_mfma_f32_16x16x32_bf16 v[100:103], v[148:151], v[218:221], v[100:103]
	v_mfma_f32_16x16x32_bf16 v[96:99], v[202:205], v[218:221], v[96:99]
	v_mfma_f32_16x16x32_bf16 v[84:87], v[148:151], v[226:229], v[84:87]
	v_mfma_f32_16x16x32_bf16 v[80:83], v[202:205], v[226:229], v[80:83]
	v_mfma_f32_16x16x32_bf16 v[68:71], v[148:151], v[234:237], v[68:71]
	v_mfma_f32_16x16x32_bf16 v[64:67], v[202:205], v[234:237], v[64:67]
	v_mfma_f32_16x16x32_bf16 v[132:135], v[176:179], v[214:217], v[132:135]
	v_mfma_f32_16x16x32_bf16 v[126:129], v[206:209], v[214:217], v[126:129]
	v_mfma_f32_16x16x32_bf16 v[100:103], v[176:179], v[222:225], v[100:103]
	v_mfma_f32_16x16x32_bf16 v[96:99], v[206:209], v[222:225], v[96:99]
	v_mfma_f32_16x16x32_bf16 v[84:87], v[176:179], v[230:233], v[84:87]
	v_mfma_f32_16x16x32_bf16 v[80:83], v[206:209], v[230:233], v[80:83]
	v_mfma_f32_16x16x32_bf16 v[68:71], v[176:179], v[238:241], v[68:71]
	v_mfma_f32_16x16x32_bf16 v[64:67], v[206:209], v[238:241], v[64:67]
	s_setprio 0
	s_barrier
	s_add_i32 s63, s93, s31
	v_lshl_add_u64 v[180:181], s[72:73], 0, v[154:155]
	s_mov_b32 m0, s63
	ds_read_b128 v[210:213], v189 offset:16384
	ds_read_b128 v[214:217], v189 offset:17408
	ds_read_b128 v[218:221], v189 offset:18432
	ds_read_b128 v[222:225], v189 offset:19456
	ds_read_b128 v[226:229], v189 offset:20480
	ds_read_b128 v[230:233], v189 offset:21504
	ds_read_b128 v[234:237], v189 offset:22528
	ds_read_b128 v[238:241], v189 offset:23552
	global_load_lds_dwordx4 v[180:181], off
	s_add_i32 m0, s63, 0x2000
	s_add_u32 s76, s72, 0x40000
	v_lshl_add_u64 v[242:243], s[72:73], 0, v[158:159]
	s_addc_u32 s77, s73, 0
	s_add_i32 s63, s94, s31
	global_load_lds_dwordx4 v[242:243], off
	v_lshl_add_u64 v[130:131], s[76:77], 0, v[154:155]
	s_mov_b32 m0, s63
	v_lshl_add_u64 v[244:245], s[74:75], 0, v[152:153]
	global_load_lds_dwordx4 v[130:131], off
	v_lshl_add_u64 v[130:131], s[76:77], 0, v[158:159]
	s_add_i32 m0, s63, 0x2000
	v_lshl_add_u64 v[246:247], s[74:75], 0, v[156:157]
	global_load_lds_dwordx4 v[130:131], off
	s_mov_b32 m0, s71
	s_nop 0
	global_load_lds_dwordx4 v[244:245], off
	s_mov_b32 m0, s78
	s_nop 0
	global_load_lds_dwordx4 v[246:247], off
	s_mov_b64 vcc, s[100:101]
	s_cbranch_vccnz .Lrlx_P1_1
	s_waitcnt vmcnt(8)
; #define PG8_STAGE(bufoff, gbase, voff) do { _Pragma("unroll") for (int _i = 0; _i < 2; ++_i) \
;         __builtin_amdgcn_global_load_lds((const unsigned*)((const char*)(gbase) + (voff)[_i]), (PG8_LAS unsigned*)(lds + (bufoff) + ldsw + _i * 8192), 16, 0, 0); } while (0)
; #define PG8_LDA(dst, b, h) do { _Pragma("unroll") for (int m = 0; m < 4; ++m) _Pragma("unroll") for (int k = 0; k < 2; ++k) dst[m][k] = *(const PG8_LAS bf16x8*)(lds + PG8_SA(b, h) + aoff + m * 2048 + k * 1024); } while (0)
; #define PG8_LDB(dst, b, h) do { _Pragma("unroll") for (int n = 0; n < 2; ++n) _Pragma("unroll") for (int k = 0; k < 2; ++k) dst[n][k] = *(const PG8_LAS bf16x8*)(lds + PG8_SB(b, h) + boff + n * 2048 + k * 1024); } while (0)
; #define PG8_MMA(ai, bj, At, Bt) do { __builtin_amdgcn_s_setprio(1); _Pragma("unroll") for (int m = 0; m < 4; ++m) _Pragma("unroll") for (int n = 0; n < 2; ++n) _Pragma("unroll") for (int k = 0; k < 2; ++k) \
;         acc[ai][bj][m][n] = __builtin_amdgcn_mfma_f32_16x16x32_bf16(Bt[n][k], At[m][k], acc[ai][bj][m][n], 0, 0, 0); __builtin_amdgcn_s_setprio(0); } while (0)
; #define PG8_WAIT_V(n) asm volatile("s_waitcnt vmcnt(" #n ")" ::: "memory")
; #define PG8_WAIT_L(n) asm volatile("s_waitcnt lgkmcnt(" #n ")" ::: "memory")
; #define PG8_BAR __builtin_amdgcn_s_barrier()
; #define PG8_SCHED __builtin_amdgcn_sched_barrier(0)
; template <class Epi, class Sched, bool ALIGN_EPI = false, bool SP2 = false>
; __device__ __forceinline__ void gemm_phase(PG8_LAS unsigned char* lds, const Gemm g, const Sched& S, const Epi& E, const int wave_s) {
;     ...
;             PG8_WAIT_V(8); PG8_WAIT_L(0); PG8_BAR; PG8_MMA(1, 0, At, B0); PG8_MMA(1, 1, At, B1); PG8_BAR; PG8_SCHED;
;             PG8_LDB(B0, 1, 0); PG8_LDB(B1, 1, 1); PG8_SCHED; PG8_LDA(At, 1, 0); PG8_STAGE(PG8_SA(0, 1), a2 + hA, voffA);
;             PG8_WAIT_V(8); PG8_WAIT_L(0); PG8_BAR; PG8_MMA(0, 0, At, B0); PG8_MMA(0, 1, At, B1); PG8_BAR; PG8_SCHED;
.Lrlx_P1_1:
	s_mov_b64 s[100:101], 0
	s_waitcnt lgkmcnt(0)
	s_barrier
	s_setprio 1
	s_waitcnt lgkmcnt(0)
	v_mfma_f32_16x16x32_bf16 v[60:63], v[114:117], v[210:213], v[60:63]
	v_mfma_f32_16x16x32_bf16 v[56:59], v[122:125], v[210:213], v[56:59]
	v_mfma_f32_16x16x32_bf16 v[44:47], v[114:117], v[218:221], v[44:47]
	v_mfma_f32_16x16x32_bf16 v[40:43], v[122:125], v[218:221], v[40:43]
	v_mfma_f32_16x16x32_bf16 v[28:31], v[114:117], v[226:229], v[28:31]
	v_mfma_f32_16x16x32_bf16 v[24:27], v[122:125], v[226:229], v[24:27]
	v_mfma_f32_16x16x32_bf16 v[12:15], v[114:117], v[234:237], v[12:15]
	v_mfma_f32_16x16x32_bf16 v[8:11], v[122:125], v[234:237], v[8:11]
	v_mfma_f32_16x16x32_bf16 v[60:63], v[118:121], v[214:217], v[60:63]
	v_mfma_f32_16x16x32_bf16 v[56:59], v[144:147], v[214:217], v[56:59]
	v_mfma_f32_16x16x32_bf16 v[44:47], v[118:121], v[222:225], v[44:47]
	v_mfma_f32_16x16x32_bf16 v[40:43], v[144:147], v[222:225], v[40:43]
	v_mfma_f32_16x16x32_bf16 v[28:31], v[118:121], v[230:233], v[28:31]
	v_mfma_f32_16x16x32_bf16 v[24:27], v[144:147], v[230:233], v[24:27]
	v_mfma_f32_16x16x32_bf16 v[12:15], v[118:121], v[238:241], v[12:15]
	v_mfma_f32_16x16x32_bf16 v[8:11], v[144:147], v[238:241], v[8:11]
	s_setprio 0
	s_setprio 1
	v_mfma_f32_16x16x32_bf16 v[52:55], v[148:151], v[210:213], v[52:55]
	v_mfma_f32_16x16x32_bf16 v[48:51], v[202:205], v[210:213], v[48:51]
	v_mfma_f32_16x16x32_bf16 v[36:39], v[148:151], v[218:221], v[36:39]
	v_mfma_f32_16x16x32_bf16 v[32:35], v[202:205], v[218:221], v[32:35]
	v_mfma_f32_16x16x32_bf16 v[20:23], v[148:151], v[226:229], v[20:23]
	v_mfma_f32_16x16x32_bf16 v[16:19], v[202:205], v[226:229], v[16:19]
	v_mfma_f32_16x16x32_bf16 v[4:7], v[148:151], v[234:237], v[4:7]
	v_mfma_f32_16x16x32_bf16 v[0:3], v[202:205], v[234:237], v[0:3]
	v_mfma_f32_16x16x32_bf16 v[52:55], v[176:179], v[214:217], v[52:55]
	v_mfma_f32_16x16x32_bf16 v[48:51], v[206:209], v[214:217], v[48:51]
	v_mfma_f32_16x16x32_bf16 v[36:39], v[176:179], v[222:225], v[36:39]
	v_mfma_f32_16x16x32_bf16 v[32:35], v[206:209], v[222:225], v[32:35]
	v_mfma_f32_16x16x32_bf16 v[20:23], v[176:179], v[230:233], v[20:23]
	v_mfma_f32_16x16x32_bf16 v[16:19], v[206:209], v[230:233], v[16:19]
	v_mfma_f32_16x16x32_bf16 v[4:7], v[176:179], v[238:241], v[4:7]
	v_mfma_f32_16x16x32_bf16 v[0:3], v[206:209], v[238:241], v[0:3]
	s_setprio 0
	s_barrier
	s_add_i32 s63, 0, 0x18000
	v_add_u32_e32 v130, s63, v185
	s_add_i32 s65, 0, 0x1c000
	ds_read_b128 v[114:117], v130
	ds_read_b128 v[118:121], v130 offset:1024
	ds_read_b128 v[122:125], v130 offset:2048
	ds_read_b128 v[144:147], v130 offset:3072
	v_add_u32_e32 v130, s65, v185
	ds_read_b128 v[148:151], v130
	ds_read_b128 v[176:179], v130 offset:1024
	ds_read_b128 v[202:205], v130 offset:2048
	ds_read_b128 v[206:209], v130 offset:3072
	s_add_u32 s74, s74, 0x40000
	s_addc_u32 s75, s75, 0
	s_mov_b32 m0, s79
	v_lshl_add_u64 v[130:131], s[74:75], 0, v[152:153]
	ds_read_b128 v[210:213], v189 offset:32768
	ds_read_b128 v[214:217], v189 offset:33792
	ds_read_b128 v[218:221], v189 offset:34816
	ds_read_b128 v[222:225], v189 offset:35840
	ds_read_b128 v[226:229], v189 offset:36864
	ds_read_b128 v[230:233], v189 offset:37888
	ds_read_b128 v[234:237], v189 offset:38912
	ds_read_b128 v[238:241], v189 offset:39936
	global_load_lds_dwordx4 v[130:131], off
	v_lshl_add_u64 v[130:131], s[74:75], 0, v[156:157]
	s_mov_b32 m0, s80
	s_nop 0
	global_load_lds_dwordx4 v[130:131], off
	s_waitcnt vmcnt(8)
	s_waitcnt lgkmcnt(0)
	s_barrier
	s_setprio 1
	s_waitcnt lgkmcnt(0)
	v_mfma_f32_16x16x32_bf16 v[140:143], v[114:117], v[210:213], v[140:143]
	v_mfma_f32_16x16x32_bf16 v[136:139], v[122:125], v[210:213], v[136:139]
	v_mfma_f32_16x16x32_bf16 v[108:111], v[114:117], v[218:221], v[108:111]
	v_mfma_f32_16x16x32_bf16 v[104:107], v[122:125], v[218:221], v[104:107]
	v_mfma_f32_16x16x32_bf16 v[92:95], v[114:117], v[226:229], v[92:95]
	v_mfma_f32_16x16x32_bf16 v[88:91], v[122:125], v[226:229], v[88:91]
	v_mfma_f32_16x16x32_bf16 v[76:79], v[114:117], v[234:237], v[76:79]
	v_mfma_f32_16x16x32_bf16 v[72:75], v[122:125], v[234:237], v[72:75]
	v_mfma_f32_16x16x32_bf16 v[140:143], v[118:121], v[214:217], v[140:143]
	v_mfma_f32_16x16x32_bf16 v[136:139], v[144:147], v[214:217], v[136:139]
	v_mfma_f32_16x16x32_bf16 v[108:111], v[118:121], v[222:225], v[108:111]
	v_mfma_f32_16x16x32_bf16 v[104:107], v[144:147], v[222:225], v[104:107]
	v_mfma_f32_16x16x32_bf16 v[92:95], v[118:121], v[230:233], v[92:95]
	v_mfma_f32_16x16x32_bf16 v[88:91], v[144:147], v[230:233], v[88:91]
	v_mfma_f32_16x16x32_bf16 v[76:79], v[118:121], v[238:241], v[76:79]
	v_mfma_f32_16x16x32_bf16 v[72:75], v[144:147], v[238:241], v[72:75]
	s_setprio 0
	s_setprio 1
	v_mfma_f32_16x16x32_bf16 v[130:133], v[148:151], v[210:213], v[132:135]
	v_mfma_f32_16x16x32_bf16 v[126:129], v[202:205], v[210:213], v[126:129]
	v_mfma_f32_16x16x32_bf16 v[100:103], v[148:151], v[218:221], v[100:103]
	v_mfma_f32_16x16x32_bf16 v[96:99], v[202:205], v[218:221], v[96:99]
	v_mfma_f32_16x16x32_bf16 v[84:87], v[148:151], v[226:229], v[84:87]
	v_mfma_f32_16x16x32_bf16 v[80:83], v[202:205], v[226:229], v[80:83]
	v_mfma_f32_16x16x32_bf16 v[68:71], v[148:151], v[234:237], v[68:71]
	v_mfma_f32_16x16x32_bf16 v[64:67], v[202:205], v[234:237], v[64:67]
	v_mfma_f32_16x16x32_bf16 v[132:135], v[176:179], v[214:217], v[130:133]
	v_mfma_f32_16x16x32_bf16 v[128:131], v[206:209], v[214:217], v[126:129]
	v_mfma_f32_16x16x32_bf16 v[100:103], v[176:179], v[222:225], v[100:103]
	v_mfma_f32_16x16x32_bf16 v[96:99], v[206:209], v[222:225], v[96:99]
	v_mfma_f32_16x16x32_bf16 v[84:87], v[176:179], v[230:233], v[84:87]
	v_mfma_f32_16x16x32_bf16 v[80:83], v[206:209], v[230:233], v[80:83]
	v_mfma_f32_16x16x32_bf16 v[68:71], v[176:179], v[238:241], v[68:71]
	v_mfma_f32_16x16x32_bf16 v[64:67], v[206:209], v[238:241], v[64:67]
	s_setprio 0
	s_barrier
; #define PG8_STAGE(bufoff, gbase, voff) do { _Pragma("unroll") for (int _i = 0; _i < 2; ++_i) \
;         __builtin_amdgcn_global_load_lds((const unsigned*)((const char*)(gbase) + (voff)[_i]), (PG8_LAS unsigned*)(lds + (bufoff) + ldsw + _i * 8192), 16, 0, 0); } while (0)
; #define PG8_LDA(dst, b, h) do { _Pragma("unroll") for (int m = 0; m < 4; ++m) _Pragma("unroll") for (int k = 0; k < 2; ++k) dst[m][k] = *(const PG8_LAS bf16x8*)(lds + PG8_SA(b, h) + aoff + m * 2048 + k * 1024); } while (0)
; #define PG8_MMA(ai, bj, At, Bt) do { __builtin_amdgcn_s_setprio(1); _Pragma("unroll") for (int m = 0; m < 4; ++m) _Pragma("unroll") for (int n = 0; n < 2; ++n) _Pragma("unroll") for (int k = 0; k < 2; ++k) \
;         acc[ai][bj][m][n] = __builtin_amdgcn_mfma_f32_16x16x32_bf16(Bt[n][k], At[m][k], acc[ai][bj][m][n], 0, 0, 0); __builtin_amdgcn_s_setprio(0); } while (0)
; #define PG8_WAIT_V(n) asm volatile("s_waitcnt vmcnt(" #n ")" ::: "memory")
; #define PG8_WAIT_L(n) asm volatile("s_waitcnt lgkmcnt(" #n ")" ::: "memory")
; #define PG8_BAR __builtin_amdgcn_s_barrier()
; #define PG8_SCHED __builtin_amdgcn_sched_barrier(0)
; template <class Epi, class Sched, bool ALIGN_EPI = false, bool SP2 = false>
; __device__ __forceinline__ void gemm_phase(PG8_LAS unsigned char* lds, const Gemm g, const Sched& S, const Epi& E, const int wave_s) {
;     ...
;         for (int t = 0; t < nt; t += 2) {
;     ...
;             PG8_LDA(At, 1, 1); PG8_STAGE(PG8_SB(1, 0), b3, voffB); PG8_STAGE(PG8_SB(1, 1), b3 + hB, voffB); PG8_STAGE(PG8_SA(1, 0), a3, voffA);
;             PG8_WAIT_V(8); PG8_WAIT_L(0); PG8_BAR; PG8_MMA(1, 0, At, B0); PG8_MMA(1, 1, At, B1); PG8_BAR; PG8_SCHED;
	s_add_i32 s63, s63, s31
	v_lshl_add_u64 v[126:127], v[180:181], 0, s[38:39]
	s_mov_b32 m0, s63
	ds_read_b128 v[210:213], v189 offset:49152
	ds_read_b128 v[214:217], v189 offset:50176
	ds_read_b128 v[218:221], v189 offset:51200
	ds_read_b128 v[222:225], v189 offset:52224
	ds_read_b128 v[226:229], v189 offset:53248
	ds_read_b128 v[230:233], v189 offset:54272
	ds_read_b128 v[234:237], v189 offset:55296
	ds_read_b128 v[238:241], v189 offset:56320
	global_load_lds_dwordx4 v[126:127], off
	s_add_i32 m0, s63, 0x2000
	s_add_u32 s72, s72, 0x40080
	v_lshl_add_u64 v[126:127], v[242:243], 0, s[38:39]
	s_addc_u32 s73, s73, 0
	s_add_i32 s63, s65, s31
	global_load_lds_dwordx4 v[126:127], off
	v_lshl_add_u64 v[126:127], s[72:73], 0, v[154:155]
	s_mov_b32 m0, s63
	s_nop 0
	global_load_lds_dwordx4 v[126:127], off
	v_lshl_add_u64 v[126:127], s[72:73], 0, v[158:159]
	s_add_i32 m0, s63, 0x2000
	s_nop 0
	global_load_lds_dwordx4 v[126:127], off
	v_lshl_add_u64 v[126:127], v[244:245], 0, s[38:39]
	s_mov_b32 m0, s83
	s_nop 0
	global_load_lds_dwordx4 v[126:127], off
	v_lshl_add_u64 v[126:127], v[246:247], 0, s[38:39]
	s_mov_b32 m0, s88
	s_nop 0
	global_load_lds_dwordx4 v[126:127], off
	s_waitcnt vmcnt(8)
	s_waitcnt lgkmcnt(0)
	s_barrier
	s_setprio 1
	s_waitcnt lgkmcnt(0)
	v_mfma_f32_16x16x32_bf16 v[60:63], v[114:117], v[210:213], v[60:63]
	v_mfma_f32_16x16x32_bf16 v[56:59], v[122:125], v[210:213], v[56:59]
	v_mfma_f32_16x16x32_bf16 v[44:47], v[114:117], v[218:221], v[44:47]
	v_mfma_f32_16x16x32_bf16 v[40:43], v[122:125], v[218:221], v[40:43]
	v_mfma_f32_16x16x32_bf16 v[28:31], v[114:117], v[226:229], v[28:31]
	v_mfma_f32_16x16x32_bf16 v[24:27], v[122:125], v[226:229], v[24:27]
	v_mfma_f32_16x16x32_bf16 v[12:15], v[114:117], v[234:237], v[12:15]
	v_mfma_f32_16x16x32_bf16 v[8:11], v[122:125], v[234:237], v[8:11]
	v_mfma_f32_16x16x32_bf16 v[60:63], v[118:121], v[214:217], v[60:63]
	v_mfma_f32_16x16x32_bf16 v[56:59], v[144:147], v[214:217], v[56:59]
	v_mfma_f32_16x16x32_bf16 v[44:47], v[118:121], v[222:225], v[44:47]
	v_mfma_f32_16x16x32_bf16 v[40:43], v[144:147], v[222:225], v[40:43]
	v_mfma_f32_16x16x32_bf16 v[28:31], v[118:121], v[230:233], v[28:31]
	v_mfma_f32_16x16x32_bf16 v[24:27], v[144:147], v[230:233], v[24:27]
	v_mfma_f32_16x16x32_bf16 v[12:15], v[118:121], v[238:241], v[12:15]
	v_mfma_f32_16x16x32_bf16 v[8:11], v[144:147], v[238:241], v[8:11]
	s_setprio 0
	s_setprio 1
	v_mfma_f32_16x16x32_bf16 v[52:55], v[148:151], v[210:213], v[52:55]
	v_mfma_f32_16x16x32_bf16 v[48:51], v[202:205], v[210:213], v[48:51]
	v_mfma_f32_16x16x32_bf16 v[36:39], v[148:151], v[218:221], v[36:39]
	v_mfma_f32_16x16x32_bf16 v[32:35], v[202:205], v[218:221], v[32:35]
	v_mfma_f32_16x16x32_bf16 v[20:23], v[148:151], v[226:229], v[20:23]
	v_mfma_f32_16x16x32_bf16 v[16:19], v[202:205], v[226:229], v[16:19]
	v_mfma_f32_16x16x32_bf16 v[4:7], v[148:151], v[234:237], v[4:7]
	v_mfma_f32_16x16x32_bf16 v[0:3], v[202:205], v[234:237], v[0:3]
	v_mfma_f32_16x16x32_bf16 v[52:55], v[176:179], v[214:217], v[52:55]
	v_mfma_f32_16x16x32_bf16 v[48:51], v[206:209], v[214:217], v[48:51]
	v_mfma_f32_16x16x32_bf16 v[36:39], v[176:179], v[222:225], v[36:39]
	v_mfma_f32_16x16x32_bf16 v[32:35], v[206:209], v[222:225], v[32:35]
	v_mfma_f32_16x16x32_bf16 v[20:23], v[176:179], v[230:233], v[20:23]
	v_mfma_f32_16x16x32_bf16 v[16:19], v[206:209], v[230:233], v[16:19]
	v_mfma_f32_16x16x32_bf16 v[4:7], v[176:179], v[238:241], v[4:7]
	v_mfma_f32_16x16x32_bf16 v[0:3], v[206:209], v[238:241], v[0:3]
	s_setprio 0
	s_barrier
	s_add_i32 s35, s35, 2
	s_add_u32 s6, s6, 0x100
	s_addc_u32 s7, s7, 0
	s_add_u32 s13, s13, 0x100
	s_addc_u32 s34, s34, 0
	s_cmp_gt_u32 s35, 13
	s_cbranch_scc1 .LBB0_207

; #define PG8_BAR __builtin_amdgcn_s_barrier()
; template <class Epi, class Sched, bool ALIGN_EPI = false, bool SP2 = false>
; __device__ __forceinline__ void gemm_phase(PG8_LAS unsigned char* lds, const Gemm g, const Sched& S, const Epi& E, const int wave_s) {
;     ...
;         if constexpr (ALIGN_EPI) { if (wr == 0) PG8_BAR; }
.LBB0_207:
	s_mov_b64 s[100:101], -1
	s_and_b64 vcc, exec, s[42:43]
	s_cbranch_vccz .LBB0_209
	s_barrier

; __device__ __forceinline__ int lane_now() { int l; asm volatile("v_mbcnt_lo_u32_b32 %0, -1, 0\n\tv_mbcnt_hi_u32_b32 %0, -1, %0" : "=v"(l)); return l; }
; template <class Epi, class Sched, bool ALIGN_EPI = false, bool SP2 = false>
; __device__ __forceinline__ void gemm_phase(PG8_LAS unsigned char* lds, const Gemm g, const Sched& S, const Epi& E, const int wave_s) {
;     int tid_ = (wave_s << 6) | lane_now(); asm volatile("" : "+v"(tid_));
;     const int tid = tid_, wid = __builtin_amdgcn_readfirstlane(tid >> 6), lane = tid & 63, wr = wid >> 2, wc = wid & 3, fr = lane & 15, fq = lane >> 4;
.LBB0_613:
	s_waitcnt lgkmcnt(0)
	s_barrier
	s_mov_b64 s[100:101], 0
	s_bfe_u32 s3, s10, 0x10004
	s_cmp_eq_u32 s3, 0
	s_cbranch_scc1 .Lstag_P3_done
	s_lshl_b32 s3, s3, 1

; #define PG8_STAGE(bufoff, gbase, voff) do { _Pragma("unroll") for (int _i = 0; _i < 2; ++_i) \
;         __builtin_amdgcn_global_load_lds((const unsigned*)((const char*)(gbase) + (voff)[_i]), (PG8_LAS unsigned*)(lds + (bufoff) + ldsw + _i * 8192), 16, 0, 0); } while (0)
; #define PG8_LDA(dst, b, h) do { _Pragma("unroll") for (int m = 0; m < 4; ++m) _Pragma("unroll") for (int k = 0; k < 2; ++k) dst[m][k] = *(const PG8_LAS bf16x8*)(lds + PG8_SA(b, h) + aoff + m * 2048 + k * 1024); } while (0)
; #define PG8_LDB(dst, b, h) do { _Pragma("unroll") for (int n = 0; n < 2; ++n) _Pragma("unroll") for (int k = 0; k < 2; ++k) dst[n][k] = *(const PG8_LAS bf16x8*)(lds + PG8_SB(b, h) + boff + n * 2048 + k * 1024); } while (0)
; #define PG8_MMA(ai, bj, At, Bt) do { __builtin_amdgcn_s_setprio(1); _Pragma("unroll") for (int m = 0; m < 4; ++m) _Pragma("unroll") for (int n = 0; n < 2; ++n) _Pragma("unroll") for (int k = 0; k < 2; ++k) \
;         acc[ai][bj][m][n] = __builtin_amdgcn_mfma_f32_16x16x32_bf16(Bt[n][k], At[m][k], acc[ai][bj][m][n], 0, 0, 0); __builtin_amdgcn_s_setprio(0); } while (0)
; #define PG8_WAIT_V(n) asm volatile("s_waitcnt vmcnt(" #n ")" ::: "memory")
; #define PG8_WAIT_L(n) asm volatile("s_waitcnt lgkmcnt(" #n ")" ::: "memory")
; #define PG8_BAR __builtin_amdgcn_s_barrier()
; #define PG8_SCHED __builtin_amdgcn_sched_barrier(0)
; template <class Epi, class Sched, bool ALIGN_EPI = false, bool SP2 = false>
; __device__ __forceinline__ void gemm_phase(PG8_LAS unsigned char* lds, const Gemm g, const Sched& S, const Epi& E, const int wave_s) {
;     ...
;             PG8_LDB(B0, 0, 0); PG8_LDB(B1, 0, 1); PG8_SCHED; PG8_LDA(At, 0, 0); PG8_STAGE(PG8_SA(1, 1), a1 + hA, voffA);
;             PG8_WAIT_V(8); PG8_WAIT_L(0); PG8_BAR; PG8_MMA(0, 0, At, B0); PG8_MMA(0, 1, At, B1); PG8_BAR; PG8_SCHED;
;             PG8_LDA(At, 0, 1); PG8_STAGE(PG8_SB(0, 0), b2, voffB); PG8_STAGE(PG8_SB(0, 1), b2 + hB, voffB); PG8_STAGE(PG8_SA(0, 0), a2, voffA);
;             PG8_WAIT_V(8); PG8_WAIT_L(0); PG8_BAR; PG8_MMA(1, 0, At, B0); PG8_MMA(1, 1, At, B1); PG8_BAR; PG8_SCHED;
.LBB0_622:
	s_add_u32 s8, s64, s66
	s_addc_u32 s9, s65, s67
	s_add_u32 s8, s8, 0x100
	s_addc_u32 s9, s9, 0
	s_add_u32 s68, s92, s66
	s_addc_u32 s69, s93, s67
	s_add_i32 s95, 0, 0x10000
	v_add_u32_e32 v164, s95, v154
	v_add_u32_e32 v180, s89, v154
	ds_read_b128 v[128:131], v164
	ds_read_b128 v[156:159], v164 offset:1024
	ds_read_b128 v[160:163], v164 offset:2048
	ds_read_b128 v[164:167], v164 offset:3072
	ds_read_b128 v[168:171], v180
	ds_read_b128 v[172:175], v180 offset:1024
	ds_read_b128 v[176:179], v180 offset:2048
	ds_read_b128 v[180:183], v180 offset:3072
	s_cmpk_eq_i32 s66, 0x700
	s_cselect_b32 s71, s34, s9
	s_cselect_b32 s70, s35, s8
	s_cselect_b32 s69, s90, s69
	s_cselect_b32 s68, s91, s68
	v_lshl_add_u64 v[212:213], v[148:149], 0, s[66:67]
	s_add_i32 m0, s75, 0xc000
	ds_read_b128 v[184:187], v155
	ds_read_b128 v[188:191], v155 offset:1024
	ds_read_b128 v[192:195], v155 offset:2048
	ds_read_b128 v[196:199], v155 offset:3072
	ds_read_b128 v[200:203], v155 offset:4096
	ds_read_b128 v[204:207], v155 offset:5120
	ds_read_b128 v[208:211], v155 offset:6144
	ds_read_b128 v[218:221], v155 offset:7168
	global_load_lds_dwordx4 v[212:213], off
	v_lshl_add_u64 v[212:213], v[150:151], 0, s[66:67]
	s_add_i32 m0, s75, 0xe000
	s_nop 0
	global_load_lds_dwordx4 v[212:213], off
	s_mov_b64 vcc, s[100:101]
	s_cbranch_vccnz .Lrlx_P3_0
	s_waitcnt vmcnt(8)
.Lrlx_P3_0:
	s_waitcnt lgkmcnt(0)
	s_barrier
	s_setprio 1
	s_waitcnt lgkmcnt(0)
	v_mfma_f32_16x16x32_bf16 v[124:127], v[128:131], v[184:187], v[124:127]
	v_mfma_f32_16x16x32_bf16 v[120:123], v[160:163], v[184:187], v[120:123]
	v_mfma_f32_16x16x32_bf16 v[108:111], v[128:131], v[192:195], v[108:111]
	v_mfma_f32_16x16x32_bf16 v[104:107], v[160:163], v[192:195], v[104:107]
	v_mfma_f32_16x16x32_bf16 v[92:95], v[128:131], v[200:203], v[92:95]
	v_mfma_f32_16x16x32_bf16 v[88:91], v[160:163], v[200:203], v[88:91]
	v_mfma_f32_16x16x32_bf16 v[76:79], v[128:131], v[208:211], v[76:79]
	v_mfma_f32_16x16x32_bf16 v[72:75], v[160:163], v[208:211], v[72:75]
	v_mfma_f32_16x16x32_bf16 v[124:127], v[156:159], v[188:191], v[124:127]
	v_mfma_f32_16x16x32_bf16 v[120:123], v[164:167], v[188:191], v[120:123]
	v_mfma_f32_16x16x32_bf16 v[108:111], v[156:159], v[196:199], v[108:111]
	v_mfma_f32_16x16x32_bf16 v[104:107], v[164:167], v[196:199], v[104:107]
	v_mfma_f32_16x16x32_bf16 v[92:95], v[156:159], v[204:207], v[92:95]
	v_mfma_f32_16x16x32_bf16 v[88:91], v[164:167], v[204:207], v[88:91]
	v_mfma_f32_16x16x32_bf16 v[76:79], v[156:159], v[218:221], v[76:79]
	v_mfma_f32_16x16x32_bf16 v[72:75], v[164:167], v[218:221], v[72:75]
	s_setprio 0
	s_setprio 1
	v_mfma_f32_16x16x32_bf16 v[116:119], v[168:171], v[184:187], v[116:119]
	v_mfma_f32_16x16x32_bf16 v[112:115], v[176:179], v[184:187], v[112:115]
	v_mfma_f32_16x16x32_bf16 v[100:103], v[168:171], v[192:195], v[100:103]
	v_mfma_f32_16x16x32_bf16 v[96:99], v[176:179], v[192:195], v[96:99]
	v_mfma_f32_16x16x32_bf16 v[84:87], v[168:171], v[200:203], v[84:87]
	v_mfma_f32_16x16x32_bf16 v[80:83], v[176:179], v[200:203], v[80:83]
	v_mfma_f32_16x16x32_bf16 v[68:71], v[168:171], v[208:211], v[68:71]
	v_mfma_f32_16x16x32_bf16 v[64:67], v[176:179], v[208:211], v[64:67]
	v_mfma_f32_16x16x32_bf16 v[116:119], v[172:175], v[188:191], v[116:119]
	v_mfma_f32_16x16x32_bf16 v[112:115], v[180:183], v[188:191], v[112:115]
	v_mfma_f32_16x16x32_bf16 v[100:103], v[172:175], v[196:199], v[100:103]
	v_mfma_f32_16x16x32_bf16 v[96:99], v[180:183], v[196:199], v[96:99]
	v_mfma_f32_16x16x32_bf16 v[84:87], v[172:175], v[204:207], v[84:87]
	v_mfma_f32_16x16x32_bf16 v[80:83], v[180:183], v[204:207], v[80:83]
	v_mfma_f32_16x16x32_bf16 v[68:71], v[172:175], v[218:221], v[68:71]
	v_mfma_f32_16x16x32_bf16 v[64:67], v[180:183], v[218:221], v[64:67]
	s_setprio 0
	s_barrier
	s_add_i32 s8, s95, s72
	v_lshl_add_u64 v[212:213], s[68:69], 0, v[136:137]
	s_mov_b32 m0, s8
	ds_read_b128 v[184:187], v155 offset:16384
	ds_read_b128 v[188:191], v155 offset:17408
	ds_read_b128 v[192:195], v155 offset:18432
	ds_read_b128 v[196:199], v155 offset:19456
	ds_read_b128 v[200:203], v155 offset:20480
	ds_read_b128 v[204:207], v155 offset:21504
	ds_read_b128 v[208:211], v155 offset:22528
	ds_read_b128 v[218:221], v155 offset:23552
	global_load_lds_dwordx4 v[212:213], off
	s_add_i32 m0, s8, 0x2000
	s_add_u32 s8, s68, 0x40000
	v_lshl_add_u64 v[222:223], s[68:69], 0, v[132:133]
	s_addc_u32 s9, s69, 0
	s_add_i32 s95, s89, s72
	global_load_lds_dwordx4 v[222:223], off
	v_lshl_add_u64 v[224:225], s[8:9], 0, v[136:137]
	s_mov_b32 m0, s95
	v_lshl_add_u64 v[226:227], s[70:71], 0, v[134:135]
	global_load_lds_dwordx4 v[224:225], off
	v_lshl_add_u64 v[224:225], s[8:9], 0, v[132:133]
	s_add_i32 m0, s95, 0x2000
	s_nop 0
	global_load_lds_dwordx4 v[224:225], off
	v_lshl_add_u64 v[224:225], s[70:71], 0, v[138:139]
	s_mov_b32 m0, s75
	s_nop 0
	global_load_lds_dwordx4 v[224:225], off
	s_mov_b32 m0, s76
	s_nop 0
	global_load_lds_dwordx4 v[226:227], off
	s_mov_b64 vcc, s[100:101]
	s_cbranch_vccnz .Lrlx_P3_1
	s_waitcnt vmcnt(8)
; #define PG8_STAGE(bufoff, gbase, voff) do { _Pragma("unroll") for (int _i = 0; _i < 2; ++_i) \
;         __builtin_amdgcn_global_load_lds((const unsigned*)((const char*)(gbase) + (voff)[_i]), (PG8_LAS unsigned*)(lds + (bufoff) + ldsw + _i * 8192), 16, 0, 0); } while (0)
; #define PG8_LDA(dst, b, h) do { _Pragma("unroll") for (int m = 0; m < 4; ++m) _Pragma("unroll") for (int k = 0; k < 2; ++k) dst[m][k] = *(const PG8_LAS bf16x8*)(lds + PG8_SA(b, h) + aoff + m * 2048 + k * 1024); } while (0)
; #define PG8_LDB(dst, b, h) do { _Pragma("unroll") for (int n = 0; n < 2; ++n) _Pragma("unroll") for (int k = 0; k < 2; ++k) dst[n][k] = *(const PG8_LAS bf16x8*)(lds + PG8_SB(b, h) + boff + n * 2048 + k * 1024); } while (0)
; #define PG8_MMA(ai, bj, At, Bt) do { __builtin_amdgcn_s_setprio(1); _Pragma("unroll") for (int m = 0; m < 4; ++m) _Pragma("unroll") for (int n = 0; n < 2; ++n) _Pragma("unroll") for (int k = 0; k < 2; ++k) \
;         acc[ai][bj][m][n] = __builtin_amdgcn_mfma_f32_16x16x32_bf16(Bt[n][k], At[m][k], acc[ai][bj][m][n], 0, 0, 0); __builtin_amdgcn_s_setprio(0); } while (0)
; #define PG8_WAIT_V(n) asm volatile("s_waitcnt vmcnt(" #n ")" ::: "memory")
; #define PG8_WAIT_L(n) asm volatile("s_waitcnt lgkmcnt(" #n ")" ::: "memory")
; #define PG8_BAR __builtin_amdgcn_s_barrier()
; #define PG8_SCHED __builtin_amdgcn_sched_barrier(0)
; template <class Epi, class Sched, bool ALIGN_EPI = false, bool SP2 = false>
; __device__ __forceinline__ void gemm_phase(PG8_LAS unsigned char* lds, const Gemm g, const Sched& S, const Epi& E, const int wave_s) {
;     ...
;             PG8_WAIT_V(8); PG8_WAIT_L(0); PG8_BAR; PG8_MMA(1, 0, At, B0); PG8_MMA(1, 1, At, B1); PG8_BAR; PG8_SCHED;
;             PG8_LDB(B0, 1, 0); PG8_LDB(B1, 1, 1); PG8_SCHED; PG8_LDA(At, 1, 0); PG8_STAGE(PG8_SA(0, 1), a2 + hA, voffA);
;             PG8_WAIT_V(8); PG8_WAIT_L(0); PG8_BAR; PG8_MMA(0, 0, At, B0); PG8_MMA(0, 1, At, B1); PG8_BAR; PG8_SCHED;
.Lrlx_P3_1:
	s_mov_b64 s[100:101], 0
	s_waitcnt lgkmcnt(0)
	s_barrier
	s_setprio 1
	s_waitcnt lgkmcnt(0)
	v_mfma_f32_16x16x32_bf16 v[60:63], v[128:131], v[184:187], v[60:63]
	v_mfma_f32_16x16x32_bf16 v[56:59], v[160:163], v[184:187], v[56:59]
	v_mfma_f32_16x16x32_bf16 v[44:47], v[128:131], v[192:195], v[44:47]
	v_mfma_f32_16x16x32_bf16 v[40:43], v[160:163], v[192:195], v[40:43]
	v_mfma_f32_16x16x32_bf16 v[28:31], v[128:131], v[200:203], v[28:31]
	v_mfma_f32_16x16x32_bf16 v[24:27], v[160:163], v[200:203], v[24:27]
	v_mfma_f32_16x16x32_bf16 v[12:15], v[128:131], v[208:211], v[12:15]
	v_mfma_f32_16x16x32_bf16 v[8:11], v[160:163], v[208:211], v[8:11]
	v_mfma_f32_16x16x32_bf16 v[60:63], v[156:159], v[188:191], v[60:63]
	v_mfma_f32_16x16x32_bf16 v[56:59], v[164:167], v[188:191], v[56:59]
	v_mfma_f32_16x16x32_bf16 v[44:47], v[156:159], v[196:199], v[44:47]
	v_mfma_f32_16x16x32_bf16 v[40:43], v[164:167], v[196:199], v[40:43]
	v_mfma_f32_16x16x32_bf16 v[28:31], v[156:159], v[204:207], v[28:31]
	v_mfma_f32_16x16x32_bf16 v[24:27], v[164:167], v[204:207], v[24:27]
	v_mfma_f32_16x16x32_bf16 v[12:15], v[156:159], v[218:221], v[12:15]
	v_mfma_f32_16x16x32_bf16 v[8:11], v[164:167], v[218:221], v[8:11]
	s_setprio 0
	s_setprio 1
	v_mfma_f32_16x16x32_bf16 v[52:55], v[168:171], v[184:187], v[52:55]
	v_mfma_f32_16x16x32_bf16 v[48:51], v[176:179], v[184:187], v[48:51]
	v_mfma_f32_16x16x32_bf16 v[36:39], v[168:171], v[192:195], v[36:39]
	v_mfma_f32_16x16x32_bf16 v[32:35], v[176:179], v[192:195], v[32:35]
	v_mfma_f32_16x16x32_bf16 v[20:23], v[168:171], v[200:203], v[20:23]
	v_mfma_f32_16x16x32_bf16 v[16:19], v[176:179], v[200:203], v[16:19]
	v_mfma_f32_16x16x32_bf16 v[4:7], v[168:171], v[208:211], v[4:7]
	v_mfma_f32_16x16x32_bf16 v[0:3], v[176:179], v[208:211], v[0:3]
	v_mfma_f32_16x16x32_bf16 v[52:55], v[172:175], v[188:191], v[52:55]
	v_mfma_f32_16x16x32_bf16 v[48:51], v[180:183], v[188:191], v[48:51]
	v_mfma_f32_16x16x32_bf16 v[36:39], v[172:175], v[196:199], v[36:39]
	v_mfma_f32_16x16x32_bf16 v[32:35], v[180:183], v[196:199], v[32:35]
	v_mfma_f32_16x16x32_bf16 v[20:23], v[172:175], v[204:207], v[20:23]
	v_mfma_f32_16x16x32_bf16 v[16:19], v[180:183], v[204:207], v[16:19]
	v_mfma_f32_16x16x32_bf16 v[4:7], v[172:175], v[218:221], v[4:7]
	v_mfma_f32_16x16x32_bf16 v[0:3], v[180:183], v[218:221], v[0:3]
	s_setprio 0
	s_barrier
	s_add_i32 s95, 0, 0x18000
	s_add_i32 s96, 0, 0x1c000
	v_add_u32_e32 v164, s95, v154
	v_add_u32_e32 v180, s96, v154
	ds_read_b128 v[128:131], v164
	ds_read_b128 v[156:159], v164 offset:1024
	ds_read_b128 v[160:163], v164 offset:2048
	ds_read_b128 v[164:167], v164 offset:3072
	ds_read_b128 v[168:171], v180
	ds_read_b128 v[172:175], v180 offset:1024
	ds_read_b128 v[176:179], v180 offset:2048
	ds_read_b128 v[180:183], v180 offset:3072
	s_add_u32 s8, s70, 0x40000
	s_addc_u32 s9, s71, 0
	s_mov_b32 m0, s77
	v_lshl_add_u64 v[228:229], s[8:9], 0, v[138:139]
	ds_read_b128 v[184:187], v155 offset:32768
	ds_read_b128 v[188:191], v155 offset:33792
	ds_read_b128 v[192:195], v155 offset:34816
	ds_read_b128 v[196:199], v155 offset:35840
	ds_read_b128 v[200:203], v155 offset:36864
	ds_read_b128 v[204:207], v155 offset:37888
	ds_read_b128 v[208:211], v155 offset:38912
	ds_read_b128 v[218:221], v155 offset:39936
	global_load_lds_dwordx4 v[228:229], off
	v_lshl_add_u64 v[228:229], s[8:9], 0, v[134:135]
	s_mov_b32 m0, s78
	s_nop 0
	global_load_lds_dwordx4 v[228:229], off
	s_waitcnt vmcnt(8)
	s_waitcnt lgkmcnt(0)
	s_barrier
	s_setprio 1
	s_waitcnt lgkmcnt(0)
	v_mfma_f32_16x16x32_bf16 v[124:127], v[128:131], v[184:187], v[124:127]
	v_mfma_f32_16x16x32_bf16 v[120:123], v[160:163], v[184:187], v[120:123]
	v_mfma_f32_16x16x32_bf16 v[108:111], v[128:131], v[192:195], v[108:111]
	v_mfma_f32_16x16x32_bf16 v[104:107], v[160:163], v[192:195], v[104:107]
	v_mfma_f32_16x16x32_bf16 v[92:95], v[128:131], v[200:203], v[92:95]
	v_mfma_f32_16x16x32_bf16 v[88:91], v[160:163], v[200:203], v[88:91]
	v_mfma_f32_16x16x32_bf16 v[76:79], v[128:131], v[208:211], v[76:79]
	v_mfma_f32_16x16x32_bf16 v[72:75], v[160:163], v[208:211], v[72:75]
	v_mfma_f32_16x16x32_bf16 v[124:127], v[156:159], v[188:191], v[124:127]
	v_mfma_f32_16x16x32_bf16 v[120:123], v[164:167], v[188:191], v[120:123]
	v_mfma_f32_16x16x32_bf16 v[108:111], v[156:159], v[196:199], v[108:111]
	v_mfma_f32_16x16x32_bf16 v[104:107], v[164:167], v[196:199], v[104:107]
	v_mfma_f32_16x16x32_bf16 v[92:95], v[156:159], v[204:207], v[92:95]
	v_mfma_f32_16x16x32_bf16 v[88:91], v[164:167], v[204:207], v[88:91]
	v_mfma_f32_16x16x32_bf16 v[76:79], v[156:159], v[218:221], v[76:79]
	v_mfma_f32_16x16x32_bf16 v[72:75], v[164:167], v[218:221], v[72:75]
	s_setprio 0
	s_setprio 1
	v_mfma_f32_16x16x32_bf16 v[116:119], v[168:171], v[184:187], v[116:119]
	v_mfma_f32_16x16x32_bf16 v[112:115], v[176:179], v[184:187], v[112:115]
	v_mfma_f32_16x16x32_bf16 v[100:103], v[168:171], v[192:195], v[100:103]
	v_mfma_f32_16x16x32_bf16 v[96:99], v[176:179], v[192:195], v[96:99]
	v_mfma_f32_16x16x32_bf16 v[84:87], v[168:171], v[200:203], v[84:87]
	v_mfma_f32_16x16x32_bf16 v[80:83], v[176:179], v[200:203], v[80:83]
	v_mfma_f32_16x16x32_bf16 v[68:71], v[168:171], v[208:211], v[68:71]
	v_mfma_f32_16x16x32_bf16 v[64:67], v[176:179], v[208:211], v[64:67]
	v_mfma_f32_16x16x32_bf16 v[116:119], v[172:175], v[188:191], v[116:119]
	v_mfma_f32_16x16x32_bf16 v[112:115], v[180:183], v[188:191], v[112:115]
	v_mfma_f32_16x16x32_bf16 v[100:103], v[172:175], v[196:199], v[100:103]
	v_mfma_f32_16x16x32_bf16 v[96:99], v[180:183], v[196:199], v[96:99]
	v_mfma_f32_16x16x32_bf16 v[84:87], v[172:175], v[204:207], v[84:87]
	v_mfma_f32_16x16x32_bf16 v[80:83], v[180:183], v[204:207], v[80:83]
	v_mfma_f32_16x16x32_bf16 v[68:71], v[172:175], v[218:221], v[68:71]
	v_mfma_f32_16x16x32_bf16 v[64:67], v[180:183], v[218:221], v[64:67]
	s_setprio 0
	s_barrier
; #define PG8_STAGE(bufoff, gbase, voff) do { _Pragma("unroll") for (int _i = 0; _i < 2; ++_i) \
;         __builtin_amdgcn_global_load_lds((const unsigned*)((const char*)(gbase) + (voff)[_i]), (PG8_LAS unsigned*)(lds + (bufoff) + ldsw + _i * 8192), 16, 0, 0); } while (0)
; #define PG8_LDA(dst, b, h) do { _Pragma("unroll") for (int m = 0; m < 4; ++m) _Pragma("unroll") for (int k = 0; k < 2; ++k) dst[m][k] = *(const PG8_LAS bf16x8*)(lds + PG8_SA(b, h) + aoff + m * 2048 + k * 1024); } while (0)
; #define PG8_MMA(ai, bj, At, Bt) do { __builtin_amdgcn_s_setprio(1); _Pragma("unroll") for (int m = 0; m < 4; ++m) _Pragma("unroll") for (int n = 0; n < 2; ++n) _Pragma("unroll") for (int k = 0; k < 2; ++k) \
;         acc[ai][bj][m][n] = __builtin_amdgcn_mfma_f32_16x16x32_bf16(Bt[n][k], At[m][k], acc[ai][bj][m][n], 0, 0, 0); __builtin_amdgcn_s_setprio(0); } while (0)
; #define PG8_WAIT_V(n) asm volatile("s_waitcnt vmcnt(" #n ")" ::: "memory")
; #define PG8_WAIT_L(n) asm volatile("s_waitcnt lgkmcnt(" #n ")" ::: "memory")
; #define PG8_BAR __builtin_amdgcn_s_barrier()
; #define PG8_SCHED __builtin_amdgcn_sched_barrier(0)
; template <class Epi, class Sched, bool ALIGN_EPI = false, bool SP2 = false>
; __device__ __forceinline__ void gemm_phase(PG8_LAS unsigned char* lds, const Gemm g, const Sched& S, const Epi& E, const int wave_s) {
;     ...
;             PG8_LDA(At, 1, 1); PG8_STAGE(PG8_SB(1, 0), b3, voffB); PG8_STAGE(PG8_SB(1, 1), b3 + hB, voffB); PG8_STAGE(PG8_SA(1, 0), a3, voffA);
;             PG8_WAIT_V(8); PG8_WAIT_L(0); PG8_BAR; PG8_MMA(1, 0, At, B0); PG8_MMA(1, 1, At, B1); PG8_BAR; PG8_SCHED;
	s_add_i32 s8, s95, s72
	v_lshl_add_u64 v[212:213], v[212:213], 0, s[6:7]
	s_mov_b32 m0, s8
	ds_read_b128 v[184:187], v155 offset:49152
	ds_read_b128 v[188:191], v155 offset:50176
	ds_read_b128 v[192:195], v155 offset:51200
	ds_read_b128 v[196:199], v155 offset:52224
	ds_read_b128 v[200:203], v155 offset:53248
	ds_read_b128 v[204:207], v155 offset:54272
	ds_read_b128 v[208:211], v155 offset:55296
	ds_read_b128 v[218:221], v155 offset:56320
	global_load_lds_dwordx4 v[212:213], off
	s_add_i32 m0, s8, 0x2000
	s_add_u32 s8, s68, 0x40080
	v_lshl_add_u64 v[212:213], v[222:223], 0, s[6:7]
	s_addc_u32 s9, s69, 0
	s_add_i32 s68, s96, s72
	global_load_lds_dwordx4 v[212:213], off
	v_lshl_add_u64 v[212:213], s[8:9], 0, v[136:137]
	s_mov_b32 m0, s68
	s_nop 0
	global_load_lds_dwordx4 v[212:213], off
	v_lshl_add_u64 v[212:213], s[8:9], 0, v[132:133]
	s_add_i32 m0, s68, 0x2000
	s_nop 0
	global_load_lds_dwordx4 v[212:213], off
	v_lshl_add_u64 v[212:213], v[224:225], 0, s[6:7]
	s_mov_b32 m0, s81
	s_nop 0
	global_load_lds_dwordx4 v[212:213], off
	v_lshl_add_u64 v[212:213], v[226:227], 0, s[6:7]
	s_mov_b32 m0, s82
	s_nop 0
	global_load_lds_dwordx4 v[212:213], off
	s_waitcnt vmcnt(8)
	s_waitcnt lgkmcnt(0)
	s_barrier
	s_setprio 1
	s_waitcnt lgkmcnt(0)
	v_mfma_f32_16x16x32_bf16 v[60:63], v[128:131], v[184:187], v[60:63]
	v_mfma_f32_16x16x32_bf16 v[56:59], v[160:163], v[184:187], v[56:59]
	v_mfma_f32_16x16x32_bf16 v[44:47], v[128:131], v[192:195], v[44:47]
	v_mfma_f32_16x16x32_bf16 v[40:43], v[160:163], v[192:195], v[40:43]
	v_mfma_f32_16x16x32_bf16 v[28:31], v[128:131], v[200:203], v[28:31]
	v_mfma_f32_16x16x32_bf16 v[24:27], v[160:163], v[200:203], v[24:27]
	v_mfma_f32_16x16x32_bf16 v[12:15], v[128:131], v[208:211], v[12:15]
	v_mfma_f32_16x16x32_bf16 v[8:11], v[160:163], v[208:211], v[8:11]
	v_mfma_f32_16x16x32_bf16 v[60:63], v[156:159], v[188:191], v[60:63]
	v_mfma_f32_16x16x32_bf16 v[56:59], v[164:167], v[188:191], v[56:59]
	v_mfma_f32_16x16x32_bf16 v[44:47], v[156:159], v[196:199], v[44:47]
	v_mfma_f32_16x16x32_bf16 v[40:43], v[164:167], v[196:199], v[40:43]
	v_mfma_f32_16x16x32_bf16 v[28:31], v[156:159], v[204:207], v[28:31]
	v_mfma_f32_16x16x32_bf16 v[24:27], v[164:167], v[204:207], v[24:27]
	v_mfma_f32_16x16x32_bf16 v[12:15], v[156:159], v[218:221], v[12:15]
	v_mfma_f32_16x16x32_bf16 v[8:11], v[164:167], v[218:221], v[8:11]
	s_setprio 0
	s_setprio 1
	v_mfma_f32_16x16x32_bf16 v[52:55], v[168:171], v[184:187], v[52:55]
	v_mfma_f32_16x16x32_bf16 v[48:51], v[176:179], v[184:187], v[48:51]
	v_mfma_f32_16x16x32_bf16 v[36:39], v[168:171], v[192:195], v[36:39]
	v_mfma_f32_16x16x32_bf16 v[32:35], v[176:179], v[192:195], v[32:35]
	v_mfma_f32_16x16x32_bf16 v[20:23], v[168:171], v[200:203], v[20:23]
	v_mfma_f32_16x16x32_bf16 v[16:19], v[176:179], v[200:203], v[16:19]
	v_mfma_f32_16x16x32_bf16 v[4:7], v[168:171], v[208:211], v[4:7]
	v_mfma_f32_16x16x32_bf16 v[0:3], v[176:179], v[208:211], v[0:3]
	v_mfma_f32_16x16x32_bf16 v[52:55], v[172:175], v[188:191], v[52:55]
	v_mfma_f32_16x16x32_bf16 v[48:51], v[180:183], v[188:191], v[48:51]
	v_mfma_f32_16x16x32_bf16 v[36:39], v[172:175], v[196:199], v[36:39]
	v_mfma_f32_16x16x32_bf16 v[32:35], v[180:183], v[196:199], v[32:35]
	v_mfma_f32_16x16x32_bf16 v[20:23], v[172:175], v[204:207], v[20:23]
	v_mfma_f32_16x16x32_bf16 v[16:19], v[180:183], v[204:207], v[16:19]
	v_mfma_f32_16x16x32_bf16 v[4:7], v[172:175], v[218:221], v[4:7]
	v_mfma_f32_16x16x32_bf16 v[0:3], v[180:183], v[218:221], v[0:3]
	s_setprio 0
	s_barrier
	s_add_i32 s94, s94, 2
	s_add_u32 s66, s66, 0x100
	s_addc_u32 s67, s67, 0
	s_cmp_gt_u32 s94, 13
	s_cbranch_scc1 .LBB0_625

; #define PG8_BAR __builtin_amdgcn_s_barrier()
; template <class Epi, class Sched, bool ALIGN_EPI = false, bool SP2 = false>
; __device__ __forceinline__ void gemm_phase(PG8_LAS unsigned char* lds, const Gemm g, const Sched& S, const Epi& E, const int wave_s) {
;     ...
;         if constexpr (ALIGN_EPI) { if (wr == 0) PG8_BAR; }
.LBB0_625:
	s_mov_b64 s[100:101], -1
	s_and_b64 vcc, exec, s[36:37]
	s_cbranch_vccz .LBB0_627
	s_barrier

;     __host__ __device__ bool next(int i, Unit& u) const {
;         const long L = (long)i * G + c; if (L >= nwg) return false;
;         int wgid = (int)L; { const int q = nwg / NXCD, r = nwg % NXCD, xcd = wgid % NXCD, off = wgid / NXCD; wgid = (xcd < r ? xcd * (q + 1) : r * (q + 1) + (xcd - r) * q) + off; }
;         const int nig = WGM * nN, gid = wgid / nig, fm = gid * WGM, gsz = (nM - fm) < WGM ? (nM - fm) : WGM;
;         u.pm = fm + ((wgid % nig) % gsz); u.pn = (wgid % nig) / gsz; if (rev) u.pm = nM - 1 - u.pm; return true;
.LBB0_685:
	s_waitcnt lgkmcnt(0)
	s_barrier
	s_mov_b64 s[100:101], 0
	v_mbcnt_lo_u32_b32 v0, -1, 0
	v_mbcnt_hi_u32_b32 v0, -1, v0
	s_andn2_b64 vcc, exec, s[0:1]
	v_or_b32_e32 v8, s84, v0
	v_cndmask_b32_e64 v0, 0, 1, s[0:1]
	v_cmp_ne_u32_e64 s[2:3], 1, v0
	v_readfirstlane_b32 s4, v8
	s_cbranch_vccnz .LBB0_687
	s_ashr_i32 s0, s10, 31
	s_lshr_b32 s0, s0, 29
	s_add_i32 s0, s10, s0
	s_ashr_i32 s1, s0, 3
	s_and_b32 s0, s0, -8
	s_sub_i32 s0, s10, s0
	s_cmp_lt_i32 s0, 0
	s_movk_i32 s5, 0xc1
	s_cselect_b32 s5, s5, 0xc0
	s_mul_i32 s0, s0, s5
	s_add_i32 s0, s0, s1
	s_ashr_i32 s1, s0, 31
	s_lshr_b32 s1, s1, 27
	s_add_i32 s1, s0, s1
	s_ashr_i32 s5, s1, 5
	s_andn2_b32 s1, s1, 31
	s_sub_i32 s0, s0, s1
	s_bfe_i32 s1, s0, 0x80000
	s_bfe_u32 s1, s1, 0x3000c
	s_add_i32 s1, s0, s1
	s_bfe_i32 s6, s1, 0x80000
	s_and_b32 s1, s1, 0xf8
	s_sub_i32 s0, s1, s0
	s_sext_i32_i8 s0, s0
	s_lshl_b32 s1, s5, 3
	s_sext_i32_i16 s6, s6
	s_sub_i32 s0, s0, s1
	s_ashr_i32 s60, s6, 3
	s_add_i32 s62, s0, 0x17f

; #define PG8_STAGE(bufoff, gbase, voff) do { _Pragma("unroll") for (int _i = 0; _i < 2; ++_i) \
;         __builtin_amdgcn_global_load_lds((const unsigned*)((const char*)(gbase) + (voff)[_i]), (PG8_LAS unsigned*)(lds + (bufoff) + ldsw + _i * 8192), 16, 0, 0); } while (0)
; #define PG8_LDA(dst, b, h) do { _Pragma("unroll") for (int m = 0; m < 4; ++m) _Pragma("unroll") for (int k = 0; k < 2; ++k) dst[m][k] = *(const PG8_LAS bf16x8*)(lds + PG8_SA(b, h) + aoff + m * 2048 + k * 1024); } while (0)
; #define PG8_LDB(dst, b, h) do { _Pragma("unroll") for (int n = 0; n < 2; ++n) _Pragma("unroll") for (int k = 0; k < 2; ++k) dst[n][k] = *(const PG8_LAS bf16x8*)(lds + PG8_SB(b, h) + boff + n * 2048 + k * 1024); } while (0)
; #define PG8_MMA(ai, bj, At, Bt) do { __builtin_amdgcn_s_setprio(1); _Pragma("unroll") for (int m = 0; m < 4; ++m) _Pragma("unroll") for (int n = 0; n < 2; ++n) _Pragma("unroll") for (int k = 0; k < 2; ++k) \
;         acc[ai][bj][m][n] = __builtin_amdgcn_mfma_f32_16x16x32_bf16(Bt[n][k], At[m][k], acc[ai][bj][m][n], 0, 0, 0); __builtin_amdgcn_s_setprio(0); } while (0)
; #define PG8_WAIT_V(n) asm volatile("s_waitcnt vmcnt(" #n ")" ::: "memory")
; #define PG8_WAIT_L(n) asm volatile("s_waitcnt lgkmcnt(" #n ")" ::: "memory")
; #define PG8_BAR __builtin_amdgcn_s_barrier()
; #define PG8_SCHED __builtin_amdgcn_sched_barrier(0)
; template <class Epi, class Sched, bool ALIGN_EPI = false, bool SP2 = false>
; __device__ __forceinline__ void gemm_phase(PG8_LAS unsigned char* lds, const Gemm g, const Sched& S, const Epi& E, const int wave_s) {
;     ...
;             PG8_LDB(B0, 0, 0); PG8_LDB(B1, 0, 1); PG8_SCHED; PG8_LDA(At, 0, 0); PG8_STAGE(PG8_SA(1, 1), a1 + hA, voffA);
;             PG8_WAIT_V(8); PG8_WAIT_L(0); PG8_BAR; PG8_MMA(0, 0, At, B0); PG8_MMA(0, 1, At, B1); PG8_BAR; PG8_SCHED;
;             PG8_LDA(At, 0, 1); PG8_STAGE(PG8_SB(0, 0), b2, voffB); PG8_STAGE(PG8_SB(0, 1), b2 + hB, voffB); PG8_STAGE(PG8_SA(0, 0), a2, voffA);
;             PG8_WAIT_V(8); PG8_WAIT_L(0); PG8_BAR; PG8_MMA(1, 0, At, B0); PG8_MMA(1, 1, At, B1); PG8_BAR; PG8_SCHED;
.LBB0_696:
	ds_read_b128 v[144:147], v155
	ds_read_b128 v[148:151], v155 offset:1024
	ds_read_b128 v[158:161], v155 offset:2048
	ds_read_b128 v[162:165], v155 offset:3072
	ds_read_b128 v[166:169], v156
	ds_read_b128 v[170:173], v156 offset:1024
	ds_read_b128 v[174:177], v156 offset:2048
	ds_read_b128 v[178:181], v156 offset:3072
	s_add_u32 s66, s64, 0xfffc0080
	s_addc_u32 s67, s65, -1
	s_cmp_eq_u32 s78, 12
	s_cselect_b32 s69, s8, s67
	s_cselect_b32 s68, s9, s66
	s_cselect_b32 s67, s47, s77
	s_cselect_b32 s66, s49, s61
	v_lshl_add_u64 v[218:219], s[64:65], 0, v[136:137]
	s_add_i32 m0, s12, 0xc000
	ds_read_b128 v[182:185], v157
	ds_read_b128 v[186:189], v157 offset:1024
	ds_read_b128 v[190:193], v157 offset:2048
	ds_read_b128 v[194:197], v157 offset:3072
	ds_read_b128 v[198:201], v157 offset:4096
	ds_read_b128 v[202:205], v157 offset:5120
	ds_read_b128 v[206:209], v157 offset:6144
	ds_read_b128 v[210:213], v157 offset:7168
	global_load_lds_dwordx4 v[218:219], off
	v_lshl_add_u64 v[218:219], s[64:65], 0, v[138:139]
	s_add_i32 m0, s12, 0xe000
	s_nop 0
	global_load_lds_dwordx4 v[218:219], off
	s_mov_b64 vcc, s[100:101]
	s_cbranch_vccnz .Lrlx_P4_0
	s_waitcnt vmcnt(8)
.Lrlx_P4_0:
	s_waitcnt lgkmcnt(0)
	s_barrier
	s_setprio 1
	s_waitcnt lgkmcnt(0)
	v_mfma_f32_16x16x32_bf16 v[124:127], v[144:147], v[182:185], v[124:127]
	v_mfma_f32_16x16x32_bf16 v[120:123], v[158:161], v[182:185], v[120:123]
	v_mfma_f32_16x16x32_bf16 v[108:111], v[144:147], v[190:193], v[108:111]
	v_mfma_f32_16x16x32_bf16 v[104:107], v[158:161], v[190:193], v[104:107]
	v_mfma_f32_16x16x32_bf16 v[92:95], v[144:147], v[198:201], v[92:95]
	v_mfma_f32_16x16x32_bf16 v[88:91], v[158:161], v[198:201], v[88:91]
	v_mfma_f32_16x16x32_bf16 v[76:79], v[144:147], v[206:209], v[76:79]
	v_mfma_f32_16x16x32_bf16 v[72:75], v[158:161], v[206:209], v[72:75]
	v_mfma_f32_16x16x32_bf16 v[124:127], v[148:151], v[186:189], v[124:127]
	v_mfma_f32_16x16x32_bf16 v[120:123], v[162:165], v[186:189], v[120:123]
	v_mfma_f32_16x16x32_bf16 v[108:111], v[148:151], v[194:197], v[108:111]
	v_mfma_f32_16x16x32_bf16 v[104:107], v[162:165], v[194:197], v[104:107]
	v_mfma_f32_16x16x32_bf16 v[92:95], v[148:151], v[202:205], v[92:95]
	v_mfma_f32_16x16x32_bf16 v[88:91], v[162:165], v[202:205], v[88:91]
	v_mfma_f32_16x16x32_bf16 v[76:79], v[148:151], v[210:213], v[76:79]
	v_mfma_f32_16x16x32_bf16 v[72:75], v[162:165], v[210:213], v[72:75]
	s_setprio 0
	s_setprio 1
	v_mfma_f32_16x16x32_bf16 v[116:119], v[166:169], v[182:185], v[116:119]
	v_mfma_f32_16x16x32_bf16 v[112:115], v[174:177], v[182:185], v[112:115]
	v_mfma_f32_16x16x32_bf16 v[100:103], v[166:169], v[190:193], v[100:103]
	v_mfma_f32_16x16x32_bf16 v[96:99], v[174:177], v[190:193], v[96:99]
	v_mfma_f32_16x16x32_bf16 v[84:87], v[166:169], v[198:201], v[84:87]
	v_mfma_f32_16x16x32_bf16 v[80:83], v[174:177], v[198:201], v[80:83]
	v_mfma_f32_16x16x32_bf16 v[68:71], v[166:169], v[206:209], v[68:71]
	v_mfma_f32_16x16x32_bf16 v[64:67], v[174:177], v[206:209], v[64:67]
	v_mfma_f32_16x16x32_bf16 v[116:119], v[170:173], v[186:189], v[116:119]
	v_mfma_f32_16x16x32_bf16 v[112:115], v[178:181], v[186:189], v[112:115]
	v_mfma_f32_16x16x32_bf16 v[100:103], v[170:173], v[194:197], v[100:103]
	v_mfma_f32_16x16x32_bf16 v[96:99], v[178:181], v[194:197], v[96:99]
	v_mfma_f32_16x16x32_bf16 v[84:87], v[170:173], v[202:205], v[84:87]
	v_mfma_f32_16x16x32_bf16 v[80:83], v[178:181], v[202:205], v[80:83]
	v_mfma_f32_16x16x32_bf16 v[68:71], v[170:173], v[210:213], v[68:71]
	v_mfma_f32_16x16x32_bf16 v[64:67], v[178:181], v[210:213], v[64:67]
	s_setprio 0
	s_barrier
	s_add_i32 s79, s75, s11
	v_lshl_add_u64 v[218:219], s[66:67], 0, v[130:131]
	s_mov_b32 m0, s79
	ds_read_b128 v[182:185], v157 offset:16384
	ds_read_b128 v[186:189], v157 offset:17408
	ds_read_b128 v[190:193], v157 offset:18432
	ds_read_b128 v[194:197], v157 offset:19456
	ds_read_b128 v[198:201], v157 offset:20480
	ds_read_b128 v[202:205], v157 offset:21504
	ds_read_b128 v[206:209], v157 offset:22528
	ds_read_b128 v[210:213], v157 offset:23552
	global_load_lds_dwordx4 v[218:219], off
	s_add_i32 m0, s79, 0x2000
	s_add_u32 s80, s66, 0x40000
	v_lshl_add_u64 v[220:221], s[66:67], 0, v[134:135]
	s_addc_u32 s81, s67, 0
	s_add_i32 s79, s76, s11
	global_load_lds_dwordx4 v[220:221], off
	v_lshl_add_u64 v[222:223], s[80:81], 0, v[130:131]
	s_mov_b32 m0, s79
	v_lshl_add_u64 v[224:225], s[68:69], 0, v[132:133]
	global_load_lds_dwordx4 v[222:223], off
	v_lshl_add_u64 v[222:223], s[80:81], 0, v[134:135]
	s_add_i32 m0, s79, 0x2000
	s_nop 0
	global_load_lds_dwordx4 v[222:223], off
	v_lshl_add_u64 v[222:223], s[68:69], 0, v[128:129]
	s_mov_b32 m0, s12
	s_nop 0
	global_load_lds_dwordx4 v[222:223], off
	s_mov_b32 m0, s13
	s_nop 0
	global_load_lds_dwordx4 v[224:225], off
	s_mov_b64 vcc, s[100:101]
	s_cbranch_vccnz .Lrlx_P4_1
	s_waitcnt vmcnt(8)
; #define PG8_STAGE(bufoff, gbase, voff) do { _Pragma("unroll") for (int _i = 0; _i < 2; ++_i) \
;         __builtin_amdgcn_global_load_lds((const unsigned*)((const char*)(gbase) + (voff)[_i]), (PG8_LAS unsigned*)(lds + (bufoff) + ldsw + _i * 8192), 16, 0, 0); } while (0)
; #define PG8_LDA(dst, b, h) do { _Pragma("unroll") for (int m = 0; m < 4; ++m) _Pragma("unroll") for (int k = 0; k < 2; ++k) dst[m][k] = *(const PG8_LAS bf16x8*)(lds + PG8_SA(b, h) + aoff + m * 2048 + k * 1024); } while (0)
; #define PG8_LDB(dst, b, h) do { _Pragma("unroll") for (int n = 0; n < 2; ++n) _Pragma("unroll") for (int k = 0; k < 2; ++k) dst[n][k] = *(const PG8_LAS bf16x8*)(lds + PG8_SB(b, h) + boff + n * 2048 + k * 1024); } while (0)
; #define PG8_MMA(ai, bj, At, Bt) do { __builtin_amdgcn_s_setprio(1); _Pragma("unroll") for (int m = 0; m < 4; ++m) _Pragma("unroll") for (int n = 0; n < 2; ++n) _Pragma("unroll") for (int k = 0; k < 2; ++k) \
;         acc[ai][bj][m][n] = __builtin_amdgcn_mfma_f32_16x16x32_bf16(Bt[n][k], At[m][k], acc[ai][bj][m][n], 0, 0, 0); __builtin_amdgcn_s_setprio(0); } while (0)
; #define PG8_WAIT_V(n) asm volatile("s_waitcnt vmcnt(" #n ")" ::: "memory")
; #define PG8_WAIT_L(n) asm volatile("s_waitcnt lgkmcnt(" #n ")" ::: "memory")
; #define PG8_BAR __builtin_amdgcn_s_barrier()
; #define PG8_SCHED __builtin_amdgcn_sched_barrier(0)
; template <class Epi, class Sched, bool ALIGN_EPI = false, bool SP2 = false>
; __device__ __forceinline__ void gemm_phase(PG8_LAS unsigned char* lds, const Gemm g, const Sched& S, const Epi& E, const int wave_s) {
;     ...
;             PG8_WAIT_V(8); PG8_WAIT_L(0); PG8_BAR; PG8_MMA(1, 0, At, B0); PG8_MMA(1, 1, At, B1); PG8_BAR; PG8_SCHED;
;             PG8_LDB(B0, 1, 0); PG8_LDB(B1, 1, 1); PG8_SCHED; PG8_LDA(At, 1, 0); PG8_STAGE(PG8_SA(0, 1), a2 + hA, voffA);
;             PG8_WAIT_V(8); PG8_WAIT_L(0); PG8_BAR; PG8_MMA(0, 0, At, B0); PG8_MMA(0, 1, At, B1); PG8_BAR; PG8_SCHED;
.Lrlx_P4_1:
	s_mov_b64 s[100:101], 0
	s_waitcnt lgkmcnt(0)
	s_barrier
	s_setprio 1
	s_waitcnt lgkmcnt(0)
	v_mfma_f32_16x16x32_bf16 v[60:63], v[144:147], v[182:185], v[60:63]
	v_mfma_f32_16x16x32_bf16 v[56:59], v[158:161], v[182:185], v[56:59]
	v_mfma_f32_16x16x32_bf16 v[44:47], v[144:147], v[190:193], v[44:47]
	v_mfma_f32_16x16x32_bf16 v[40:43], v[158:161], v[190:193], v[40:43]
	v_mfma_f32_16x16x32_bf16 v[28:31], v[144:147], v[198:201], v[28:31]
	v_mfma_f32_16x16x32_bf16 v[24:27], v[158:161], v[198:201], v[24:27]
	v_mfma_f32_16x16x32_bf16 v[12:15], v[144:147], v[206:209], v[12:15]
	v_mfma_f32_16x16x32_bf16 v[8:11], v[158:161], v[206:209], v[8:11]
	v_mfma_f32_16x16x32_bf16 v[60:63], v[148:151], v[186:189], v[60:63]
	v_mfma_f32_16x16x32_bf16 v[56:59], v[162:165], v[186:189], v[56:59]
	v_mfma_f32_16x16x32_bf16 v[44:47], v[148:151], v[194:197], v[44:47]
	v_mfma_f32_16x16x32_bf16 v[40:43], v[162:165], v[194:197], v[40:43]
	v_mfma_f32_16x16x32_bf16 v[28:31], v[148:151], v[202:205], v[28:31]
	v_mfma_f32_16x16x32_bf16 v[24:27], v[162:165], v[202:205], v[24:27]
	v_mfma_f32_16x16x32_bf16 v[12:15], v[148:151], v[210:213], v[12:15]
	v_mfma_f32_16x16x32_bf16 v[8:11], v[162:165], v[210:213], v[8:11]
	s_setprio 0
	s_setprio 1
	v_mfma_f32_16x16x32_bf16 v[52:55], v[166:169], v[182:185], v[52:55]
	v_mfma_f32_16x16x32_bf16 v[48:51], v[174:177], v[182:185], v[48:51]
	v_mfma_f32_16x16x32_bf16 v[36:39], v[166:169], v[190:193], v[36:39]
	v_mfma_f32_16x16x32_bf16 v[32:35], v[174:177], v[190:193], v[32:35]
	v_mfma_f32_16x16x32_bf16 v[20:23], v[166:169], v[198:201], v[20:23]
	v_mfma_f32_16x16x32_bf16 v[16:19], v[174:177], v[198:201], v[16:19]
	v_mfma_f32_16x16x32_bf16 v[4:7], v[166:169], v[206:209], v[4:7]
	v_mfma_f32_16x16x32_bf16 v[0:3], v[174:177], v[206:209], v[0:3]
	v_mfma_f32_16x16x32_bf16 v[52:55], v[170:173], v[186:189], v[52:55]
	v_mfma_f32_16x16x32_bf16 v[48:51], v[178:181], v[186:189], v[48:51]
	v_mfma_f32_16x16x32_bf16 v[36:39], v[170:173], v[194:197], v[36:39]
	v_mfma_f32_16x16x32_bf16 v[32:35], v[178:181], v[194:197], v[32:35]
	v_mfma_f32_16x16x32_bf16 v[20:23], v[170:173], v[202:205], v[20:23]
	v_mfma_f32_16x16x32_bf16 v[16:19], v[178:181], v[202:205], v[16:19]
	v_mfma_f32_16x16x32_bf16 v[4:7], v[170:173], v[210:213], v[4:7]
	v_mfma_f32_16x16x32_bf16 v[0:3], v[178:181], v[210:213], v[0:3]
	s_setprio 0
	s_barrier
	s_add_i32 s79, 0, 0x18000
	s_add_i32 s80, 0, 0x1c000
	v_add_u32_e32 v162, s79, v153
	v_add_u32_e32 v178, s80, v153
	ds_read_b128 v[144:147], v162
	ds_read_b128 v[148:151], v162 offset:1024
	ds_read_b128 v[158:161], v162 offset:2048
	ds_read_b128 v[162:165], v162 offset:3072
	ds_read_b128 v[166:169], v178
	ds_read_b128 v[170:173], v178 offset:1024
	ds_read_b128 v[174:177], v178 offset:2048
	ds_read_b128 v[178:181], v178 offset:3072
	s_add_u32 s68, s68, 0x40000
	s_addc_u32 s69, s69, 0
	s_mov_b32 m0, s34
	v_lshl_add_u64 v[226:227], s[68:69], 0, v[128:129]
	ds_read_b128 v[182:185], v157 offset:32768
	ds_read_b128 v[186:189], v157 offset:33792
	ds_read_b128 v[190:193], v157 offset:34816
	ds_read_b128 v[194:197], v157 offset:35840
	ds_read_b128 v[198:201], v157 offset:36864
	ds_read_b128 v[202:205], v157 offset:37888
	ds_read_b128 v[206:209], v157 offset:38912
	ds_read_b128 v[210:213], v157 offset:39936
	global_load_lds_dwordx4 v[226:227], off
	v_lshl_add_u64 v[226:227], s[68:69], 0, v[132:133]
	s_mov_b32 m0, s35
	s_nop 0
	global_load_lds_dwordx4 v[226:227], off
	s_waitcnt vmcnt(8)
	s_waitcnt lgkmcnt(0)
	s_barrier
	s_setprio 1
	s_waitcnt lgkmcnt(0)
	v_mfma_f32_16x16x32_bf16 v[124:127], v[144:147], v[182:185], v[124:127]
	v_mfma_f32_16x16x32_bf16 v[120:123], v[158:161], v[182:185], v[120:123]
	v_mfma_f32_16x16x32_bf16 v[108:111], v[144:147], v[190:193], v[108:111]
	v_mfma_f32_16x16x32_bf16 v[104:107], v[158:161], v[190:193], v[104:107]
	v_mfma_f32_16x16x32_bf16 v[92:95], v[144:147], v[198:201], v[92:95]
	v_mfma_f32_16x16x32_bf16 v[88:91], v[158:161], v[198:201], v[88:91]
	v_mfma_f32_16x16x32_bf16 v[76:79], v[144:147], v[206:209], v[76:79]
	v_mfma_f32_16x16x32_bf16 v[72:75], v[158:161], v[206:209], v[72:75]
	v_mfma_f32_16x16x32_bf16 v[124:127], v[148:151], v[186:189], v[124:127]
	v_mfma_f32_16x16x32_bf16 v[120:123], v[162:165], v[186:189], v[120:123]
	v_mfma_f32_16x16x32_bf16 v[108:111], v[148:151], v[194:197], v[108:111]
	v_mfma_f32_16x16x32_bf16 v[104:107], v[162:165], v[194:197], v[104:107]
	v_mfma_f32_16x16x32_bf16 v[92:95], v[148:151], v[202:205], v[92:95]
	v_mfma_f32_16x16x32_bf16 v[88:91], v[162:165], v[202:205], v[88:91]
	v_mfma_f32_16x16x32_bf16 v[76:79], v[148:151], v[210:213], v[76:79]
	v_mfma_f32_16x16x32_bf16 v[72:75], v[162:165], v[210:213], v[72:75]
	s_setprio 0
	s_setprio 1
	v_mfma_f32_16x16x32_bf16 v[116:119], v[166:169], v[182:185], v[116:119]
	v_mfma_f32_16x16x32_bf16 v[112:115], v[174:177], v[182:185], v[112:115]
	v_mfma_f32_16x16x32_bf16 v[100:103], v[166:169], v[190:193], v[100:103]
	v_mfma_f32_16x16x32_bf16 v[96:99], v[174:177], v[190:193], v[96:99]
	v_mfma_f32_16x16x32_bf16 v[84:87], v[166:169], v[198:201], v[84:87]
	v_mfma_f32_16x16x32_bf16 v[80:83], v[174:177], v[198:201], v[80:83]
	v_mfma_f32_16x16x32_bf16 v[68:71], v[166:169], v[206:209], v[68:71]
	v_mfma_f32_16x16x32_bf16 v[64:67], v[174:177], v[206:209], v[64:67]
	v_mfma_f32_16x16x32_bf16 v[116:119], v[170:173], v[186:189], v[116:119]
	v_mfma_f32_16x16x32_bf16 v[112:115], v[178:181], v[186:189], v[112:115]
	v_mfma_f32_16x16x32_bf16 v[100:103], v[170:173], v[194:197], v[100:103]
	v_mfma_f32_16x16x32_bf16 v[96:99], v[178:181], v[194:197], v[96:99]
	v_mfma_f32_16x16x32_bf16 v[84:87], v[170:173], v[202:205], v[84:87]
	v_mfma_f32_16x16x32_bf16 v[80:83], v[178:181], v[202:205], v[80:83]
	v_mfma_f32_16x16x32_bf16 v[68:71], v[170:173], v[210:213], v[68:71]
	v_mfma_f32_16x16x32_bf16 v[64:67], v[178:181], v[210:213], v[64:67]
	s_setprio 0
	s_barrier
; #define PG8_STAGE(bufoff, gbase, voff) do { _Pragma("unroll") for (int _i = 0; _i < 2; ++_i) \
;         __builtin_amdgcn_global_load_lds((const unsigned*)((const char*)(gbase) + (voff)[_i]), (PG8_LAS unsigned*)(lds + (bufoff) + ldsw + _i * 8192), 16, 0, 0); } while (0)
; #define PG8_LDA(dst, b, h) do { _Pragma("unroll") for (int m = 0; m < 4; ++m) _Pragma("unroll") for (int k = 0; k < 2; ++k) dst[m][k] = *(const PG8_LAS bf16x8*)(lds + PG8_SA(b, h) + aoff + m * 2048 + k * 1024); } while (0)
; #define PG8_MMA(ai, bj, At, Bt) do { __builtin_amdgcn_s_setprio(1); _Pragma("unroll") for (int m = 0; m < 4; ++m) _Pragma("unroll") for (int n = 0; n < 2; ++n) _Pragma("unroll") for (int k = 0; k < 2; ++k) \
;         acc[ai][bj][m][n] = __builtin_amdgcn_mfma_f32_16x16x32_bf16(Bt[n][k], At[m][k], acc[ai][bj][m][n], 0, 0, 0); __builtin_amdgcn_s_setprio(0); } while (0)
; #define PG8_WAIT_V(n) asm volatile("s_waitcnt vmcnt(" #n ")" ::: "memory")
; #define PG8_WAIT_L(n) asm volatile("s_waitcnt lgkmcnt(" #n ")" ::: "memory")
; #define PG8_BAR __builtin_amdgcn_s_barrier()
; #define PG8_SCHED __builtin_amdgcn_sched_barrier(0)
;     __device__ __forceinline__ void operator()(const f32x4 (&acc)[2][2][4][2], const Unit& u, int wr, int wc, int fr, int fq) const {
;         const int row0 = u.pm * BM + wr * 64 + fr, col0 = u.pn * BM + wc * 32 + 8 * fq;
; #pragma unroll
;         for (int ai = 0; ai < 2; ++ai)
; #pragma unroll
;             for (int m = 0; m < 4; ++m) { const size_t row = (size_t)(row0 + ai * HALF + m * 16); float s = 0.f;
; #pragma unroll
;                 for (int bj = 0; bj < 2; ++bj) { const size_t off = row * 1024 + col0 + bj * HALF; const u32x4 h = __builtin_nontemporal_load((const u32x4*)(XB + off));
; template <class Epi, class Sched, bool ALIGN_EPI = false, bool SP2 = false>
; __device__ __forceinline__ void gemm_phase(PG8_LAS unsigned char* lds, const Gemm g, const Sched& S, const Epi& E, const int wave_s) {
;     ...
;             PG8_LDA(At, 1, 1); PG8_STAGE(PG8_SB(1, 0), b3, voffB); PG8_STAGE(PG8_SB(1, 1), b3 + hB, voffB); PG8_STAGE(PG8_SA(1, 0), a3, voffA);
;             PG8_WAIT_V(8); PG8_WAIT_L(0); PG8_BAR; PG8_MMA(1, 0, At, B0); PG8_MMA(1, 1, At, B1); PG8_BAR; PG8_SCHED;
	s_add_i32 s68, s79, s11
	v_lshl_add_u64 v[218:219], v[218:219], 0, s[36:37]
	s_mov_b32 m0, s68
	ds_read_b128 v[182:185], v157 offset:49152
	ds_read_b128 v[186:189], v157 offset:50176
	ds_read_b128 v[190:193], v157 offset:51200
	ds_read_b128 v[194:197], v157 offset:52224
	ds_read_b128 v[198:201], v157 offset:53248
	ds_read_b128 v[202:205], v157 offset:54272
	ds_read_b128 v[206:209], v157 offset:55296
	ds_read_b128 v[210:213], v157 offset:56320
	global_load_lds_dwordx4 v[218:219], off
	s_add_i32 m0, s68, 0x2000
	s_add_u32 s66, s66, 0x40080
	v_lshl_add_u64 v[218:219], v[220:221], 0, s[36:37]
	s_addc_u32 s67, s67, 0
	s_add_i32 s68, s80, s11
	global_load_lds_dwordx4 v[218:219], off
	v_lshl_add_u64 v[218:219], s[66:67], 0, v[130:131]
	s_mov_b32 m0, s68
	s_nop 0
	global_load_lds_dwordx4 v[218:219], off
	v_lshl_add_u64 v[218:219], s[66:67], 0, v[134:135]
	s_add_i32 m0, s68, 0x2000
	s_nop 0
	global_load_lds_dwordx4 v[218:219], off
	v_lshl_add_u64 v[218:219], v[222:223], 0, s[36:37]
	s_mov_b32 m0, s70
	s_nop 0
	global_load_lds_dwordx4 v[218:219], off
	v_lshl_add_u64 v[218:219], v[224:225], 0, s[36:37]
	s_mov_b32 m0, s71
	s_nop 0
	global_load_lds_dwordx4 v[218:219], off
	s_waitcnt vmcnt(8)
	s_waitcnt lgkmcnt(0)
	s_barrier
	s_setprio 1
	s_waitcnt lgkmcnt(0)
	v_mfma_f32_16x16x32_bf16 v[60:63], v[144:147], v[182:185], v[60:63]
	v_mfma_f32_16x16x32_bf16 v[56:59], v[158:161], v[182:185], v[56:59]
	v_mfma_f32_16x16x32_bf16 v[44:47], v[144:147], v[190:193], v[44:47]
	v_mfma_f32_16x16x32_bf16 v[40:43], v[158:161], v[190:193], v[40:43]
	v_mfma_f32_16x16x32_bf16 v[28:31], v[144:147], v[198:201], v[28:31]
	v_mfma_f32_16x16x32_bf16 v[24:27], v[158:161], v[198:201], v[24:27]
	v_mfma_f32_16x16x32_bf16 v[12:15], v[144:147], v[206:209], v[12:15]
	v_mfma_f32_16x16x32_bf16 v[8:11], v[158:161], v[206:209], v[8:11]
	v_mfma_f32_16x16x32_bf16 v[60:63], v[148:151], v[186:189], v[60:63]
	v_mfma_f32_16x16x32_bf16 v[56:59], v[162:165], v[186:189], v[56:59]
	v_mfma_f32_16x16x32_bf16 v[44:47], v[148:151], v[194:197], v[44:47]
	v_mfma_f32_16x16x32_bf16 v[40:43], v[162:165], v[194:197], v[40:43]
	v_mfma_f32_16x16x32_bf16 v[28:31], v[148:151], v[202:205], v[28:31]
	v_mfma_f32_16x16x32_bf16 v[24:27], v[162:165], v[202:205], v[24:27]
	v_mfma_f32_16x16x32_bf16 v[12:15], v[148:151], v[210:213], v[12:15]
	v_mfma_f32_16x16x32_bf16 v[8:11], v[162:165], v[210:213], v[8:11]
	s_setprio 0
	s_setprio 1
	v_mfma_f32_16x16x32_bf16 v[52:55], v[166:169], v[182:185], v[52:55]
	v_mfma_f32_16x16x32_bf16 v[48:51], v[174:177], v[182:185], v[48:51]
	v_mfma_f32_16x16x32_bf16 v[36:39], v[166:169], v[190:193], v[36:39]
	v_mfma_f32_16x16x32_bf16 v[32:35], v[174:177], v[190:193], v[32:35]
	v_mfma_f32_16x16x32_bf16 v[20:23], v[166:169], v[198:201], v[20:23]
	v_mfma_f32_16x16x32_bf16 v[16:19], v[174:177], v[198:201], v[16:19]
	v_mfma_f32_16x16x32_bf16 v[4:7], v[166:169], v[206:209], v[4:7]
	v_mfma_f32_16x16x32_bf16 v[0:3], v[174:177], v[206:209], v[0:3]
	v_mfma_f32_16x16x32_bf16 v[52:55], v[170:173], v[186:189], v[52:55]
	v_mfma_f32_16x16x32_bf16 v[48:51], v[178:181], v[186:189], v[48:51]
	v_mfma_f32_16x16x32_bf16 v[36:39], v[170:173], v[194:197], v[36:39]
	v_mfma_f32_16x16x32_bf16 v[32:35], v[178:181], v[194:197], v[32:35]
	v_mfma_f32_16x16x32_bf16 v[20:23], v[170:173], v[202:205], v[20:23]
	v_mfma_f32_16x16x32_bf16 v[16:19], v[178:181], v[202:205], v[16:19]
	v_mfma_f32_16x16x32_bf16 v[4:7], v[170:173], v[210:213], v[4:7]
	v_mfma_f32_16x16x32_bf16 v[0:3], v[178:181], v[210:213], v[0:3]
	s_setprio 0
	s_barrier
	s_add_i32 s78, s78, 2
	s_add_u32 s64, s64, 0x100
	s_addc_u32 s65, s65, 0
	s_add_u32 s61, s61, 0x100
	s_addc_u32 s77, s77, 0
	s_cmp_gt_u32 s78, 13
	s_cbranch_scc0 .LBB0_696
	s_and_b64 vcc, exec, s[38:39]
	s_cbranch_vccz .LBB0_699
	s_barrier
.LBB0_699:
	s_mov_b64 s[100:101], -1
	v_lshl_add_u32 v150, s62, 8, v152
	v_lshl_or_b32 v148, s60, 8, v154
	v_ashrrev_i32_e32 v151, 31, v150
	v_ashrrev_i32_e32 v149, 31, v148
	v_lshlrev_b64 v[144:145], 10, v[150:151]
	v_lshl_add_u64 v[144:145], v[144:145], 0, v[148:149]
	v_lshlrev_b64 v[146:147], 1, v[144:145]
	v_lshl_add_u64 v[162:163], s[24:25], 0, v[146:147]
	global_load_dwordx4 v[168:171], v[162:163], off nt
	global_load_dwordx4 v[172:175], v[162:163], off offset:256 nt
	s_mov_b32 s99, 0
	s_mov_b32 s98, 0x8000
	v_lshl_add_u64 v[212:213], v[162:163], 0, s[98:99]
	global_load_dwordx4 v[176:179], v[212:213], off nt
	global_load_dwordx4 v[180:183], v[212:213], off offset:256 nt
	s_mov_b32 s98, 0x10000
	v_lshl_add_u64 v[212:213], v[162:163], 0, s[98:99]
	global_load_dwordx4 v[184:187], v[212:213], off nt
	global_load_dwordx4 v[188:191], v[212:213], off offset:256 nt
	s_mov_b32 s98, 0x18000
	v_lshl_add_u64 v[212:213], v[162:163], 0, s[98:99]
	global_load_dwordx4 v[192:195], v[212:213], off nt
	global_load_dwordx4 v[196:199], v[212:213], off offset:256 nt
	s_mov_b32 s98, 0x40000
	v_lshl_add_u64 v[212:213], v[162:163], 0, s[98:99]
	global_load_dwordx4 v[200:203], v[212:213], off nt
	global_load_dwordx4 v[204:207], v[212:213], off offset:256 nt
	s_mov_b32 s98, 0x48000
	v_lshl_add_u64 v[212:213], v[162:163], 0, s[98:99]
	global_load_dwordx4 v[208:211], v[212:213], off nt
	global_load_dwordx4 v[228:231], v[212:213], off offset:256 nt
	s_mov_b32 s98, 0x50000
	v_lshl_add_u64 v[212:213], v[162:163], 0, s[98:99]
	global_load_dwordx4 v[232:235], v[212:213], off nt
	global_load_dwordx4 v[236:239], v[212:213], off offset:256 nt
	s_mov_b32 s98, 0x58000
	v_lshl_add_u64 v[212:213], v[162:163], 0, s[98:99]
	global_load_dwordx4 v[240:243], v[212:213], off nt
	global_load_dwordx4 v[244:247], v[212:213], off offset:256 nt
	v_lshl_add_u64 v[144:145], s[14:15], 0, v[146:147]
	s_waitcnt vmcnt(15)
; __device__ __forceinline__ float bflo(unsigned w) { return __uint_as_float(w << 16); }
; __device__ __forceinline__ float bfhi(unsigned w) { return __uint_as_float(w & 0xffff0000u); }
; __device__ __forceinline__ u32x4 pk8(const f32x4 a, const f32x4 b) { u32x4 w; w.x = pkbf(a[0], a[1]); w.y = pkbf(a[2], a[3]); w.z = pkbf(b[0], b[1]); w.w = pkbf(b[2], b[3]); return w; }
; __device__ __forceinline__ float sumsq4(const f32x4 a) { return (a[0] * a[0] + a[1] * a[1]) + (a[2] * a[2] + a[3] * a[3]); }
;     __device__ __forceinline__ void operator()(const f32x4 (&acc)[2][2][4][2], const Unit& u, int wr, int wc, int fr, int fq) const {
;     ...
;             for (int m = 0; m < 4; ++m) { const size_t row = (size_t)(row0 + ai * HALF + m * 16); float s = 0.f;
; #pragma unroll
;                 for (int bj = 0; bj < 2; ++bj) { const size_t off = row * 1024 + col0 + bj * HALF; const u32x4 h = __builtin_nontemporal_load((const u32x4*)(XB + off));
;                     f32x4 a = acc[ai][bj][m][0], b = acc[ai][bj][m][1];
;                     a[0] += bflo(h.x); a[1] += bfhi(h.x); a[2] += bflo(h.y); a[3] += bfhi(h.y); b[0] += bflo(h.z); b[1] += bfhi(h.z); b[2] += bflo(h.w); b[3] += bfhi(h.w);
;                     s += sumsq4(a) + sumsq4(b); *(u32x4*)(HB + off) = pk8(a, b); }
;                 s += __shfl_xor(s, 16); s += __shfl_xor(s, 32);
;                 if (fq == 0) unsafeAtomicAdd(ss + row, s); }
	v_mov_b32_e32 v158, v168
	v_mov_b32_e32 v159, v169
	v_mov_b32_e32 v160, v170
	v_mov_b32_e32 v161, v171
	v_lshlrev_b32_e32 v164, 16, v158
	v_and_b32_e32 v165, 0xffff0000, v158
	v_lshlrev_b32_e32 v158, 16, v159
	v_and_b32_e32 v159, 0xffff0000, v159
	v_lshlrev_b32_e32 v166, 16, v160
	v_and_b32_e32 v167, 0xffff0000, v160
	v_lshlrev_b32_e32 v160, 16, v161
	v_and_b32_e32 v161, 0xffff0000, v161
	v_pk_add_f32 v[124:125], v[124:125], v[164:165]
	v_pk_add_f32 v[126:127], v[126:127], v[158:159]
	v_pk_add_f32 v[158:159], v[120:121], v[166:167]
	v_pk_add_f32 v[160:161], v[122:123], v[160:161]
	v_cvt_pk_bf16_f32 v120, v124, v125
	v_cvt_pk_bf16_f32 v121, v126, v127
	v_cvt_pk_bf16_f32 v122, v158, v159
	v_cvt_pk_bf16_f32 v123, v160, v161
	global_store_dwordx4 v[144:145], v[120:123], off
	v_pk_mul_f32 v[124:125], v[124:125], v[124:125]
	v_pk_mul_f32 v[126:127], v[126:127], v[126:127]
	v_pk_mul_f32 v[158:159], v[158:159], v[158:159]
	v_pk_mul_f32 v[160:161], v[160:161], v[160:161]
	v_add_f32_e32 v158, v158, v159
	v_add_f32_e32 v160, v160, v161
	v_add_f32_e32 v126, v126, v127
	v_add_f32_e32 v124, v124, v125
	v_add_f32_e32 v125, v158, v160
	v_add_f32_e32 v124, v124, v126
	v_add_f32_e32 v158, v124, v125
	s_waitcnt vmcnt(15)
	v_mov_b32_e32 v120, v172
	v_mov_b32_e32 v121, v173
	v_mov_b32_e32 v122, v174
	v_mov_b32_e32 v123, v175
	v_lshlrev_b32_e32 v124, 16, v120
	v_and_b32_e32 v125, 0xffff0000, v120
	v_lshlrev_b32_e32 v120, 16, v121
	v_and_b32_e32 v121, 0xffff0000, v121
	v_lshlrev_b32_e32 v126, 16, v122
	v_and_b32_e32 v127, 0xffff0000, v122
	v_lshlrev_b32_e32 v122, 16, v123
	v_and_b32_e32 v123, 0xffff0000, v123
	v_pk_add_f32 v[116:117], v[116:117], v[124:125]
	v_pk_add_f32 v[118:119], v[118:119], v[120:121]
	v_pk_add_f32 v[112:113], v[112:113], v[126:127]
	v_pk_add_f32 v[114:115], v[114:115], v[122:123]
	v_pk_mul_f32 v[120:121], v[116:117], v[116:117]
	v_pk_mul_f32 v[122:123], v[118:119], v[118:119]
	v_pk_mul_f32 v[124:125], v[112:113], v[112:113]
	v_pk_mul_f32 v[126:127], v[114:115], v[114:115]
	v_add_f32_e32 v124, v124, v125
	v_add_f32_e32 v126, v126, v127
	v_add_f32_e32 v122, v122, v123
	v_add_f32_e32 v120, v120, v121
	v_add_f32_e32 v121, v124, v126
	v_add_f32_e32 v120, v120, v122
	v_add_f32_e32 v120, v120, v121
	v_add_f32_e32 v120, v158, v120
	v_mov_b32_e32 v121, v120
	s_nop 1
	v_permlane16_swap_b32_e32 v121, v120
	v_cvt_pk_bf16_f32 v116, v116, v117
	v_cvt_pk_bf16_f32 v117, v118, v119
	v_cvt_pk_bf16_f32 v119, v114, v115
	v_cvt_pk_bf16_f32 v118, v112, v113
	s_waitcnt lgkmcnt(0)
	v_add_f32_e32 v114, v120, v121
	v_mov_b32_e32 v115, v114
	s_nop 1
	v_permlane32_swap_b32_e32 v115, v114
	v_or_b32_e32 v112, 0x100, v146
	v_mov_b32_e32 v113, v147
	v_lshl_add_u64 v[112:113], s[14:15], 0, v[112:113]
	global_store_dwordx4 v[112:113], v[116:119], off
	v_lshl_add_u64 v[112:113], v[150:151], 2, s[26:27]
	s_and_saveexec_b64 s[60:61], s[4:5]
	s_cbranch_execz .LBB0_701
	s_waitcnt lgkmcnt(0)
	v_add_f32_e32 v114, v114, v115
	global_atomic_add_f32 v[112:113], v114, off
.LBB0_701:
	s_or_b64 exec, exec, s[60:61]
	v_or_b32_e32 v114, 16, v150
	s_waitcnt lgkmcnt(0)
	v_ashrrev_i32_e32 v115, 31, v114
	v_lshlrev_b64 v[114:115], 10, v[114:115]
	v_lshl_add_u64 v[114:115], v[114:115], 0, v[148:149]
	v_lshlrev_b64 v[118:119], 1, v[114:115]
	v_lshl_add_u64 v[120:121], s[24:25], 0, v[118:119]
	v_lshl_add_u64 v[122:123], s[14:15], 0, v[118:119]
	v_or_b32_e32 v118, 0x100, v118
	s_waitcnt vmcnt(15)
	v_mov_b32_e32 v114, v176
	v_mov_b32_e32 v115, v177
	v_mov_b32_e32 v116, v178
	v_mov_b32_e32 v117, v179
	v_lshlrev_b32_e32 v124, 16, v114
	v_and_b32_e32 v125, 0xffff0000, v114
	v_lshlrev_b32_e32 v114, 16, v115
	v_and_b32_e32 v115, 0xffff0000, v115
	v_lshlrev_b32_e32 v126, 16, v116
	v_and_b32_e32 v127, 0xffff0000, v116
	v_lshlrev_b32_e32 v116, 16, v117
	v_and_b32_e32 v117, 0xffff0000, v117
	v_pk_add_f32 v[108:109], v[108:109], v[124:125]
	v_pk_add_f32 v[110:111], v[110:111], v[114:115]
	v_pk_add_f32 v[114:115], v[104:105], v[126:127]
	v_pk_add_f32 v[116:117], v[106:107], v[116:117]
	v_cvt_pk_bf16_f32 v104, v108, v109
	v_cvt_pk_bf16_f32 v105, v110, v111
	v_cvt_pk_bf16_f32 v106, v114, v115
	v_cvt_pk_bf16_f32 v107, v116, v117
	global_store_dwordx4 v[122:123], v[104:107], off
	v_pk_mul_f32 v[108:109], v[108:109], v[108:109]
	v_pk_mul_f32 v[110:111], v[110:111], v[110:111]
	v_pk_mul_f32 v[114:115], v[114:115], v[114:115]
	v_pk_mul_f32 v[116:117], v[116:117], v[116:117]
	v_add_f32_e32 v114, v114, v115
	v_add_f32_e32 v116, v116, v117
	v_add_f32_e32 v110, v110, v111
	v_add_f32_e32 v108, v108, v109
	v_add_f32_e32 v109, v114, v116
	v_add_f32_e32 v108, v108, v110
	v_add_f32_e32 v114, v108, v109
	s_waitcnt vmcnt(15)
	v_mov_b32_e32 v104, v180
	v_mov_b32_e32 v105, v181
	v_mov_b32_e32 v106, v182
	v_mov_b32_e32 v107, v183
	v_lshlrev_b32_e32 v108, 16, v104
	v_and_b32_e32 v109, 0xffff0000, v104
	v_lshlrev_b32_e32 v104, 16, v105
	v_and_b32_e32 v105, 0xffff0000, v105
	v_lshlrev_b32_e32 v110, 16, v106
	v_and_b32_e32 v111, 0xffff0000, v106
	v_lshlrev_b32_e32 v106, 16, v107
	v_and_b32_e32 v107, 0xffff0000, v107
	v_pk_add_f32 v[100:101], v[100:101], v[108:109]
	v_pk_add_f32 v[102:103], v[102:103], v[104:105]
	v_pk_add_f32 v[96:97], v[96:97], v[110:111]
	v_pk_add_f32 v[104:105], v[98:99], v[106:107]
	v_pk_mul_f32 v[98:99], v[100:101], v[100:101]
	v_pk_mul_f32 v[106:107], v[102:103], v[102:103]
	v_pk_mul_f32 v[108:109], v[96:97], v[96:97]
	v_pk_mul_f32 v[110:111], v[104:105], v[104:105]
	v_add_f32_e32 v108, v108, v109
	v_add_f32_e32 v110, v110, v111
	v_add_f32_e32 v106, v106, v107
	v_add_f32_e32 v98, v98, v99
	v_add_f32_e32 v99, v108, v110
	v_add_f32_e32 v98, v98, v106
	v_add_f32_e32 v98, v98, v99
	v_add_f32_e32 v106, v114, v98
	v_mov_b32_e32 v107, v106
	s_nop 1
	v_permlane16_swap_b32_e32 v107, v106
	v_cvt_pk_bf16_f32 v98, v100, v101
	v_cvt_pk_bf16_f32 v100, v96, v97
	v_cvt_pk_bf16_f32 v99, v102, v103
	v_cvt_pk_bf16_f32 v101, v104, v105
	s_waitcnt lgkmcnt(0)
	v_add_f32_e32 v96, v106, v107
	v_mov_b32_e32 v97, v96
	s_nop 1
	v_permlane32_swap_b32_e32 v97, v96
	v_lshl_add_u64 v[102:103], s[14:15], 0, v[118:119]
	global_store_dwordx4 v[102:103], v[98:101], off
	s_and_saveexec_b64 s[60:61], s[4:5]
	s_cbranch_execz .LBB0_703
	s_waitcnt lgkmcnt(0)
	v_add_f32_e32 v96, v96, v97
	global_atomic_add_f32 v[112:113], v96, off offset:64
; __device__ __forceinline__ float bflo(unsigned w) { return __uint_as_float(w << 16); }
; __device__ __forceinline__ float bfhi(unsigned w) { return __uint_as_float(w & 0xffff0000u); }
; __device__ __forceinline__ u32x4 pk8(const f32x4 a, const f32x4 b) { u32x4 w; w.x = pkbf(a[0], a[1]); w.y = pkbf(a[2], a[3]); w.z = pkbf(b[0], b[1]); w.w = pkbf(b[2], b[3]); return w; }
; __device__ __forceinline__ float sumsq4(const f32x4 a) { return (a[0] * a[0] + a[1] * a[1]) + (a[2] * a[2] + a[3] * a[3]); }
;     __device__ __forceinline__ void operator()(const f32x4 (&acc)[2][2][4][2], const Unit& u, int wr, int wc, int fr, int fq) const {
;     ...
;             for (int m = 0; m < 4; ++m) { const size_t row = (size_t)(row0 + ai * HALF + m * 16); float s = 0.f;
; #pragma unroll
;                 for (int bj = 0; bj < 2; ++bj) { const size_t off = row * 1024 + col0 + bj * HALF; const u32x4 h = __builtin_nontemporal_load((const u32x4*)(XB + off));
;                     f32x4 a = acc[ai][bj][m][0], b = acc[ai][bj][m][1];
;                     a[0] += bflo(h.x); a[1] += bfhi(h.x); a[2] += bflo(h.y); a[3] += bfhi(h.y); b[0] += bflo(h.z); b[1] += bfhi(h.z); b[2] += bflo(h.w); b[3] += bfhi(h.w);
;                     s += sumsq4(a) + sumsq4(b); *(u32x4*)(HB + off) = pk8(a, b); }
;                 s += __shfl_xor(s, 16); s += __shfl_xor(s, 32);
;                 if (fq == 0) unsafeAtomicAdd(ss + row, s); }
.LBB0_703:
	s_or_b64 exec, exec, s[60:61]
	v_or_b32_e32 v96, 32, v150
	s_waitcnt lgkmcnt(0)
	v_ashrrev_i32_e32 v97, 31, v96
	v_lshlrev_b64 v[96:97], 10, v[96:97]
	v_lshl_add_u64 v[96:97], v[96:97], 0, v[148:149]
	v_lshlrev_b64 v[100:101], 1, v[96:97]
	v_lshl_add_u64 v[102:103], s[24:25], 0, v[100:101]
	v_lshl_add_u64 v[104:105], s[14:15], 0, v[100:101]
	v_or_b32_e32 v100, 0x100, v100
	s_waitcnt vmcnt(15)
	v_mov_b32_e32 v96, v184
	v_mov_b32_e32 v97, v185
	v_mov_b32_e32 v98, v186
	v_mov_b32_e32 v99, v187
	v_lshlrev_b32_e32 v106, 16, v96
	v_and_b32_e32 v107, 0xffff0000, v96
	v_lshlrev_b32_e32 v96, 16, v97
	v_and_b32_e32 v97, 0xffff0000, v97
	v_lshlrev_b32_e32 v108, 16, v98
	v_and_b32_e32 v109, 0xffff0000, v98
	v_lshlrev_b32_e32 v98, 16, v99
	v_and_b32_e32 v99, 0xffff0000, v99
	v_pk_add_f32 v[92:93], v[92:93], v[106:107]
	v_pk_add_f32 v[94:95], v[94:95], v[96:97]
	v_pk_add_f32 v[96:97], v[88:89], v[108:109]
	v_pk_add_f32 v[98:99], v[90:91], v[98:99]
	v_cvt_pk_bf16_f32 v88, v92, v93
	v_cvt_pk_bf16_f32 v89, v94, v95
	v_cvt_pk_bf16_f32 v90, v96, v97
	v_cvt_pk_bf16_f32 v91, v98, v99
	global_store_dwordx4 v[104:105], v[88:91], off
	v_pk_mul_f32 v[92:93], v[92:93], v[92:93]
	v_pk_mul_f32 v[94:95], v[94:95], v[94:95]
	v_pk_mul_f32 v[96:97], v[96:97], v[96:97]
	v_pk_mul_f32 v[98:99], v[98:99], v[98:99]
	v_add_f32_e32 v96, v96, v97
	v_add_f32_e32 v98, v98, v99
	v_add_f32_e32 v94, v94, v95
	v_add_f32_e32 v92, v92, v93
	v_add_f32_e32 v93, v96, v98
	v_add_f32_e32 v92, v92, v94
	v_add_f32_e32 v96, v92, v93
	s_waitcnt vmcnt(15)
	v_mov_b32_e32 v88, v188
	v_mov_b32_e32 v89, v189
	v_mov_b32_e32 v90, v190
	v_mov_b32_e32 v91, v191
	v_lshlrev_b32_e32 v92, 16, v88
	v_and_b32_e32 v93, 0xffff0000, v88
	v_lshlrev_b32_e32 v88, 16, v89
	v_and_b32_e32 v89, 0xffff0000, v89
	v_lshlrev_b32_e32 v94, 16, v90
	v_and_b32_e32 v95, 0xffff0000, v90
	v_lshlrev_b32_e32 v90, 16, v91
	v_and_b32_e32 v91, 0xffff0000, v91
	v_pk_add_f32 v[84:85], v[84:85], v[92:93]
	v_pk_add_f32 v[86:87], v[86:87], v[88:89]
	v_pk_add_f32 v[80:81], v[80:81], v[94:95]
	v_pk_add_f32 v[88:89], v[82:83], v[90:91]
	v_pk_mul_f32 v[82:83], v[84:85], v[84:85]
	v_pk_mul_f32 v[90:91], v[86:87], v[86:87]
	v_pk_mul_f32 v[92:93], v[80:81], v[80:81]
	v_pk_mul_f32 v[94:95], v[88:89], v[88:89]
	v_add_f32_e32 v92, v92, v93
	v_add_f32_e32 v94, v94, v95
	v_add_f32_e32 v90, v90, v91
	v_add_f32_e32 v82, v82, v83
	v_add_f32_e32 v83, v92, v94
	v_add_f32_e32 v82, v82, v90
	v_add_f32_e32 v82, v82, v83
	v_add_f32_e32 v90, v96, v82
	v_mov_b32_e32 v91, v90
	s_nop 1
	v_permlane16_swap_b32_e32 v91, v90
	v_cvt_pk_bf16_f32 v82, v84, v85
	v_cvt_pk_bf16_f32 v84, v80, v81
	v_cvt_pk_bf16_f32 v83, v86, v87
	v_cvt_pk_bf16_f32 v85, v88, v89
	s_waitcnt lgkmcnt(0)
	v_add_f32_e32 v80, v90, v91
	v_mov_b32_e32 v81, v80
	s_nop 1
	v_permlane32_swap_b32_e32 v81, v80
	v_lshl_add_u64 v[86:87], s[14:15], 0, v[100:101]
	global_store_dwordx4 v[86:87], v[82:85], off
	s_and_saveexec_b64 s[60:61], s[4:5]
	s_cbranch_execz .LBB0_705
	s_waitcnt lgkmcnt(0)
	v_add_f32_e32 v80, v80, v81
	global_atomic_add_f32 v[112:113], v80, off offset:128
.LBB0_705:
	s_or_b64 exec, exec, s[60:61]
	v_or_b32_e32 v80, 48, v150
	s_waitcnt lgkmcnt(0)
	v_ashrrev_i32_e32 v81, 31, v80
	v_lshlrev_b64 v[80:81], 10, v[80:81]
	v_lshl_add_u64 v[80:81], v[80:81], 0, v[148:149]
	v_lshlrev_b64 v[84:85], 1, v[80:81]
	v_lshl_add_u64 v[86:87], s[24:25], 0, v[84:85]
	v_lshl_add_u64 v[88:89], s[14:15], 0, v[84:85]
	v_or_b32_e32 v84, 0x100, v84
	s_waitcnt vmcnt(15)
	v_mov_b32_e32 v80, v192
	v_mov_b32_e32 v81, v193
	v_mov_b32_e32 v82, v194
	v_mov_b32_e32 v83, v195
	v_lshlrev_b32_e32 v90, 16, v80
	v_and_b32_e32 v91, 0xffff0000, v80
	v_lshlrev_b32_e32 v80, 16, v81
	v_and_b32_e32 v81, 0xffff0000, v81
	v_lshlrev_b32_e32 v92, 16, v82
	v_and_b32_e32 v93, 0xffff0000, v82
	v_lshlrev_b32_e32 v82, 16, v83
	v_and_b32_e32 v83, 0xffff0000, v83
	v_pk_add_f32 v[76:77], v[76:77], v[90:91]
	v_pk_add_f32 v[78:79], v[78:79], v[80:81]
	v_pk_add_f32 v[80:81], v[72:73], v[92:93]
	v_pk_add_f32 v[82:83], v[74:75], v[82:83]
	v_cvt_pk_bf16_f32 v72, v76, v77
	v_cvt_pk_bf16_f32 v73, v78, v79
	v_cvt_pk_bf16_f32 v74, v80, v81
	v_cvt_pk_bf16_f32 v75, v82, v83
	global_store_dwordx4 v[88:89], v[72:75], off
	v_pk_mul_f32 v[76:77], v[76:77], v[76:77]
	v_pk_mul_f32 v[78:79], v[78:79], v[78:79]
	v_pk_mul_f32 v[80:81], v[80:81], v[80:81]
	v_pk_mul_f32 v[82:83], v[82:83], v[82:83]
	v_add_f32_e32 v80, v80, v81
	v_add_f32_e32 v82, v82, v83
	v_add_f32_e32 v78, v78, v79
	v_add_f32_e32 v76, v76, v77
	v_add_f32_e32 v77, v80, v82
	v_add_f32_e32 v76, v76, v78
	v_add_f32_e32 v80, v76, v77
	s_waitcnt vmcnt(15)
	v_mov_b32_e32 v72, v196
	v_mov_b32_e32 v73, v197
	v_mov_b32_e32 v74, v198
	v_mov_b32_e32 v75, v199
	v_lshlrev_b32_e32 v76, 16, v72
	v_and_b32_e32 v77, 0xffff0000, v72
	v_lshlrev_b32_e32 v72, 16, v73
	v_and_b32_e32 v73, 0xffff0000, v73
	v_lshlrev_b32_e32 v78, 16, v74
	v_and_b32_e32 v79, 0xffff0000, v74
	v_lshlrev_b32_e32 v74, 16, v75
	v_and_b32_e32 v75, 0xffff0000, v75
	v_pk_add_f32 v[68:69], v[68:69], v[76:77]
	v_pk_add_f32 v[70:71], v[70:71], v[72:73]
	v_pk_add_f32 v[64:65], v[64:65], v[78:79]
	v_pk_add_f32 v[72:73], v[66:67], v[74:75]
	v_pk_mul_f32 v[66:67], v[68:69], v[68:69]
	v_pk_mul_f32 v[74:75], v[70:71], v[70:71]
	v_pk_mul_f32 v[76:77], v[64:65], v[64:65]
	v_pk_mul_f32 v[78:79], v[72:73], v[72:73]
	v_add_f32_e32 v76, v76, v77
	v_add_f32_e32 v78, v78, v79
	v_add_f32_e32 v74, v74, v75
	v_add_f32_e32 v66, v66, v67
	v_add_f32_e32 v67, v76, v78
	v_add_f32_e32 v66, v66, v74
	v_add_f32_e32 v66, v66, v67
	v_add_f32_e32 v74, v80, v66
	v_mov_b32_e32 v75, v74
	s_nop 1
	v_permlane16_swap_b32_e32 v75, v74
	v_cvt_pk_bf16_f32 v66, v68, v69
	v_cvt_pk_bf16_f32 v68, v64, v65
	v_cvt_pk_bf16_f32 v67, v70, v71
	v_cvt_pk_bf16_f32 v69, v72, v73
	s_waitcnt lgkmcnt(0)
	v_add_f32_e32 v64, v74, v75
	v_mov_b32_e32 v65, v64
	s_nop 1
	v_permlane32_swap_b32_e32 v65, v64
	v_lshl_add_u64 v[70:71], s[14:15], 0, v[84:85]
	global_store_dwordx4 v[70:71], v[66:69], off
	s_and_saveexec_b64 s[60:61], s[4:5]
	s_cbranch_execz .LBB0_707
	s_waitcnt lgkmcnt(0)
	v_add_f32_e32 v64, v64, v65
	global_atomic_add_f32 v[112:113], v64, off offset:192
; __device__ __forceinline__ float bflo(unsigned w) { return __uint_as_float(w << 16); }
; __device__ __forceinline__ float bfhi(unsigned w) { return __uint_as_float(w & 0xffff0000u); }
; __device__ __forceinline__ u32x4 pk8(const f32x4 a, const f32x4 b) { u32x4 w; w.x = pkbf(a[0], a[1]); w.y = pkbf(a[2], a[3]); w.z = pkbf(b[0], b[1]); w.w = pkbf(b[2], b[3]); return w; }
; __device__ __forceinline__ float sumsq4(const f32x4 a) { return (a[0] * a[0] + a[1] * a[1]) + (a[2] * a[2] + a[3] * a[3]); }
;     __device__ __forceinline__ void operator()(const f32x4 (&acc)[2][2][4][2], const Unit& u, int wr, int wc, int fr, int fq) const {
;     ...
;             for (int m = 0; m < 4; ++m) { const size_t row = (size_t)(row0 + ai * HALF + m * 16); float s = 0.f;
; #pragma unroll
;                 for (int bj = 0; bj < 2; ++bj) { const size_t off = row * 1024 + col0 + bj * HALF; const u32x4 h = __builtin_nontemporal_load((const u32x4*)(XB + off));
;                     f32x4 a = acc[ai][bj][m][0], b = acc[ai][bj][m][1];
;                     a[0] += bflo(h.x); a[1] += bfhi(h.x); a[2] += bflo(h.y); a[3] += bfhi(h.y); b[0] += bflo(h.z); b[1] += bfhi(h.z); b[2] += bflo(h.w); b[3] += bfhi(h.w);
;                     s += sumsq4(a) + sumsq4(b); *(u32x4*)(HB + off) = pk8(a, b); }
;                 s += __shfl_xor(s, 16); s += __shfl_xor(s, 32);
;                 if (fq == 0) unsafeAtomicAdd(ss + row, s); }
.LBB0_707:
	s_or_b64 exec, exec, s[60:61]
	v_lshl_add_u64 v[68:69], v[146:147], 0, s[0:1]
	v_lshl_add_u64 v[70:71], s[24:25], 0, v[68:69]
	s_waitcnt lgkmcnt(0)
	v_lshl_add_u64 v[68:69], s[14:15], 0, v[68:69]
	s_waitcnt vmcnt(15)
	v_mov_b32_e32 v64, v200
	v_mov_b32_e32 v65, v201
	v_mov_b32_e32 v66, v202
	v_mov_b32_e32 v67, v203
	v_lshlrev_b32_e32 v72, 16, v64
	v_and_b32_e32 v73, 0xffff0000, v64
	v_lshlrev_b32_e32 v64, 16, v65
	v_and_b32_e32 v65, 0xffff0000, v65
	v_lshlrev_b32_e32 v74, 16, v66
	v_and_b32_e32 v75, 0xffff0000, v66
	v_lshlrev_b32_e32 v66, 16, v67
	v_and_b32_e32 v67, 0xffff0000, v67
	v_pk_add_f32 v[60:61], v[60:61], v[72:73]
	v_pk_add_f32 v[62:63], v[62:63], v[64:65]
	v_pk_add_f32 v[64:65], v[56:57], v[74:75]
	v_pk_add_f32 v[66:67], v[58:59], v[66:67]
	v_cvt_pk_bf16_f32 v56, v60, v61
	v_cvt_pk_bf16_f32 v57, v62, v63
	v_cvt_pk_bf16_f32 v58, v64, v65
	v_cvt_pk_bf16_f32 v59, v66, v67
	global_store_dwordx4 v[68:69], v[56:59], off
	v_pk_mul_f32 v[60:61], v[60:61], v[60:61]
	v_pk_mul_f32 v[62:63], v[62:63], v[62:63]
	v_pk_mul_f32 v[64:65], v[64:65], v[64:65]
	v_pk_mul_f32 v[66:67], v[66:67], v[66:67]
	v_add_f32_e32 v64, v64, v65
	v_add_f32_e32 v66, v66, v67
	v_add_f32_e32 v62, v62, v63
	v_add_f32_e32 v60, v60, v61
	v_add_f32_e32 v61, v64, v66
	v_add_f32_e32 v60, v60, v62
	v_add_f32_e32 v66, v60, v61
	s_waitcnt vmcnt(15)
	v_mov_b32_e32 v56, v204
	v_mov_b32_e32 v57, v205
	v_mov_b32_e32 v58, v206
	v_mov_b32_e32 v59, v207
	v_lshlrev_b32_e32 v60, 16, v56
	v_and_b32_e32 v61, 0xffff0000, v56
	v_lshlrev_b32_e32 v56, 16, v57
	v_and_b32_e32 v57, 0xffff0000, v57
	v_lshlrev_b32_e32 v62, 16, v58
	v_and_b32_e32 v63, 0xffff0000, v58
	v_lshlrev_b32_e32 v58, 16, v59
	v_and_b32_e32 v59, 0xffff0000, v59
	v_pk_add_f32 v[52:53], v[52:53], v[60:61]
	v_pk_add_f32 v[54:55], v[54:55], v[56:57]
	v_pk_add_f32 v[48:49], v[48:49], v[62:63]
	v_pk_add_f32 v[56:57], v[50:51], v[58:59]
	v_pk_mul_f32 v[58:59], v[52:53], v[52:53]
	v_pk_mul_f32 v[60:61], v[54:55], v[54:55]
	v_pk_mul_f32 v[62:63], v[48:49], v[48:49]
	v_pk_mul_f32 v[64:65], v[56:57], v[56:57]
	v_cvt_pk_bf16_f32 v50, v52, v53
	v_add_f32_e32 v51, v64, v65
	v_add_f32_e32 v52, v62, v63
	v_add_f32_e32 v53, v60, v61
	v_add_f32_e32 v58, v58, v59
	v_add_f32_e32 v51, v52, v51
	v_add_f32_e32 v52, v58, v53
	v_add_f32_e32 v51, v52, v51
	v_add_f32_e32 v58, v66, v51
	v_cvt_pk_bf16_f32 v51, v54, v55
	v_mov_b32_e32 v55, v58
	s_nop 1
	v_permlane16_swap_b32_e32 v55, v58
	v_cvt_pk_bf16_f32 v52, v48, v49
	v_add_co_u32_e32 v54, vcc, 0x40000, v144
	v_cvt_pk_bf16_f32 v53, v56, v57
	s_waitcnt lgkmcnt(0)
	v_add_f32_e32 v48, v58, v55
	v_mov_b32_e32 v49, v48
	s_nop 1
	v_permlane32_swap_b32_e32 v49, v48
	v_addc_co_u32_e32 v55, vcc, 0, v145, vcc
	global_store_dwordx4 v[54:55], v[50:53], off offset:256
	s_and_saveexec_b64 s[60:61], s[4:5]
	s_cbranch_execz .LBB0_709
	s_waitcnt lgkmcnt(0)
	v_add_f32_e32 v48, v48, v49
	global_atomic_add_f32 v[112:113], v48, off offset:512
.LBB0_709:
	s_or_b64 exec, exec, s[60:61]
	v_lshl_add_u64 v[52:53], v[146:147], 0, s[40:41]
	v_lshl_add_u64 v[54:55], s[24:25], 0, v[52:53]
	s_waitcnt lgkmcnt(0)
	v_lshl_add_u64 v[52:53], s[14:15], 0, v[52:53]
	s_waitcnt vmcnt(15)
	v_mov_b32_e32 v48, v208
	v_mov_b32_e32 v49, v209
	v_mov_b32_e32 v50, v210
	v_mov_b32_e32 v51, v211
	v_lshlrev_b32_e32 v56, 16, v48
	v_and_b32_e32 v57, 0xffff0000, v48
	v_lshlrev_b32_e32 v48, 16, v49
	v_and_b32_e32 v49, 0xffff0000, v49
	v_lshlrev_b32_e32 v58, 16, v50
	v_and_b32_e32 v59, 0xffff0000, v50
	v_lshlrev_b32_e32 v50, 16, v51
	v_and_b32_e32 v51, 0xffff0000, v51
	v_pk_add_f32 v[44:45], v[44:45], v[56:57]
	v_pk_add_f32 v[46:47], v[46:47], v[48:49]
	v_pk_add_f32 v[48:49], v[40:41], v[58:59]
	v_pk_add_f32 v[50:51], v[42:43], v[50:51]
	v_cvt_pk_bf16_f32 v40, v44, v45
	v_cvt_pk_bf16_f32 v41, v46, v47
	v_cvt_pk_bf16_f32 v42, v48, v49
	v_cvt_pk_bf16_f32 v43, v50, v51
	global_store_dwordx4 v[52:53], v[40:43], off
	v_pk_mul_f32 v[44:45], v[44:45], v[44:45]
	v_pk_mul_f32 v[46:47], v[46:47], v[46:47]
	v_pk_mul_f32 v[48:49], v[48:49], v[48:49]
	v_pk_mul_f32 v[50:51], v[50:51], v[50:51]
	v_add_f32_e32 v48, v48, v49
	v_add_f32_e32 v50, v50, v51
	v_add_f32_e32 v46, v46, v47
	v_add_f32_e32 v44, v44, v45
	v_add_f32_e32 v45, v48, v50
	v_add_f32_e32 v44, v44, v46
	v_add_f32_e32 v50, v44, v45
	s_waitcnt vmcnt(15)
	v_mov_b32_e32 v40, v228
	v_mov_b32_e32 v41, v229
	v_mov_b32_e32 v42, v230
	v_mov_b32_e32 v43, v231
	v_lshlrev_b32_e32 v44, 16, v40
	v_and_b32_e32 v45, 0xffff0000, v40
	v_lshlrev_b32_e32 v40, 16, v41
	v_and_b32_e32 v41, 0xffff0000, v41
	v_lshlrev_b32_e32 v46, 16, v42
	v_and_b32_e32 v47, 0xffff0000, v42
	v_lshlrev_b32_e32 v42, 16, v43
	v_and_b32_e32 v43, 0xffff0000, v43
	v_pk_add_f32 v[36:37], v[36:37], v[44:45]
	v_pk_add_f32 v[38:39], v[38:39], v[40:41]
	v_pk_add_f32 v[32:33], v[32:33], v[46:47]
	v_pk_add_f32 v[40:41], v[34:35], v[42:43]
	v_pk_mul_f32 v[42:43], v[36:37], v[36:37]
	v_pk_mul_f32 v[44:45], v[38:39], v[38:39]
	v_pk_mul_f32 v[46:47], v[32:33], v[32:33]
	v_pk_mul_f32 v[48:49], v[40:41], v[40:41]
	v_cvt_pk_bf16_f32 v34, v36, v37
	v_add_f32_e32 v35, v48, v49
	v_add_f32_e32 v36, v46, v47
	v_add_f32_e32 v37, v44, v45
	v_add_f32_e32 v42, v42, v43
	v_add_f32_e32 v35, v36, v35
	v_add_f32_e32 v36, v42, v37
	v_add_f32_e32 v35, v36, v35
	v_add_f32_e32 v42, v50, v35
	v_cvt_pk_bf16_f32 v35, v38, v39
	v_mov_b32_e32 v39, v42
	s_nop 1
	v_permlane16_swap_b32_e32 v39, v42
	v_cvt_pk_bf16_f32 v36, v32, v33
	v_add_co_u32_e32 v38, vcc, 0x48000, v144
	v_cvt_pk_bf16_f32 v37, v40, v41
	s_waitcnt lgkmcnt(0)
	v_add_f32_e32 v32, v42, v39
	v_mov_b32_e32 v33, v32
	s_nop 1
	v_permlane32_swap_b32_e32 v33, v32
	v_addc_co_u32_e32 v39, vcc, 0, v145, vcc
	global_store_dwordx4 v[38:39], v[34:37], off offset:256
	s_and_saveexec_b64 s[60:61], s[4:5]
	s_cbranch_execz .LBB0_711
	s_waitcnt lgkmcnt(0)
	v_add_f32_e32 v32, v32, v33
	global_atomic_add_f32 v[112:113], v32, off offset:576
; __device__ __forceinline__ float bflo(unsigned w) { return __uint_as_float(w << 16); }
; __device__ __forceinline__ float bfhi(unsigned w) { return __uint_as_float(w & 0xffff0000u); }
; __device__ __forceinline__ u32x4 pk8(const f32x4 a, const f32x4 b) { u32x4 w; w.x = pkbf(a[0], a[1]); w.y = pkbf(a[2], a[3]); w.z = pkbf(b[0], b[1]); w.w = pkbf(b[2], b[3]); return w; }
; __device__ __forceinline__ float sumsq4(const f32x4 a) { return (a[0] * a[0] + a[1] * a[1]) + (a[2] * a[2] + a[3] * a[3]); }
;     __device__ __forceinline__ void operator()(const f32x4 (&acc)[2][2][4][2], const Unit& u, int wr, int wc, int fr, int fq) const {
;     ...
;             for (int m = 0; m < 4; ++m) { const size_t row = (size_t)(row0 + ai * HALF + m * 16); float s = 0.f;
; #pragma unroll
;                 for (int bj = 0; bj < 2; ++bj) { const size_t off = row * 1024 + col0 + bj * HALF; const u32x4 h = __builtin_nontemporal_load((const u32x4*)(XB + off));
;                     f32x4 a = acc[ai][bj][m][0], b = acc[ai][bj][m][1];
;                     a[0] += bflo(h.x); a[1] += bfhi(h.x); a[2] += bflo(h.y); a[3] += bfhi(h.y); b[0] += bflo(h.z); b[1] += bfhi(h.z); b[2] += bflo(h.w); b[3] += bfhi(h.w);
;                     s += sumsq4(a) + sumsq4(b); *(u32x4*)(HB + off) = pk8(a, b); }
;                 s += __shfl_xor(s, 16); s += __shfl_xor(s, 32);
;                 if (fq == 0) unsafeAtomicAdd(ss + row, s); }
.LBB0_711:
	s_or_b64 exec, exec, s[60:61]
	v_lshl_add_u64 v[36:37], v[146:147], 0, s[42:43]
	v_lshl_add_u64 v[38:39], s[24:25], 0, v[36:37]
	s_waitcnt lgkmcnt(0)
	v_lshl_add_u64 v[36:37], s[14:15], 0, v[36:37]
	s_waitcnt vmcnt(15)
	v_mov_b32_e32 v32, v232
	v_mov_b32_e32 v33, v233
	v_mov_b32_e32 v34, v234
	v_mov_b32_e32 v35, v235
	v_lshlrev_b32_e32 v40, 16, v32
	v_and_b32_e32 v41, 0xffff0000, v32
	v_lshlrev_b32_e32 v32, 16, v33
	v_and_b32_e32 v33, 0xffff0000, v33
	v_lshlrev_b32_e32 v42, 16, v34
	v_and_b32_e32 v43, 0xffff0000, v34
	v_lshlrev_b32_e32 v34, 16, v35
	v_and_b32_e32 v35, 0xffff0000, v35
	v_pk_add_f32 v[28:29], v[28:29], v[40:41]
	v_pk_add_f32 v[30:31], v[30:31], v[32:33]
	v_pk_add_f32 v[32:33], v[24:25], v[42:43]
	v_pk_add_f32 v[34:35], v[26:27], v[34:35]
	v_cvt_pk_bf16_f32 v24, v28, v29
	v_cvt_pk_bf16_f32 v25, v30, v31
	v_cvt_pk_bf16_f32 v26, v32, v33
	v_cvt_pk_bf16_f32 v27, v34, v35
	global_store_dwordx4 v[36:37], v[24:27], off
	v_pk_mul_f32 v[28:29], v[28:29], v[28:29]
	v_pk_mul_f32 v[30:31], v[30:31], v[30:31]
	v_pk_mul_f32 v[32:33], v[32:33], v[32:33]
	v_pk_mul_f32 v[34:35], v[34:35], v[34:35]
	v_add_f32_e32 v32, v32, v33
	v_add_f32_e32 v34, v34, v35
	v_add_f32_e32 v30, v30, v31
	v_add_f32_e32 v28, v28, v29
	v_add_f32_e32 v29, v32, v34
	v_add_f32_e32 v28, v28, v30
	v_add_f32_e32 v34, v28, v29
	s_waitcnt vmcnt(15)
	v_mov_b32_e32 v24, v236
	v_mov_b32_e32 v25, v237
	v_mov_b32_e32 v26, v238
	v_mov_b32_e32 v27, v239
	v_lshlrev_b32_e32 v28, 16, v24
	v_and_b32_e32 v29, 0xffff0000, v24
	v_lshlrev_b32_e32 v24, 16, v25
	v_and_b32_e32 v25, 0xffff0000, v25
	v_lshlrev_b32_e32 v30, 16, v26
	v_and_b32_e32 v31, 0xffff0000, v26
	v_lshlrev_b32_e32 v26, 16, v27
	v_and_b32_e32 v27, 0xffff0000, v27
	v_pk_add_f32 v[20:21], v[20:21], v[28:29]
	v_pk_add_f32 v[22:23], v[22:23], v[24:25]
	v_pk_add_f32 v[16:17], v[16:17], v[30:31]
	v_pk_add_f32 v[24:25], v[18:19], v[26:27]
	v_pk_mul_f32 v[26:27], v[20:21], v[20:21]
	v_pk_mul_f32 v[28:29], v[22:23], v[22:23]
	v_pk_mul_f32 v[30:31], v[16:17], v[16:17]
	v_pk_mul_f32 v[32:33], v[24:25], v[24:25]
	v_cvt_pk_bf16_f32 v18, v20, v21
	v_add_f32_e32 v19, v32, v33
	v_add_f32_e32 v20, v30, v31
	v_add_f32_e32 v21, v28, v29
	v_add_f32_e32 v26, v26, v27
	v_add_f32_e32 v19, v20, v19
	v_add_f32_e32 v20, v26, v21
	v_add_f32_e32 v19, v20, v19
	v_add_f32_e32 v26, v34, v19
	v_cvt_pk_bf16_f32 v19, v22, v23
	v_mov_b32_e32 v23, v26
	s_nop 1
	v_permlane16_swap_b32_e32 v23, v26
	v_cvt_pk_bf16_f32 v20, v16, v17
	v_add_co_u32_e32 v22, vcc, 0x50000, v144
	v_cvt_pk_bf16_f32 v21, v24, v25
	s_waitcnt lgkmcnt(0)
	v_add_f32_e32 v16, v26, v23
	v_mov_b32_e32 v17, v16
	s_nop 1
	v_permlane32_swap_b32_e32 v17, v16
	v_addc_co_u32_e32 v23, vcc, 0, v145, vcc
	global_store_dwordx4 v[22:23], v[18:21], off offset:256
	s_and_saveexec_b64 s[60:61], s[4:5]
	s_cbranch_execz .LBB0_713
	s_waitcnt lgkmcnt(0)
	v_add_f32_e32 v16, v16, v17
	global_atomic_add_f32 v[112:113], v16, off offset:640
.LBB0_713:
	s_or_b64 exec, exec, s[60:61]
	v_lshl_add_u64 v[20:21], v[146:147], 0, s[44:45]
	v_lshl_add_u64 v[22:23], s[24:25], 0, v[20:21]
	s_waitcnt lgkmcnt(0)
	v_lshl_add_u64 v[20:21], s[14:15], 0, v[20:21]
	s_waitcnt vmcnt(15)
	v_mov_b32_e32 v16, v240
	v_mov_b32_e32 v17, v241
	v_mov_b32_e32 v18, v242
	v_mov_b32_e32 v19, v243
	v_lshlrev_b32_e32 v24, 16, v16
	v_and_b32_e32 v25, 0xffff0000, v16
	v_lshlrev_b32_e32 v16, 16, v17
	v_and_b32_e32 v17, 0xffff0000, v17
	v_lshlrev_b32_e32 v26, 16, v18
	v_and_b32_e32 v27, 0xffff0000, v18
	v_lshlrev_b32_e32 v18, 16, v19
	v_and_b32_e32 v19, 0xffff0000, v19
	v_pk_add_f32 v[12:13], v[12:13], v[24:25]
	v_pk_add_f32 v[14:15], v[14:15], v[16:17]
	v_pk_add_f32 v[16:17], v[8:9], v[26:27]
	v_pk_add_f32 v[18:19], v[10:11], v[18:19]
	v_cvt_pk_bf16_f32 v8, v12, v13
	v_cvt_pk_bf16_f32 v9, v14, v15
	v_cvt_pk_bf16_f32 v10, v16, v17
	v_cvt_pk_bf16_f32 v11, v18, v19
	global_store_dwordx4 v[20:21], v[8:11], off
	v_pk_mul_f32 v[12:13], v[12:13], v[12:13]
	v_pk_mul_f32 v[14:15], v[14:15], v[14:15]
	v_pk_mul_f32 v[16:17], v[16:17], v[16:17]
	v_pk_mul_f32 v[18:19], v[18:19], v[18:19]
	v_add_f32_e32 v16, v16, v17
	v_add_f32_e32 v18, v18, v19
	v_add_f32_e32 v14, v14, v15
	v_add_f32_e32 v12, v12, v13
	v_add_f32_e32 v13, v16, v18
	v_add_f32_e32 v12, v12, v14
	v_add_f32_e32 v18, v12, v13
	s_waitcnt vmcnt(15)
	v_mov_b32_e32 v8, v244
	v_mov_b32_e32 v9, v245
	v_mov_b32_e32 v10, v246
	v_mov_b32_e32 v11, v247
	v_lshlrev_b32_e32 v12, 16, v8
	v_and_b32_e32 v13, 0xffff0000, v8
	v_lshlrev_b32_e32 v8, 16, v9
	v_and_b32_e32 v9, 0xffff0000, v9
	v_lshlrev_b32_e32 v14, 16, v10
	v_and_b32_e32 v15, 0xffff0000, v10
	v_lshlrev_b32_e32 v10, 16, v11
	v_and_b32_e32 v11, 0xffff0000, v11
	v_pk_add_f32 v[4:5], v[4:5], v[12:13]
	v_pk_add_f32 v[6:7], v[6:7], v[8:9]
	v_pk_add_f32 v[0:1], v[0:1], v[14:15]
	v_pk_add_f32 v[8:9], v[2:3], v[10:11]
	v_pk_mul_f32 v[10:11], v[4:5], v[4:5]
	v_pk_mul_f32 v[12:13], v[6:7], v[6:7]
	v_pk_mul_f32 v[14:15], v[0:1], v[0:1]
	v_pk_mul_f32 v[16:17], v[8:9], v[8:9]
	v_cvt_pk_bf16_f32 v2, v4, v5
	v_add_f32_e32 v3, v16, v17
	v_add_f32_e32 v4, v14, v15
	v_add_f32_e32 v5, v12, v13
	v_add_f32_e32 v10, v10, v11
	v_add_f32_e32 v3, v4, v3
	v_add_f32_e32 v4, v10, v5
	v_add_f32_e32 v3, v4, v3
	v_add_f32_e32 v10, v18, v3
	v_cvt_pk_bf16_f32 v3, v6, v7
	v_mov_b32_e32 v7, v10
	s_nop 1
	v_permlane16_swap_b32_e32 v7, v10
	v_cvt_pk_bf16_f32 v4, v0, v1
	v_add_co_u32_e32 v6, vcc, 0x58000, v144
	v_cvt_pk_bf16_f32 v5, v8, v9
	s_waitcnt lgkmcnt(0)
	v_add_f32_e32 v0, v10, v7
	v_mov_b32_e32 v1, v0
	s_nop 1
	v_permlane32_swap_b32_e32 v1, v0
	v_addc_co_u32_e32 v7, vcc, 0, v145, vcc
	global_store_dwordx4 v[6:7], v[2:5], off offset:256
	s_and_saveexec_b64 s[60:61], s[4:5]
	s_cbranch_execz .LBB0_715
	s_waitcnt lgkmcnt(0)
	v_add_f32_e32 v0, v0, v1
	global_atomic_add_f32 v[112:113], v0, off offset:704

; __device__ __forceinline__ int lane_now() { int l; asm volatile("v_mbcnt_lo_u32_b32 %0, -1, 0\n\tv_mbcnt_hi_u32_b32 %0, -1, %0" : "=v"(l)); return l; }
; #define PG8_STAGE(bufoff, gbase, voff) do { _Pragma("unroll") for (int _i = 0; _i < 2; ++_i) \
;         __builtin_amdgcn_global_load_lds((const unsigned*)((const char*)(gbase) + (voff)[_i]), (PG8_LAS unsigned*)(lds + (bufoff) + ldsw + _i * 8192), 16, 0, 0); } while (0)
; template <class Epi, class Sched, bool ALIGN_EPI = false, bool SP2 = false>
; __device__ __forceinline__ void gemm_phase(PG8_LAS unsigned char* lds, const Gemm g, const Sched& S, const Epi& E, const int wave_s) {
;     int tid_ = (wave_s << 6) | lane_now(); asm volatile("" : "+v"(tid_));
;     const int tid = tid_, wid = __builtin_amdgcn_readfirstlane(tid >> 6), lane = tid & 63, wr = wid >> 2, wc = wid & 3, fr = lane & 15, fq = lane >> 4;
;     const int K = g.K, nt = K / BK, lda = g.lda, ldb = g.ldb;
;     unsigned voffA[2], voffB[2];
; #pragma unroll
;     for (int i = 0; i < 2; ++i) { int R, C; stage_rc(tid * 16 + i * 8192, R, C); const int Rb = Epi::PERM ? ((R & ~31) + perm32(R & 31)) : R;
;         voffA[i] = (unsigned)(R * lda + C) * 2u; voffB[i] = (unsigned)(Rb * ldb + C) * 2u; }
;     const size_t kstep = (size_t)(BK * 2);
;     const size_t hA = (size_t)HALF * lda * 2, hB = (size_t)HALF * ldb * 2;
;     const size_t tA = 2 * hA, tB = 2 * hB;
;     const unsigned ldsw = (unsigned)wid * 1024u;
;     const int aoff = lds_byte(wr * 64 + fr, fq * 8), boff = lds_byte(wc * 32 + fr, fq * 8);
;     ...
;     Unit cur, nxt; int ui = 0; float pf[8] = {0.f, 0.f, 0.f, 0.f, 0.f, 0.f, 0.f, 0.f};
;     if (!S.next(0, cur)) return;
;     f32x4 acc[2][2][4][2];
; #pragma unroll
;     for (int a = 0; a < 2; ++a)
; #pragma unroll
;         for (int b = 0; b < 2; ++b)
; #pragma unroll
;             for (int m = 0; m < 4; ++m)
; #pragma unroll
;                 for (int n = 0; n < 2; ++n) acc[a][b][m][n] = (f32x4){0.f, 0.f, 0.f, 0.f};
;     bf16x8 At[4][2], B0[2][2], B1[2][2];
;     const char* cA = (const char*)g.A + (size_t)cur.pm * tA; const char* cB = (const char*)g.Bt + (size_t)cur.pn * tB;
;     S.a_ready(cur);
;     if constexpr (SP2) {
;         PG8_STAGE(PG8_SB(0, 0), cB, voffB); PG8_STAGE(PG8_SB(0, 1), cB + hB, voffB); PG8_STAGE(PG8_SA(0, 0), cA, voffA); PG8_STAGE(PG8_SA(0, 1), cA + hA, voffA);
;         if (wr == 1) PG8_BAR;
.LBB0_773:
	s_waitcnt lgkmcnt(0)
	s_barrier
	s_mov_b64 s[100:101], 0
	v_mbcnt_lo_u32_b32 v0, -1, 0
	v_mbcnt_hi_u32_b32 v0, -1, v0
	s_cmpk_gt_i32 s10, 0x17ff
	v_or_b32_e32 v9, s84, v0
	s_nop 0
	v_readfirstlane_b32 s5, v9
	s_cbranch_scc1 .LBB0_791
	v_lshlrev_b32_e32 v0, 4, v9
	v_add_u32_e32 v1, 0x2000, v0
	v_ashrrev_i32_e32 v2, 31, v1
	v_lshrrev_b32_e32 v2, 22, v2
	v_add_u32_e32 v2, v1, v2
	v_ashrrev_i32_e32 v8, 10, v2
	v_mul_i32_i24_e32 v2, 0x400, v8
	v_sub_u32_e32 v1, v1, v2
	v_lshrrev_b32_e32 v2, 4, v1
	v_bitop3_b32 v1, v2, v1, 32 bitop3:0x6c
	v_ashrrev_i32_e32 v2, 31, v1
	v_lshrrev_b32_e32 v2, 26, v2
	v_add_u32_e32 v2, v1, v2
	v_lshlrev_b32_e32 v3, 3, v8
	v_ashrrev_i32_e32 v10, 6, v2
	v_and_b32_e32 v3, -16, v3
	v_add_u32_e32 v3, v10, v3
	v_and_b32_e32 v4, 3, v10
	s_mov_b32 s0, 0x1fffe0
	v_lshrrev_b32_e32 v5, 2, v3
	v_lshlrev_b32_e32 v6, 1, v3
	v_and_b32_e32 v2, 0xc0, v2
	v_and_or_b32 v4, v3, s0, v4
	v_and_b32_e32 v5, 4, v5
	v_and_b32_e32 v6, 24, v6
	v_sub_u32_e32 v1, v1, v2
	v_mov_b32_e32 v2, 1
	v_or3_b32 v4, v4, v5, v6
	v_lshlrev_b32_e32 v5, 5, v8
	v_ashrrev_i16_sdwa v1, v2, sext(v1) dst_sel:DWORD dst_unused:UNUSED_PAD src0_sel:DWORD src1_sel:BYTE_0
	v_and_b32_e32 v5, 32, v5
	v_bfe_i32 v11, v1, 0, 16
	v_add_lshl_u32 v1, v5, v11, 1
	v_lshl_add_u32 v128, v4, 11, v1
	v_lshl_add_u32 v130, v3, 11, v1
	v_bfe_i32 v1, v9, 27, 1
	v_lshrrev_b32_e32 v1, 22, v1
	v_add_u32_e32 v1, v0, v1
	v_and_b32_e32 v1, 0xfffffc00, v1
	v_sub_u32_e32 v0, v0, v1
	v_lshrrev_b32_e32 v1, 4, v0
	v_ashrrev_i32_e32 v3, 31, v9
	v_bitop3_b32 v0, v1, v0, 32 bitop3:0x6c
	v_lshrrev_b32_e32 v3, 26, v3
	v_ashrrev_i32_e32 v1, 31, v0
	v_add_u32_e32 v3, v9, v3
	v_lshrrev_b32_e32 v1, 26, v1
	v_ashrrev_i32_e32 v13, 6, v3
	v_add_u32_e32 v1, v0, v1
	v_lshlrev_b32_e32 v3, 3, v13
	v_ashrrev_i32_e32 v12, 6, v1
	v_and_b32_e32 v3, -16, v3
	v_add_u32_e32 v3, v12, v3
	v_and_b32_e32 v4, 3, v12
	s_ashr_i32 s12, s10, 31
	v_and_or_b32 v4, v3, s0, v4
	s_lshr_b32 s0, s12, 29
	s_add_i32 s0, s10, s0
	s_ashr_i32 s6, s5, 6
	s_ashr_i32 s1, s0, 3
	s_and_b32 s0, s0, -8
	s_ashr_i32 s9, s5, 8
	s_lshl_b32 s11, s6, 10
	s_sub_i32 s0, s10, s0
	s_cmp_lt_i32 s0, 0
	s_movk_i32 s13, 0x301
	s_cselect_b32 s4, s13, 0x300
	s_mul_i32 s0, s0, s4
	s_add_i32 s0, s0, s1
	s_ashr_i32 s1, s0, 31
	s_lshr_b32 s1, s1, 25
	s_add_i32 s1, s0, s1
	s_ashr_i32 s4, s1, 7
	s_and_b32 s1, s1, 0xffffff80
	s_sub_i32 s0, s0, s1
	s_bfe_i32 s1, s0, 0x80000
	s_bfe_u32 s1, s1, 0x3000c
	s_add_i32 s1, s0, s1
	s_lshl_b32 s7, s4, 3
	s_bfe_i32 s4, s1, 0x80000
	s_and_b32 s1, s1, 0xf8
	s_sub_i32 s0, s0, s1
	s_sext_i32_i16 s4, s4
	s_sext_i32_i8 s0, s0
	v_lshrrev_b32_e32 v5, 2, v3
	v_lshlrev_b32_e32 v6, 1, v3
	v_and_b32_e32 v1, 0xc0, v1
	s_lshr_b32 s4, s4, 3
	s_add_i32 s50, s7, s0
	v_and_b32_e32 v5, 4, v5
	v_and_b32_e32 v6, 24, v6
	v_sub_u32_e32 v0, v0, v1
	s_ashr_i32 s51, s50, 31
	s_bfe_i64 s[18:19], s[4:5], 0x100000
	v_or3_b32 v4, v4, v5, v6
	v_lshlrev_b32_e32 v5, 5, v13
	v_ashrrev_i16_sdwa v0, v2, sext(v0) dst_sel:DWORD dst_unused:UNUSED_PAD src0_sel:DWORD src1_sel:BYTE_0
	s_lshl_b64 s[0:1], s[50:51], 19
	s_lshl_b64 s[18:19], s[18:19], 19
	v_and_b32_e32 v5, 32, v5
	v_bfe_i32 v14, v0, 0, 16
	s_add_u32 s56, s54, s18
	v_add_lshl_u32 v0, v5, v14, 1
	s_addc_u32 s57, s55, s19
	s_add_i32 s34, s11, 0
	v_lshl_add_u32 v132, v4, 11, v0
	s_add_i32 m0, s34, 0x10000
	v_lshl_add_u32 v134, v3, 11, v0
	global_load_lds_dwordx4 v132, s[56:57]
	s_add_i32 m0, s34, 0x12000
	s_add_u32 s18, s56, 0x40000
	global_load_lds_dwordx4 v128, s[56:57]
	s_addc_u32 s19, s57, 0
	s_add_i32 m0, s34, 0x14000
	v_mov_b32_e32 v133, 0
	global_load_lds_dwordx4 v132, s[18:19]
	s_add_i32 m0, s34, 0x16000
	s_add_u32 s58, s14, s0
	s_addc_u32 s59, s15, s1
	s_add_i32 s35, s34, 0x2000
	global_load_lds_dwordx4 v128, s[18:19]
	s_mov_b32 m0, s34
	s_add_u32 s0, s58, 0x40000
	global_load_lds_dwordx4 v134, s[58:59]
	s_mov_b32 m0, s35
	s_addc_u32 s1, s59, 0
	s_add_i32 s60, s34, 0x4000
	global_load_lds_dwordx4 v130, s[58:59]
	s_mov_b32 m0, s60
	s_add_i32 s61, s34, 0x6000
	global_load_lds_dwordx4 v134, s[0:1]
	s_mov_b32 m0, s61
	v_mov_b32_e32 v129, v133
	global_load_lds_dwordx4 v130, s[0:1]
	v_mov_b32_e32 v135, v133
	v_mov_b32_e32 v131, v133
	s_cmp_eq_u32 s9, 1
	s_mov_b32 s62, 0
	v_lshl_add_u64 v[6:7], s[56:57], 0, v[132:133]
	v_lshl_add_u64 v[4:5], s[56:57], 0, v[128:129]
	v_lshl_add_u64 v[0:1], s[58:59], 0, v[134:135]
	s_cselect_b64 s[0:1], -1, 0
	s_cmp_lg_u32 s9, 1
	v_lshl_add_u64 v[2:3], s[58:59], 0, v[130:131]
	s_cbranch_scc1 .LBB0_776
	s_barrier

; #define PG8_STAGE(bufoff, gbase, voff) do { _Pragma("unroll") for (int _i = 0; _i < 2; ++_i) \
;         __builtin_amdgcn_global_load_lds((const unsigned*)((const char*)(gbase) + (voff)[_i]), (PG8_LAS unsigned*)(lds + (bufoff) + ldsw + _i * 8192), 16, 0, 0); } while (0)
; #define PG8_LDA(dst, b, h) do { _Pragma("unroll") for (int m = 0; m < 4; ++m) _Pragma("unroll") for (int k = 0; k < 2; ++k) dst[m][k] = *(const PG8_LAS bf16x8*)(lds + PG8_SA(b, h) + aoff + m * 2048 + k * 1024); } while (0)
; #define PG8_LDB(dst, b, h) do { _Pragma("unroll") for (int n = 0; n < 2; ++n) _Pragma("unroll") for (int k = 0; k < 2; ++k) dst[n][k] = *(const PG8_LAS bf16x8*)(lds + PG8_SB(b, h) + boff + n * 2048 + k * 1024); } while (0)
; #define PG8_MMA(ai, bj, At, Bt) do { __builtin_amdgcn_s_setprio(1); _Pragma("unroll") for (int m = 0; m < 4; ++m) _Pragma("unroll") for (int n = 0; n < 2; ++n) _Pragma("unroll") for (int k = 0; k < 2; ++k) \
;         acc[ai][bj][m][n] = __builtin_amdgcn_mfma_f32_16x16x32_bf16(Bt[n][k], At[m][k], acc[ai][bj][m][n], 0, 0, 0); __builtin_amdgcn_s_setprio(0); } while (0)
; #define PG8_WAIT_V(n) asm volatile("s_waitcnt vmcnt(" #n ")" ::: "memory")
; #define PG8_WAIT_L(n) asm volatile("s_waitcnt lgkmcnt(" #n ")" ::: "memory")
; #define PG8_BAR __builtin_amdgcn_s_barrier()
; #define PG8_SCHED __builtin_amdgcn_sched_barrier(0)
; template <class Epi, class Sched, bool ALIGN_EPI = false, bool SP2 = false>
; __device__ __forceinline__ void gemm_phase(PG8_LAS unsigned char* lds, const Gemm g, const Sched& S, const Epi& E, const int wave_s) {
;     ...
;             PG8_LDB(B0, 0, 0); PG8_LDB(B1, 0, 1); PG8_SCHED; PG8_LDA(At, 0, 0); PG8_STAGE(PG8_SA(1, 1), a1 + hA, voffA);
;             PG8_WAIT_V(8); PG8_WAIT_L(0); PG8_BAR; PG8_MMA(0, 0, At, B0); PG8_MMA(0, 1, At, B1); PG8_BAR; PG8_SCHED;
;             PG8_LDA(At, 0, 1); PG8_STAGE(PG8_SB(0, 0), b2, voffB); PG8_STAGE(PG8_SB(0, 1), b2 + hB, voffB); PG8_STAGE(PG8_SA(0, 0), a2, voffA);
;             PG8_WAIT_V(8); PG8_WAIT_L(0); PG8_BAR; PG8_MMA(1, 0, At, B0); PG8_MMA(1, 1, At, B1); PG8_BAR; PG8_SCHED;
.LBB0_782:
	v_add_u32_e32 v161, s66, v149
	ds_read_b128 v[162:165], v161
	ds_read_b128 v[166:169], v161 offset:1024
	ds_read_b128 v[170:173], v161 offset:2048
	ds_read_b128 v[174:177], v161 offset:3072
	v_add_u32_e32 v161, s67, v149
	ds_read_b128 v[178:181], v161
	ds_read_b128 v[182:185], v161 offset:1024
	ds_read_b128 v[186:189], v161 offset:2048
	ds_read_b128 v[190:193], v161 offset:3072
	s_add_u32 s58, s50, 0xfffc0080
	s_addc_u32 s59, s51, -1
	s_and_b64 s[56:57], s[56:57], exec
	s_cselect_b32 s59, s9, s59
	s_cselect_b32 s58, s45, s58
	s_cselect_b32 s57, s43, s74
	s_cselect_b32 s56, s72, s73
	v_lshl_add_u64 v[230:231], s[50:51], 0, v[136:137]
	s_add_i32 m0, s34, 0xc000
	ds_read_b128 v[194:197], v151
	ds_read_b128 v[198:201], v151 offset:1024
	ds_read_b128 v[202:205], v151 offset:2048
	ds_read_b128 v[206:209], v151 offset:3072
	ds_read_b128 v[210:213], v151 offset:4096
	ds_read_b128 v[218:221], v151 offset:5120
	ds_read_b128 v[222:225], v151 offset:6144
	ds_read_b128 v[226:229], v151 offset:7168
	global_load_lds_dwordx4 v[230:231], off
	v_lshl_add_u64 v[230:231], s[50:51], 0, v[138:139]
	s_add_i32 m0, s34, 0xe000
	s_nop 0
	global_load_lds_dwordx4 v[230:231], off
	s_mov_b64 vcc, s[100:101]
	s_cbranch_vccnz .Lrlx_P5_0
	s_waitcnt vmcnt(8)
.Lrlx_P5_0:
	s_waitcnt lgkmcnt(0)
	s_barrier
	s_setprio 1
	s_waitcnt lgkmcnt(0)
	v_mfma_f32_16x16x32_bf16 v[124:127], v[162:165], v[194:197], v[124:127]
	v_mfma_f32_16x16x32_bf16 v[120:123], v[170:173], v[194:197], v[120:123]
	v_mfma_f32_16x16x32_bf16 v[108:111], v[162:165], v[202:205], v[108:111]
	v_mfma_f32_16x16x32_bf16 v[104:107], v[170:173], v[202:205], v[104:107]
	v_mfma_f32_16x16x32_bf16 v[92:95], v[162:165], v[210:213], v[92:95]
	v_mfma_f32_16x16x32_bf16 v[88:91], v[170:173], v[210:213], v[88:91]
	v_mfma_f32_16x16x32_bf16 v[76:79], v[162:165], v[222:225], v[76:79]
	v_mfma_f32_16x16x32_bf16 v[72:75], v[170:173], v[222:225], v[72:75]
	v_mfma_f32_16x16x32_bf16 v[124:127], v[166:169], v[198:201], v[124:127]
	v_mfma_f32_16x16x32_bf16 v[120:123], v[174:177], v[198:201], v[120:123]
	v_mfma_f32_16x16x32_bf16 v[108:111], v[166:169], v[206:209], v[108:111]
	v_mfma_f32_16x16x32_bf16 v[104:107], v[174:177], v[206:209], v[104:107]
	v_mfma_f32_16x16x32_bf16 v[92:95], v[166:169], v[218:221], v[92:95]
	v_mfma_f32_16x16x32_bf16 v[88:91], v[174:177], v[218:221], v[88:91]
	v_mfma_f32_16x16x32_bf16 v[76:79], v[166:169], v[226:229], v[76:79]
	v_mfma_f32_16x16x32_bf16 v[72:75], v[174:177], v[226:229], v[72:75]
	s_setprio 0
	s_setprio 1
	v_mfma_f32_16x16x32_bf16 v[116:119], v[178:181], v[194:197], v[116:119]
	v_mfma_f32_16x16x32_bf16 v[112:115], v[186:189], v[194:197], v[112:115]
	v_mfma_f32_16x16x32_bf16 v[100:103], v[178:181], v[202:205], v[100:103]
	v_mfma_f32_16x16x32_bf16 v[96:99], v[186:189], v[202:205], v[96:99]
	v_mfma_f32_16x16x32_bf16 v[84:87], v[178:181], v[210:213], v[84:87]
	v_mfma_f32_16x16x32_bf16 v[80:83], v[186:189], v[210:213], v[80:83]
	v_mfma_f32_16x16x32_bf16 v[68:71], v[178:181], v[222:225], v[68:71]
	v_mfma_f32_16x16x32_bf16 v[64:67], v[186:189], v[222:225], v[64:67]
	v_mfma_f32_16x16x32_bf16 v[116:119], v[182:185], v[198:201], v[116:119]
	v_mfma_f32_16x16x32_bf16 v[112:115], v[190:193], v[198:201], v[112:115]
	v_mfma_f32_16x16x32_bf16 v[100:103], v[182:185], v[206:209], v[100:103]
	v_mfma_f32_16x16x32_bf16 v[96:99], v[190:193], v[206:209], v[96:99]
	v_mfma_f32_16x16x32_bf16 v[84:87], v[182:185], v[218:221], v[84:87]
	v_mfma_f32_16x16x32_bf16 v[80:83], v[190:193], v[218:221], v[80:83]
	v_mfma_f32_16x16x32_bf16 v[68:71], v[182:185], v[226:229], v[68:71]
	v_mfma_f32_16x16x32_bf16 v[64:67], v[190:193], v[226:229], v[64:67]
	s_setprio 0
	s_barrier
	s_add_i32 s76, s66, s11
	v_lshl_add_u64 v[230:231], s[56:57], 0, v[132:133]
	s_mov_b32 m0, s76
	ds_read_b128 v[194:197], v151 offset:16384
	ds_read_b128 v[198:201], v151 offset:17408
	ds_read_b128 v[202:205], v151 offset:18432
	ds_read_b128 v[206:209], v151 offset:19456
	ds_read_b128 v[210:213], v151 offset:20480
	ds_read_b128 v[218:221], v151 offset:21504
	ds_read_b128 v[222:225], v151 offset:22528
	ds_read_b128 v[226:229], v151 offset:23552
	global_load_lds_dwordx4 v[230:231], off
	s_add_i32 m0, s76, 0x2000
	s_add_u32 s76, s56, 0x40000
	v_lshl_add_u64 v[232:233], s[56:57], 0, v[128:129]
	s_addc_u32 s77, s57, 0
	s_add_i32 s78, s67, s11
	global_load_lds_dwordx4 v[232:233], off
	v_lshl_add_u64 v[234:235], s[76:77], 0, v[132:133]
	s_mov_b32 m0, s78
	v_lshl_add_u64 v[236:237], s[58:59], 0, v[130:131]
	global_load_lds_dwordx4 v[234:235], off
	v_lshl_add_u64 v[234:235], s[76:77], 0, v[128:129]
	s_add_i32 m0, s78, 0x2000
	s_nop 0
	global_load_lds_dwordx4 v[234:235], off
	v_lshl_add_u64 v[234:235], s[58:59], 0, v[134:135]
	s_mov_b32 m0, s34
	s_nop 0
	global_load_lds_dwordx4 v[234:235], off
	s_mov_b32 m0, s35
	s_nop 0
	global_load_lds_dwordx4 v[236:237], off
	s_mov_b64 vcc, s[100:101]
	s_cbranch_vccnz .Lrlx_P5_1
	s_waitcnt vmcnt(8)
; #define PG8_STAGE(bufoff, gbase, voff) do { _Pragma("unroll") for (int _i = 0; _i < 2; ++_i) \
;         __builtin_amdgcn_global_load_lds((const unsigned*)((const char*)(gbase) + (voff)[_i]), (PG8_LAS unsigned*)(lds + (bufoff) + ldsw + _i * 8192), 16, 0, 0); } while (0)
; #define PG8_LDA(dst, b, h) do { _Pragma("unroll") for (int m = 0; m < 4; ++m) _Pragma("unroll") for (int k = 0; k < 2; ++k) dst[m][k] = *(const PG8_LAS bf16x8*)(lds + PG8_SA(b, h) + aoff + m * 2048 + k * 1024); } while (0)
; #define PG8_LDB(dst, b, h) do { _Pragma("unroll") for (int n = 0; n < 2; ++n) _Pragma("unroll") for (int k = 0; k < 2; ++k) dst[n][k] = *(const PG8_LAS bf16x8*)(lds + PG8_SB(b, h) + boff + n * 2048 + k * 1024); } while (0)
; #define PG8_MMA(ai, bj, At, Bt) do { __builtin_amdgcn_s_setprio(1); _Pragma("unroll") for (int m = 0; m < 4; ++m) _Pragma("unroll") for (int n = 0; n < 2; ++n) _Pragma("unroll") for (int k = 0; k < 2; ++k) \
;         acc[ai][bj][m][n] = __builtin_amdgcn_mfma_f32_16x16x32_bf16(Bt[n][k], At[m][k], acc[ai][bj][m][n], 0, 0, 0); __builtin_amdgcn_s_setprio(0); } while (0)
; #define PG8_WAIT_V(n) asm volatile("s_waitcnt vmcnt(" #n ")" ::: "memory")
; #define PG8_WAIT_L(n) asm volatile("s_waitcnt lgkmcnt(" #n ")" ::: "memory")
; #define PG8_BAR __builtin_amdgcn_s_barrier()
; #define PG8_SCHED __builtin_amdgcn_sched_barrier(0)
; template <class Epi, class Sched, bool ALIGN_EPI = false, bool SP2 = false>
; __device__ __forceinline__ void gemm_phase(PG8_LAS unsigned char* lds, const Gemm g, const Sched& S, const Epi& E, const int wave_s) {
;     ...
;             PG8_WAIT_V(8); PG8_WAIT_L(0); PG8_BAR; PG8_MMA(1, 0, At, B0); PG8_MMA(1, 1, At, B1); PG8_BAR; PG8_SCHED;
;             PG8_LDB(B0, 1, 0); PG8_LDB(B1, 1, 1); PG8_SCHED; PG8_LDA(At, 1, 0); PG8_STAGE(PG8_SA(0, 1), a2 + hA, voffA);
;             PG8_WAIT_V(8); PG8_WAIT_L(0); PG8_BAR; PG8_MMA(0, 0, At, B0); PG8_MMA(0, 1, At, B1); PG8_BAR; PG8_SCHED;
.Lrlx_P5_1:
	s_mov_b64 s[100:101], 0
	s_waitcnt lgkmcnt(0)
	s_barrier
	s_setprio 1
	s_waitcnt lgkmcnt(0)
	v_mfma_f32_16x16x32_bf16 v[60:63], v[162:165], v[194:197], v[60:63]
	v_mfma_f32_16x16x32_bf16 v[56:59], v[170:173], v[194:197], v[56:59]
	v_mfma_f32_16x16x32_bf16 v[44:47], v[162:165], v[202:205], v[44:47]
	v_mfma_f32_16x16x32_bf16 v[40:43], v[170:173], v[202:205], v[40:43]
	v_mfma_f32_16x16x32_bf16 v[28:31], v[162:165], v[210:213], v[28:31]
	v_mfma_f32_16x16x32_bf16 v[24:27], v[170:173], v[210:213], v[24:27]
	v_mfma_f32_16x16x32_bf16 v[12:15], v[162:165], v[222:225], v[12:15]
	v_mfma_f32_16x16x32_bf16 v[8:11], v[170:173], v[222:225], v[8:11]
	v_mfma_f32_16x16x32_bf16 v[60:63], v[166:169], v[198:201], v[60:63]
	v_mfma_f32_16x16x32_bf16 v[56:59], v[174:177], v[198:201], v[56:59]
	v_mfma_f32_16x16x32_bf16 v[44:47], v[166:169], v[206:209], v[44:47]
	v_mfma_f32_16x16x32_bf16 v[40:43], v[174:177], v[206:209], v[40:43]
	v_mfma_f32_16x16x32_bf16 v[28:31], v[166:169], v[218:221], v[28:31]
	v_mfma_f32_16x16x32_bf16 v[24:27], v[174:177], v[218:221], v[24:27]
	v_mfma_f32_16x16x32_bf16 v[12:15], v[166:169], v[226:229], v[12:15]
	v_mfma_f32_16x16x32_bf16 v[8:11], v[174:177], v[226:229], v[8:11]
	s_setprio 0
	s_setprio 1
	v_mfma_f32_16x16x32_bf16 v[52:55], v[178:181], v[194:197], v[52:55]
	v_mfma_f32_16x16x32_bf16 v[48:51], v[186:189], v[194:197], v[48:51]
	v_mfma_f32_16x16x32_bf16 v[36:39], v[178:181], v[202:205], v[36:39]
	v_mfma_f32_16x16x32_bf16 v[32:35], v[186:189], v[202:205], v[32:35]
	v_mfma_f32_16x16x32_bf16 v[20:23], v[178:181], v[210:213], v[20:23]
	v_mfma_f32_16x16x32_bf16 v[16:19], v[186:189], v[210:213], v[16:19]
	v_mfma_f32_16x16x32_bf16 v[4:7], v[178:181], v[222:225], v[4:7]
	v_mfma_f32_16x16x32_bf16 v[0:3], v[186:189], v[222:225], v[0:3]
	v_mfma_f32_16x16x32_bf16 v[52:55], v[182:185], v[198:201], v[52:55]
	v_mfma_f32_16x16x32_bf16 v[48:51], v[190:193], v[198:201], v[48:51]
	v_mfma_f32_16x16x32_bf16 v[36:39], v[182:185], v[206:209], v[36:39]
	v_mfma_f32_16x16x32_bf16 v[32:35], v[190:193], v[206:209], v[32:35]
	v_mfma_f32_16x16x32_bf16 v[20:23], v[182:185], v[218:221], v[20:23]
	v_mfma_f32_16x16x32_bf16 v[16:19], v[190:193], v[218:221], v[16:19]
	v_mfma_f32_16x16x32_bf16 v[4:7], v[182:185], v[226:229], v[4:7]
	v_mfma_f32_16x16x32_bf16 v[0:3], v[190:193], v[226:229], v[0:3]
	s_setprio 0
	s_barrier
	s_add_i32 s76, 0, 0x18000
	v_add_u32_e32 v161, s76, v149
	s_add_i32 s77, 0, 0x1c000
	ds_read_b128 v[162:165], v161
	ds_read_b128 v[166:169], v161 offset:1024
	ds_read_b128 v[170:173], v161 offset:2048
	ds_read_b128 v[174:177], v161 offset:3072
	v_add_u32_e32 v161, s77, v149
	ds_read_b128 v[178:181], v161
	ds_read_b128 v[182:185], v161 offset:1024
	ds_read_b128 v[186:189], v161 offset:2048
	ds_read_b128 v[190:193], v161 offset:3072
	s_add_u32 s58, s58, 0x40000
	s_addc_u32 s59, s59, 0
	s_mov_b32 m0, s60
	v_lshl_add_u64 v[238:239], s[58:59], 0, v[134:135]
	ds_read_b128 v[194:197], v151 offset:32768
	ds_read_b128 v[198:201], v151 offset:33792
	ds_read_b128 v[202:205], v151 offset:34816
	ds_read_b128 v[206:209], v151 offset:35840
	ds_read_b128 v[210:213], v151 offset:36864
	ds_read_b128 v[218:221], v151 offset:37888
	ds_read_b128 v[222:225], v151 offset:38912
	ds_read_b128 v[226:229], v151 offset:39936
	global_load_lds_dwordx4 v[238:239], off
	v_lshl_add_u64 v[238:239], s[58:59], 0, v[130:131]
	s_mov_b32 m0, s61
	s_nop 0
	global_load_lds_dwordx4 v[238:239], off
	s_waitcnt vmcnt(8)
	s_waitcnt lgkmcnt(0)
	s_barrier
	s_setprio 1
	s_waitcnt lgkmcnt(0)
	v_mfma_f32_16x16x32_bf16 v[124:127], v[162:165], v[194:197], v[124:127]
	v_mfma_f32_16x16x32_bf16 v[120:123], v[170:173], v[194:197], v[120:123]
	v_mfma_f32_16x16x32_bf16 v[108:111], v[162:165], v[202:205], v[108:111]
	v_mfma_f32_16x16x32_bf16 v[104:107], v[170:173], v[202:205], v[104:107]
	v_mfma_f32_16x16x32_bf16 v[92:95], v[162:165], v[210:213], v[92:95]
	v_mfma_f32_16x16x32_bf16 v[88:91], v[170:173], v[210:213], v[88:91]
	v_mfma_f32_16x16x32_bf16 v[76:79], v[162:165], v[222:225], v[76:79]
	v_mfma_f32_16x16x32_bf16 v[72:75], v[170:173], v[222:225], v[72:75]
	v_mfma_f32_16x16x32_bf16 v[124:127], v[166:169], v[198:201], v[124:127]
	v_mfma_f32_16x16x32_bf16 v[120:123], v[174:177], v[198:201], v[120:123]
	v_mfma_f32_16x16x32_bf16 v[108:111], v[166:169], v[206:209], v[108:111]
	v_mfma_f32_16x16x32_bf16 v[104:107], v[174:177], v[206:209], v[104:107]
	v_mfma_f32_16x16x32_bf16 v[92:95], v[166:169], v[218:221], v[92:95]
	v_mfma_f32_16x16x32_bf16 v[88:91], v[174:177], v[218:221], v[88:91]
	v_mfma_f32_16x16x32_bf16 v[76:79], v[166:169], v[226:229], v[76:79]
	v_mfma_f32_16x16x32_bf16 v[72:75], v[174:177], v[226:229], v[72:75]
	s_setprio 0
	s_setprio 1
	v_mfma_f32_16x16x32_bf16 v[116:119], v[178:181], v[194:197], v[116:119]
	v_mfma_f32_16x16x32_bf16 v[112:115], v[186:189], v[194:197], v[112:115]
	v_mfma_f32_16x16x32_bf16 v[100:103], v[178:181], v[202:205], v[100:103]
	v_mfma_f32_16x16x32_bf16 v[96:99], v[186:189], v[202:205], v[96:99]
	v_mfma_f32_16x16x32_bf16 v[84:87], v[178:181], v[210:213], v[84:87]
	v_mfma_f32_16x16x32_bf16 v[80:83], v[186:189], v[210:213], v[80:83]
	v_mfma_f32_16x16x32_bf16 v[68:71], v[178:181], v[222:225], v[68:71]
	v_mfma_f32_16x16x32_bf16 v[64:67], v[186:189], v[222:225], v[64:67]
	v_mfma_f32_16x16x32_bf16 v[116:119], v[182:185], v[198:201], v[116:119]
	v_mfma_f32_16x16x32_bf16 v[112:115], v[190:193], v[198:201], v[112:115]
	v_mfma_f32_16x16x32_bf16 v[100:103], v[182:185], v[206:209], v[100:103]
	v_mfma_f32_16x16x32_bf16 v[96:99], v[190:193], v[206:209], v[96:99]
	v_mfma_f32_16x16x32_bf16 v[84:87], v[182:185], v[218:221], v[84:87]
	v_mfma_f32_16x16x32_bf16 v[80:83], v[190:193], v[218:221], v[80:83]
	v_mfma_f32_16x16x32_bf16 v[68:71], v[182:185], v[226:229], v[68:71]
	v_mfma_f32_16x16x32_bf16 v[64:67], v[190:193], v[226:229], v[64:67]
	s_setprio 0
	s_barrier
; #define PG8_STAGE(bufoff, gbase, voff) do { _Pragma("unroll") for (int _i = 0; _i < 2; ++_i) \
;         __builtin_amdgcn_global_load_lds((const unsigned*)((const char*)(gbase) + (voff)[_i]), (PG8_LAS unsigned*)(lds + (bufoff) + ldsw + _i * 8192), 16, 0, 0); } while (0)
; #define PG8_LDA(dst, b, h) do { _Pragma("unroll") for (int m = 0; m < 4; ++m) _Pragma("unroll") for (int k = 0; k < 2; ++k) dst[m][k] = *(const PG8_LAS bf16x8*)(lds + PG8_SA(b, h) + aoff + m * 2048 + k * 1024); } while (0)
; #define PG8_MMA(ai, bj, At, Bt) do { __builtin_amdgcn_s_setprio(1); _Pragma("unroll") for (int m = 0; m < 4; ++m) _Pragma("unroll") for (int n = 0; n < 2; ++n) _Pragma("unroll") for (int k = 0; k < 2; ++k) \
;         acc[ai][bj][m][n] = __builtin_amdgcn_mfma_f32_16x16x32_bf16(Bt[n][k], At[m][k], acc[ai][bj][m][n], 0, 0, 0); __builtin_amdgcn_s_setprio(0); } while (0)
; #define PG8_WAIT_V(n) asm volatile("s_waitcnt vmcnt(" #n ")" ::: "memory")
; #define PG8_WAIT_L(n) asm volatile("s_waitcnt lgkmcnt(" #n ")" ::: "memory")
; #define PG8_BAR __builtin_amdgcn_s_barrier()
; #define PG8_SCHED __builtin_amdgcn_sched_barrier(0)
; template <class Epi, class Sched, bool ALIGN_EPI = false, bool SP2 = false>
; __device__ __forceinline__ void gemm_phase(PG8_LAS unsigned char* lds, const Gemm g, const Sched& S, const Epi& E, const int wave_s) {
;     ...
;             PG8_LDA(At, 1, 1); PG8_STAGE(PG8_SB(1, 0), b3, voffB); PG8_STAGE(PG8_SB(1, 1), b3 + hB, voffB); PG8_STAGE(PG8_SA(1, 0), a3, voffA);
;             PG8_WAIT_V(8); PG8_WAIT_L(0); PG8_BAR; PG8_MMA(1, 0, At, B0); PG8_MMA(1, 1, At, B1); PG8_BAR; PG8_SCHED;
	s_add_i32 s58, s76, s11
	v_lshl_add_u64 v[230:231], v[230:231], 0, s[6:7]
	s_mov_b32 m0, s58
	ds_read_b128 v[194:197], v151 offset:49152
	ds_read_b128 v[198:201], v151 offset:50176
	ds_read_b128 v[202:205], v151 offset:51200
	ds_read_b128 v[206:209], v151 offset:52224
	ds_read_b128 v[210:213], v151 offset:53248
	ds_read_b128 v[218:221], v151 offset:54272
	ds_read_b128 v[222:225], v151 offset:55296
	ds_read_b128 v[226:229], v151 offset:56320
	global_load_lds_dwordx4 v[230:231], off
	s_add_i32 m0, s58, 0x2000
	s_add_u32 s56, s56, 0x40080
	v_lshl_add_u64 v[230:231], v[232:233], 0, s[6:7]
	s_addc_u32 s57, s57, 0
	s_add_i32 s58, s77, s11
	global_load_lds_dwordx4 v[230:231], off
	v_lshl_add_u64 v[230:231], s[56:57], 0, v[132:133]
	s_mov_b32 m0, s58
	s_nop 0
	global_load_lds_dwordx4 v[230:231], off
	v_lshl_add_u64 v[230:231], s[56:57], 0, v[128:129]
	s_add_i32 m0, s58, 0x2000
	s_nop 0
	global_load_lds_dwordx4 v[230:231], off
	v_lshl_add_u64 v[230:231], v[234:235], 0, s[6:7]
	s_mov_b32 m0, s63
	s_nop 0
	global_load_lds_dwordx4 v[230:231], off
	v_lshl_add_u64 v[230:231], v[236:237], 0, s[6:7]
	s_mov_b32 m0, s64
	s_nop 0
	global_load_lds_dwordx4 v[230:231], off
	s_waitcnt vmcnt(8)
	s_waitcnt lgkmcnt(0)
	s_barrier
	s_setprio 1
	s_waitcnt lgkmcnt(0)
	v_mfma_f32_16x16x32_bf16 v[60:63], v[162:165], v[194:197], v[60:63]
	v_mfma_f32_16x16x32_bf16 v[56:59], v[170:173], v[194:197], v[56:59]
	v_mfma_f32_16x16x32_bf16 v[44:47], v[162:165], v[202:205], v[44:47]
	v_mfma_f32_16x16x32_bf16 v[40:43], v[170:173], v[202:205], v[40:43]
	v_mfma_f32_16x16x32_bf16 v[28:31], v[162:165], v[210:213], v[28:31]
	v_mfma_f32_16x16x32_bf16 v[24:27], v[170:173], v[210:213], v[24:27]
	v_mfma_f32_16x16x32_bf16 v[12:15], v[162:165], v[222:225], v[12:15]
	v_mfma_f32_16x16x32_bf16 v[8:11], v[170:173], v[222:225], v[8:11]
	v_mfma_f32_16x16x32_bf16 v[60:63], v[166:169], v[198:201], v[60:63]
	v_mfma_f32_16x16x32_bf16 v[56:59], v[174:177], v[198:201], v[56:59]
	v_mfma_f32_16x16x32_bf16 v[44:47], v[166:169], v[206:209], v[44:47]
	v_mfma_f32_16x16x32_bf16 v[40:43], v[174:177], v[206:209], v[40:43]
	v_mfma_f32_16x16x32_bf16 v[28:31], v[166:169], v[218:221], v[28:31]
	v_mfma_f32_16x16x32_bf16 v[24:27], v[174:177], v[218:221], v[24:27]
	v_mfma_f32_16x16x32_bf16 v[12:15], v[166:169], v[226:229], v[12:15]
	v_mfma_f32_16x16x32_bf16 v[8:11], v[174:177], v[226:229], v[8:11]
	s_setprio 0
	s_setprio 1
	v_mfma_f32_16x16x32_bf16 v[52:55], v[178:181], v[194:197], v[52:55]
	v_mfma_f32_16x16x32_bf16 v[48:51], v[186:189], v[194:197], v[48:51]
	v_mfma_f32_16x16x32_bf16 v[36:39], v[178:181], v[202:205], v[36:39]
	v_mfma_f32_16x16x32_bf16 v[32:35], v[186:189], v[202:205], v[32:35]
	v_mfma_f32_16x16x32_bf16 v[20:23], v[178:181], v[210:213], v[20:23]
	v_mfma_f32_16x16x32_bf16 v[16:19], v[186:189], v[210:213], v[16:19]
	v_mfma_f32_16x16x32_bf16 v[4:7], v[178:181], v[222:225], v[4:7]
	v_mfma_f32_16x16x32_bf16 v[0:3], v[186:189], v[222:225], v[0:3]
	v_mfma_f32_16x16x32_bf16 v[52:55], v[182:185], v[198:201], v[52:55]
	v_mfma_f32_16x16x32_bf16 v[48:51], v[190:193], v[198:201], v[48:51]
	v_mfma_f32_16x16x32_bf16 v[36:39], v[182:185], v[206:209], v[36:39]
	v_mfma_f32_16x16x32_bf16 v[32:35], v[190:193], v[206:209], v[32:35]
	v_mfma_f32_16x16x32_bf16 v[20:23], v[182:185], v[218:221], v[20:23]
	v_mfma_f32_16x16x32_bf16 v[16:19], v[190:193], v[218:221], v[16:19]
	v_mfma_f32_16x16x32_bf16 v[4:7], v[182:185], v[226:229], v[4:7]
	v_mfma_f32_16x16x32_bf16 v[0:3], v[190:193], v[226:229], v[0:3]
	s_setprio 0
	s_barrier
	s_add_i32 s75, s75, 2
	s_add_u32 s50, s50, 0x100
	s_addc_u32 s51, s51, 0
	s_add_u32 s73, s73, 0x100
	s_addc_u32 s74, s74, 0
	s_cmp_gt_u32 s75, 13
	s_cbranch_scc1 .LBB0_785

; #define PG8_BAR __builtin_amdgcn_s_barrier()
; template <class Epi, class Sched, bool ALIGN_EPI = false, bool SP2 = false>
; __device__ __forceinline__ void gemm_phase(PG8_LAS unsigned char* lds, const Gemm g, const Sched& S, const Epi& E, const int wave_s) {
;     ...
;         if constexpr (ALIGN_EPI) { if (wr == 0) PG8_BAR; }
.LBB0_785:
	s_mov_b64 s[100:101], -1
	s_and_b64 vcc, exec, s[18:19]
	s_cbranch_vccz .LBB0_787
	s_barrier

;     __host__ __device__ bool next(int i, Unit& u) const {
;         const long L = (long)i * G + c; if (L >= nwg) return false;
;         int wgid = (int)L; { const int q = nwg / NXCD, r = nwg % NXCD, xcd = wgid % NXCD, off = wgid / NXCD; wgid = (xcd < r ? xcd * (q + 1) : r * (q + 1) + (xcd - r) * q) + off; }
;         const int nig = WGM * nN, gid = wgid / nig, fm = gid * WGM, gsz = (nM - fm) < WGM ? (nM - fm) : WGM;
;         u.pm = fm + ((wgid % nig) % gsz); u.pn = (wgid % nig) / gsz; if (rev) u.pm = nM - 1 - u.pm; return true;
.LBB0_845:
	s_waitcnt lgkmcnt(0)
	s_barrier
	s_mov_b64 s[100:101], 0
	v_mbcnt_lo_u32_b32 v0, -1, 0
	v_mbcnt_hi_u32_b32 v0, -1, v0
	s_and_b64 vcc, exec, s[2:3]
	v_or_b32_e32 v8, s84, v0
	s_nop 0
	v_readfirstlane_b32 s4, v8
	s_cbranch_vccnz .LBB0_847
	s_ashr_i32 s0, s10, 31
	s_lshr_b32 s0, s0, 29
	s_add_i32 s0, s10, s0
	s_ashr_i32 s1, s0, 3
	s_and_b32 s0, s0, -8
	s_sub_i32 s0, s10, s0
	s_cmp_lt_i32 s0, 0
	s_movk_i32 s5, 0xc1
	s_cselect_b32 s5, s5, 0xc0
	s_mul_i32 s0, s0, s5
	s_add_i32 s0, s0, s1
	s_ashr_i32 s1, s0, 31
	s_lshr_b32 s1, s1, 27
	s_add_i32 s1, s0, s1
	s_ashr_i32 s5, s1, 5
	s_andn2_b32 s1, s1, 31
	s_sub_i32 s0, s0, s1
	s_bfe_i32 s1, s0, 0x80000
	s_bfe_u32 s1, s1, 0x3000c
	s_add_i32 s1, s0, s1
	s_bfe_i32 s6, s1, 0x80000
	s_and_b32 s1, s1, 0xf8
	s_sub_i32 s0, s1, s0
	s_sext_i32_i8 s0, s0
	s_lshl_b32 s1, s5, 3
	s_sext_i32_i16 s6, s6
	s_sub_i32 s0, s0, s1
	s_ashr_i32 s44, s6, 3
	s_add_i32 s46, s0, 0x17f

; #define PG8_STAGE(bufoff, gbase, voff) do { _Pragma("unroll") for (int _i = 0; _i < 2; ++_i) \
;         __builtin_amdgcn_global_load_lds((const unsigned*)((const char*)(gbase) + (voff)[_i]), (PG8_LAS unsigned*)(lds + (bufoff) + ldsw + _i * 8192), 16, 0, 0); } while (0)
; #define PG8_LDA(dst, b, h) do { _Pragma("unroll") for (int m = 0; m < 4; ++m) _Pragma("unroll") for (int k = 0; k < 2; ++k) dst[m][k] = *(const PG8_LAS bf16x8*)(lds + PG8_SA(b, h) + aoff + m * 2048 + k * 1024); } while (0)
; #define PG8_LDB(dst, b, h) do { _Pragma("unroll") for (int n = 0; n < 2; ++n) _Pragma("unroll") for (int k = 0; k < 2; ++k) dst[n][k] = *(const PG8_LAS bf16x8*)(lds + PG8_SB(b, h) + boff + n * 2048 + k * 1024); } while (0)
; #define PG8_MMA(ai, bj, At, Bt) do { __builtin_amdgcn_s_setprio(1); _Pragma("unroll") for (int m = 0; m < 4; ++m) _Pragma("unroll") for (int n = 0; n < 2; ++n) _Pragma("unroll") for (int k = 0; k < 2; ++k) \
;         acc[ai][bj][m][n] = __builtin_amdgcn_mfma_f32_16x16x32_bf16(Bt[n][k], At[m][k], acc[ai][bj][m][n], 0, 0, 0); __builtin_amdgcn_s_setprio(0); } while (0)
; #define PG8_WAIT_V(n) asm volatile("s_waitcnt vmcnt(" #n ")" ::: "memory")
; #define PG8_WAIT_L(n) asm volatile("s_waitcnt lgkmcnt(" #n ")" ::: "memory")
; #define PG8_BAR __builtin_amdgcn_s_barrier()
; #define PG8_SCHED __builtin_amdgcn_sched_barrier(0)
; template <class Epi, class Sched, bool ALIGN_EPI = false, bool SP2 = false>
; __device__ __forceinline__ void gemm_phase(PG8_LAS unsigned char* lds, const Gemm g, const Sched& S, const Epi& E, const int wave_s) {
;     ...
;             PG8_LDB(B0, 0, 0); PG8_LDB(B1, 0, 1); PG8_SCHED; PG8_LDA(At, 0, 0); PG8_STAGE(PG8_SA(1, 1), a1 + hA, voffA);
;             PG8_WAIT_V(8); PG8_WAIT_L(0); PG8_BAR; PG8_MMA(0, 0, At, B0); PG8_MMA(0, 1, At, B1); PG8_BAR; PG8_SCHED;
;             PG8_LDA(At, 0, 1); PG8_STAGE(PG8_SB(0, 0), b2, voffB); PG8_STAGE(PG8_SB(0, 1), b2 + hB, voffB); PG8_STAGE(PG8_SA(0, 0), a2, voffA);
;             PG8_WAIT_V(8); PG8_WAIT_L(0); PG8_BAR; PG8_MMA(1, 0, At, B0); PG8_MMA(1, 1, At, B1); PG8_BAR; PG8_SCHED;
.LBB0_856:
	ds_read_b128 v[144:147], v151
	ds_read_b128 v[154:157], v151 offset:1024
	ds_read_b128 v[158:161], v151 offset:2048
	ds_read_b128 v[162:165], v151 offset:3072
	ds_read_b128 v[166:169], v152
	ds_read_b128 v[170:173], v152 offset:1024
	ds_read_b128 v[174:177], v152 offset:2048
	ds_read_b128 v[178:181], v152 offset:3072
	s_add_u32 s50, s48, 0xfff00080
	s_addc_u32 s51, s49, -1
	s_cmp_eq_u32 s64, 60
	s_cselect_b32 s55, s8, s51
	s_cselect_b32 s54, s9, s50
	s_cselect_b32 s51, s37, s63
	s_cselect_b32 s50, s39, s45
	v_lshl_add_u64 v[218:219], s[48:49], 0, v[136:137]
	s_add_i32 m0, s12, 0xc000
	ds_read_b128 v[182:185], v153
	ds_read_b128 v[186:189], v153 offset:1024
	ds_read_b128 v[190:193], v153 offset:2048
	ds_read_b128 v[194:197], v153 offset:3072
	ds_read_b128 v[198:201], v153 offset:4096
	ds_read_b128 v[202:205], v153 offset:5120
	ds_read_b128 v[206:209], v153 offset:6144
	ds_read_b128 v[210:213], v153 offset:7168
	global_load_lds_dwordx4 v[218:219], off
	v_lshl_add_u64 v[218:219], s[48:49], 0, v[138:139]
	s_add_i32 m0, s12, 0xe000
	s_nop 0
	global_load_lds_dwordx4 v[218:219], off
	s_mov_b64 vcc, s[100:101]
	s_cbranch_vccnz .Lrlx_P6_0
	s_waitcnt vmcnt(8)
.Lrlx_P6_0:
	s_waitcnt lgkmcnt(0)
	s_barrier
	s_setprio 1
	s_waitcnt lgkmcnt(0)
	v_mfma_f32_16x16x32_bf16 v[124:127], v[144:147], v[182:185], v[124:127]
	v_mfma_f32_16x16x32_bf16 v[120:123], v[158:161], v[182:185], v[120:123]
	v_mfma_f32_16x16x32_bf16 v[108:111], v[144:147], v[190:193], v[108:111]
	v_mfma_f32_16x16x32_bf16 v[104:107], v[158:161], v[190:193], v[104:107]
	v_mfma_f32_16x16x32_bf16 v[92:95], v[144:147], v[198:201], v[92:95]
	v_mfma_f32_16x16x32_bf16 v[88:91], v[158:161], v[198:201], v[88:91]
	v_mfma_f32_16x16x32_bf16 v[76:79], v[144:147], v[206:209], v[76:79]
	v_mfma_f32_16x16x32_bf16 v[72:75], v[158:161], v[206:209], v[72:75]
	v_mfma_f32_16x16x32_bf16 v[124:127], v[154:157], v[186:189], v[124:127]
	v_mfma_f32_16x16x32_bf16 v[120:123], v[162:165], v[186:189], v[120:123]
	v_mfma_f32_16x16x32_bf16 v[108:111], v[154:157], v[194:197], v[108:111]
	v_mfma_f32_16x16x32_bf16 v[104:107], v[162:165], v[194:197], v[104:107]
	v_mfma_f32_16x16x32_bf16 v[92:95], v[154:157], v[202:205], v[92:95]
	v_mfma_f32_16x16x32_bf16 v[88:91], v[162:165], v[202:205], v[88:91]
	v_mfma_f32_16x16x32_bf16 v[76:79], v[154:157], v[210:213], v[76:79]
	v_mfma_f32_16x16x32_bf16 v[72:75], v[162:165], v[210:213], v[72:75]
	s_setprio 0
	s_setprio 1
	v_mfma_f32_16x16x32_bf16 v[116:119], v[166:169], v[182:185], v[116:119]
	v_mfma_f32_16x16x32_bf16 v[112:115], v[174:177], v[182:185], v[112:115]
	v_mfma_f32_16x16x32_bf16 v[100:103], v[166:169], v[190:193], v[100:103]
	v_mfma_f32_16x16x32_bf16 v[96:99], v[174:177], v[190:193], v[96:99]
	v_mfma_f32_16x16x32_bf16 v[84:87], v[166:169], v[198:201], v[84:87]
	v_mfma_f32_16x16x32_bf16 v[80:83], v[174:177], v[198:201], v[80:83]
	v_mfma_f32_16x16x32_bf16 v[68:71], v[166:169], v[206:209], v[68:71]
	v_mfma_f32_16x16x32_bf16 v[64:67], v[174:177], v[206:209], v[64:67]
	v_mfma_f32_16x16x32_bf16 v[116:119], v[170:173], v[186:189], v[116:119]
	v_mfma_f32_16x16x32_bf16 v[112:115], v[178:181], v[186:189], v[112:115]
	v_mfma_f32_16x16x32_bf16 v[100:103], v[170:173], v[194:197], v[100:103]
	v_mfma_f32_16x16x32_bf16 v[96:99], v[178:181], v[194:197], v[96:99]
	v_mfma_f32_16x16x32_bf16 v[84:87], v[170:173], v[202:205], v[84:87]
	v_mfma_f32_16x16x32_bf16 v[80:83], v[178:181], v[202:205], v[80:83]
	v_mfma_f32_16x16x32_bf16 v[68:71], v[170:173], v[210:213], v[68:71]
	v_mfma_f32_16x16x32_bf16 v[64:67], v[178:181], v[210:213], v[64:67]
	s_setprio 0
	s_barrier
	s_add_i32 s65, s61, s11
	v_lshl_add_u64 v[218:219], s[50:51], 0, v[130:131]
	s_mov_b32 m0, s65
	ds_read_b128 v[182:185], v153 offset:16384
	ds_read_b128 v[186:189], v153 offset:17408
	ds_read_b128 v[190:193], v153 offset:18432
	ds_read_b128 v[194:197], v153 offset:19456
	ds_read_b128 v[198:201], v153 offset:20480
	ds_read_b128 v[202:205], v153 offset:21504
	ds_read_b128 v[206:209], v153 offset:22528
	ds_read_b128 v[210:213], v153 offset:23552
	global_load_lds_dwordx4 v[218:219], off
	s_add_i32 m0, s65, 0x2000
	s_add_u32 s66, s50, 0x100000
	v_lshl_add_u64 v[220:221], s[50:51], 0, v[134:135]
	s_addc_u32 s67, s51, 0
	s_add_i32 s65, s62, s11
	global_load_lds_dwordx4 v[220:221], off
	v_lshl_add_u64 v[222:223], s[66:67], 0, v[130:131]
	s_mov_b32 m0, s65
	v_lshl_add_u64 v[224:225], s[54:55], 0, v[132:133]
	global_load_lds_dwordx4 v[222:223], off
	v_lshl_add_u64 v[222:223], s[66:67], 0, v[134:135]
	s_add_i32 m0, s65, 0x2000
	s_nop 0
	global_load_lds_dwordx4 v[222:223], off
	v_lshl_add_u64 v[222:223], s[54:55], 0, v[128:129]
	s_mov_b32 m0, s12
	s_nop 0
	global_load_lds_dwordx4 v[222:223], off
	s_mov_b32 m0, s13
	s_nop 0
	global_load_lds_dwordx4 v[224:225], off
	s_mov_b64 vcc, s[100:101]
	s_cbranch_vccnz .Lrlx_P6_1
	s_waitcnt vmcnt(8)
; #define PG8_STAGE(bufoff, gbase, voff) do { _Pragma("unroll") for (int _i = 0; _i < 2; ++_i) \
;         __builtin_amdgcn_global_load_lds((const unsigned*)((const char*)(gbase) + (voff)[_i]), (PG8_LAS unsigned*)(lds + (bufoff) + ldsw + _i * 8192), 16, 0, 0); } while (0)
; #define PG8_LDA(dst, b, h) do { _Pragma("unroll") for (int m = 0; m < 4; ++m) _Pragma("unroll") for (int k = 0; k < 2; ++k) dst[m][k] = *(const PG8_LAS bf16x8*)(lds + PG8_SA(b, h) + aoff + m * 2048 + k * 1024); } while (0)
; #define PG8_LDB(dst, b, h) do { _Pragma("unroll") for (int n = 0; n < 2; ++n) _Pragma("unroll") for (int k = 0; k < 2; ++k) dst[n][k] = *(const PG8_LAS bf16x8*)(lds + PG8_SB(b, h) + boff + n * 2048 + k * 1024); } while (0)
; #define PG8_MMA(ai, bj, At, Bt) do { __builtin_amdgcn_s_setprio(1); _Pragma("unroll") for (int m = 0; m < 4; ++m) _Pragma("unroll") for (int n = 0; n < 2; ++n) _Pragma("unroll") for (int k = 0; k < 2; ++k) \
;         acc[ai][bj][m][n] = __builtin_amdgcn_mfma_f32_16x16x32_bf16(Bt[n][k], At[m][k], acc[ai][bj][m][n], 0, 0, 0); __builtin_amdgcn_s_setprio(0); } while (0)
; #define PG8_WAIT_V(n) asm volatile("s_waitcnt vmcnt(" #n ")" ::: "memory")
; #define PG8_WAIT_L(n) asm volatile("s_waitcnt lgkmcnt(" #n ")" ::: "memory")
; #define PG8_BAR __builtin_amdgcn_s_barrier()
; #define PG8_SCHED __builtin_amdgcn_sched_barrier(0)
; template <class Epi, class Sched, bool ALIGN_EPI = false, bool SP2 = false>
; __device__ __forceinline__ void gemm_phase(PG8_LAS unsigned char* lds, const Gemm g, const Sched& S, const Epi& E, const int wave_s) {
;     ...
;             PG8_WAIT_V(8); PG8_WAIT_L(0); PG8_BAR; PG8_MMA(1, 0, At, B0); PG8_MMA(1, 1, At, B1); PG8_BAR; PG8_SCHED;
;             PG8_LDB(B0, 1, 0); PG8_LDB(B1, 1, 1); PG8_SCHED; PG8_LDA(At, 1, 0); PG8_STAGE(PG8_SA(0, 1), a2 + hA, voffA);
;             PG8_WAIT_V(8); PG8_WAIT_L(0); PG8_BAR; PG8_MMA(0, 0, At, B0); PG8_MMA(0, 1, At, B1); PG8_BAR; PG8_SCHED;
.Lrlx_P6_1:
	s_mov_b64 s[100:101], 0
	s_waitcnt lgkmcnt(0)
	s_barrier
	s_setprio 1
	s_waitcnt lgkmcnt(0)
	v_mfma_f32_16x16x32_bf16 v[60:63], v[144:147], v[182:185], v[60:63]
	v_mfma_f32_16x16x32_bf16 v[56:59], v[158:161], v[182:185], v[56:59]
	v_mfma_f32_16x16x32_bf16 v[44:47], v[144:147], v[190:193], v[44:47]
	v_mfma_f32_16x16x32_bf16 v[40:43], v[158:161], v[190:193], v[40:43]
	v_mfma_f32_16x16x32_bf16 v[28:31], v[144:147], v[198:201], v[28:31]
	v_mfma_f32_16x16x32_bf16 v[24:27], v[158:161], v[198:201], v[24:27]
	v_mfma_f32_16x16x32_bf16 v[12:15], v[144:147], v[206:209], v[12:15]
	v_mfma_f32_16x16x32_bf16 v[8:11], v[158:161], v[206:209], v[8:11]
	v_mfma_f32_16x16x32_bf16 v[60:63], v[154:157], v[186:189], v[60:63]
	v_mfma_f32_16x16x32_bf16 v[56:59], v[162:165], v[186:189], v[56:59]
	v_mfma_f32_16x16x32_bf16 v[44:47], v[154:157], v[194:197], v[44:47]
	v_mfma_f32_16x16x32_bf16 v[40:43], v[162:165], v[194:197], v[40:43]
	v_mfma_f32_16x16x32_bf16 v[28:31], v[154:157], v[202:205], v[28:31]
	v_mfma_f32_16x16x32_bf16 v[24:27], v[162:165], v[202:205], v[24:27]
	v_mfma_f32_16x16x32_bf16 v[12:15], v[154:157], v[210:213], v[12:15]
	v_mfma_f32_16x16x32_bf16 v[8:11], v[162:165], v[210:213], v[8:11]
	s_setprio 0
	s_setprio 1
	v_mfma_f32_16x16x32_bf16 v[52:55], v[166:169], v[182:185], v[52:55]
	v_mfma_f32_16x16x32_bf16 v[48:51], v[174:177], v[182:185], v[48:51]
	v_mfma_f32_16x16x32_bf16 v[36:39], v[166:169], v[190:193], v[36:39]
	v_mfma_f32_16x16x32_bf16 v[32:35], v[174:177], v[190:193], v[32:35]
	v_mfma_f32_16x16x32_bf16 v[20:23], v[166:169], v[198:201], v[20:23]
	v_mfma_f32_16x16x32_bf16 v[16:19], v[174:177], v[198:201], v[16:19]
	v_mfma_f32_16x16x32_bf16 v[4:7], v[166:169], v[206:209], v[4:7]
	v_mfma_f32_16x16x32_bf16 v[0:3], v[174:177], v[206:209], v[0:3]
	v_mfma_f32_16x16x32_bf16 v[52:55], v[170:173], v[186:189], v[52:55]
	v_mfma_f32_16x16x32_bf16 v[48:51], v[178:181], v[186:189], v[48:51]
	v_mfma_f32_16x16x32_bf16 v[36:39], v[170:173], v[194:197], v[36:39]
	v_mfma_f32_16x16x32_bf16 v[32:35], v[178:181], v[194:197], v[32:35]
	v_mfma_f32_16x16x32_bf16 v[20:23], v[170:173], v[202:205], v[20:23]
	v_mfma_f32_16x16x32_bf16 v[16:19], v[178:181], v[202:205], v[16:19]
	v_mfma_f32_16x16x32_bf16 v[4:7], v[170:173], v[210:213], v[4:7]
	v_mfma_f32_16x16x32_bf16 v[0:3], v[178:181], v[210:213], v[0:3]
	s_setprio 0
	s_barrier
	s_add_i32 s65, 0, 0x18000
	s_add_i32 s66, 0, 0x1c000
	v_add_u32_e32 v162, s65, v149
	v_add_u32_e32 v178, s66, v149
	ds_read_b128 v[144:147], v162
	ds_read_b128 v[154:157], v162 offset:1024
	ds_read_b128 v[158:161], v162 offset:2048
	ds_read_b128 v[162:165], v162 offset:3072
	ds_read_b128 v[166:169], v178
	ds_read_b128 v[170:173], v178 offset:1024
	ds_read_b128 v[174:177], v178 offset:2048
	ds_read_b128 v[178:181], v178 offset:3072
	s_add_u32 s54, s54, 0x100000
	s_addc_u32 s55, s55, 0
	s_mov_b32 m0, s34
	v_lshl_add_u64 v[226:227], s[54:55], 0, v[128:129]
	ds_read_b128 v[182:185], v153 offset:32768
	ds_read_b128 v[186:189], v153 offset:33792
	ds_read_b128 v[190:193], v153 offset:34816
	ds_read_b128 v[194:197], v153 offset:35840
	ds_read_b128 v[198:201], v153 offset:36864
	ds_read_b128 v[202:205], v153 offset:37888
	ds_read_b128 v[206:209], v153 offset:38912
	ds_read_b128 v[210:213], v153 offset:39936
	global_load_lds_dwordx4 v[226:227], off
	v_lshl_add_u64 v[226:227], s[54:55], 0, v[132:133]
	s_mov_b32 m0, s35
	s_nop 0
	global_load_lds_dwordx4 v[226:227], off
	s_waitcnt vmcnt(8)
	s_waitcnt lgkmcnt(0)
	s_barrier
	s_setprio 1
	s_waitcnt lgkmcnt(0)
	v_mfma_f32_16x16x32_bf16 v[124:127], v[144:147], v[182:185], v[124:127]
	v_mfma_f32_16x16x32_bf16 v[120:123], v[158:161], v[182:185], v[120:123]
	v_mfma_f32_16x16x32_bf16 v[108:111], v[144:147], v[190:193], v[108:111]
	v_mfma_f32_16x16x32_bf16 v[104:107], v[158:161], v[190:193], v[104:107]
	v_mfma_f32_16x16x32_bf16 v[92:95], v[144:147], v[198:201], v[92:95]
	v_mfma_f32_16x16x32_bf16 v[88:91], v[158:161], v[198:201], v[88:91]
	v_mfma_f32_16x16x32_bf16 v[76:79], v[144:147], v[206:209], v[76:79]
	v_mfma_f32_16x16x32_bf16 v[72:75], v[158:161], v[206:209], v[72:75]
	v_mfma_f32_16x16x32_bf16 v[124:127], v[154:157], v[186:189], v[124:127]
	v_mfma_f32_16x16x32_bf16 v[120:123], v[162:165], v[186:189], v[120:123]
	v_mfma_f32_16x16x32_bf16 v[108:111], v[154:157], v[194:197], v[108:111]
	v_mfma_f32_16x16x32_bf16 v[104:107], v[162:165], v[194:197], v[104:107]
	v_mfma_f32_16x16x32_bf16 v[92:95], v[154:157], v[202:205], v[92:95]
	v_mfma_f32_16x16x32_bf16 v[88:91], v[162:165], v[202:205], v[88:91]
	v_mfma_f32_16x16x32_bf16 v[76:79], v[154:157], v[210:213], v[76:79]
	v_mfma_f32_16x16x32_bf16 v[72:75], v[162:165], v[210:213], v[72:75]
	s_setprio 0
	s_setprio 1
	v_mfma_f32_16x16x32_bf16 v[116:119], v[166:169], v[182:185], v[116:119]
	v_mfma_f32_16x16x32_bf16 v[112:115], v[174:177], v[182:185], v[112:115]
	v_mfma_f32_16x16x32_bf16 v[100:103], v[166:169], v[190:193], v[100:103]
	v_mfma_f32_16x16x32_bf16 v[96:99], v[174:177], v[190:193], v[96:99]
	v_mfma_f32_16x16x32_bf16 v[84:87], v[166:169], v[198:201], v[84:87]
	v_mfma_f32_16x16x32_bf16 v[80:83], v[174:177], v[198:201], v[80:83]
	v_mfma_f32_16x16x32_bf16 v[68:71], v[166:169], v[206:209], v[68:71]
	v_mfma_f32_16x16x32_bf16 v[64:67], v[174:177], v[206:209], v[64:67]
	v_mfma_f32_16x16x32_bf16 v[116:119], v[170:173], v[186:189], v[116:119]
	v_mfma_f32_16x16x32_bf16 v[112:115], v[178:181], v[186:189], v[112:115]
	v_mfma_f32_16x16x32_bf16 v[100:103], v[170:173], v[194:197], v[100:103]
	v_mfma_f32_16x16x32_bf16 v[96:99], v[178:181], v[194:197], v[96:99]
	v_mfma_f32_16x16x32_bf16 v[84:87], v[170:173], v[202:205], v[84:87]
	v_mfma_f32_16x16x32_bf16 v[80:83], v[178:181], v[202:205], v[80:83]
	v_mfma_f32_16x16x32_bf16 v[68:71], v[170:173], v[210:213], v[68:71]
	v_mfma_f32_16x16x32_bf16 v[64:67], v[178:181], v[210:213], v[64:67]
	s_setprio 0
	s_barrier
; #define PG8_STAGE(bufoff, gbase, voff) do { _Pragma("unroll") for (int _i = 0; _i < 2; ++_i) \
;         __builtin_amdgcn_global_load_lds((const unsigned*)((const char*)(gbase) + (voff)[_i]), (PG8_LAS unsigned*)(lds + (bufoff) + ldsw + _i * 8192), 16, 0, 0); } while (0)
; #define PG8_LDA(dst, b, h) do { _Pragma("unroll") for (int m = 0; m < 4; ++m) _Pragma("unroll") for (int k = 0; k < 2; ++k) dst[m][k] = *(const PG8_LAS bf16x8*)(lds + PG8_SA(b, h) + aoff + m * 2048 + k * 1024); } while (0)
; #define PG8_MMA(ai, bj, At, Bt) do { __builtin_amdgcn_s_setprio(1); _Pragma("unroll") for (int m = 0; m < 4; ++m) _Pragma("unroll") for (int n = 0; n < 2; ++n) _Pragma("unroll") for (int k = 0; k < 2; ++k) \
;         acc[ai][bj][m][n] = __builtin_amdgcn_mfma_f32_16x16x32_bf16(Bt[n][k], At[m][k], acc[ai][bj][m][n], 0, 0, 0); __builtin_amdgcn_s_setprio(0); } while (0)
; #define PG8_WAIT_V(n) asm volatile("s_waitcnt vmcnt(" #n ")" ::: "memory")
; #define PG8_WAIT_L(n) asm volatile("s_waitcnt lgkmcnt(" #n ")" ::: "memory")
; #define PG8_BAR __builtin_amdgcn_s_barrier()
; #define PG8_SCHED __builtin_amdgcn_sched_barrier(0)
;     __device__ __forceinline__ void operator()(const f32x4 (&acc)[2][2][4][2], const Unit& u, int wr, int wc, int fr, int fq) const {
;     ...
;             for (int m = 0; m < 4; ++m) { const size_t row = (size_t)(row0 + ai * HALF + m * 16); float s = 0.f;
; #pragma unroll
;                 for (int bj = 0; bj < 2; ++bj) { const size_t off = row * 1024 + col0 + bj * HALF; const u32x4 h = __builtin_nontemporal_load((const u32x4*)(HB + off));
; template <class Epi, class Sched, bool ALIGN_EPI = false, bool SP2 = false>
; __device__ __forceinline__ void gemm_phase(PG8_LAS unsigned char* lds, const Gemm g, const Sched& S, const Epi& E, const int wave_s) {
;     ...
;             PG8_LDA(At, 1, 1); PG8_STAGE(PG8_SB(1, 0), b3, voffB); PG8_STAGE(PG8_SB(1, 1), b3 + hB, voffB); PG8_STAGE(PG8_SA(1, 0), a3, voffA);
;             PG8_WAIT_V(8); PG8_WAIT_L(0); PG8_BAR; PG8_MMA(1, 0, At, B0); PG8_MMA(1, 1, At, B1); PG8_BAR; PG8_SCHED;
	s_add_i32 s54, s65, s11
	v_lshl_add_u64 v[218:219], v[218:219], 0, s[18:19]
	s_mov_b32 m0, s54
	ds_read_b128 v[182:185], v153 offset:49152
	ds_read_b128 v[186:189], v153 offset:50176
	ds_read_b128 v[190:193], v153 offset:51200
	ds_read_b128 v[194:197], v153 offset:52224
	ds_read_b128 v[198:201], v153 offset:53248
	ds_read_b128 v[202:205], v153 offset:54272
	ds_read_b128 v[206:209], v153 offset:55296
	ds_read_b128 v[210:213], v153 offset:56320
	global_load_lds_dwordx4 v[218:219], off
	s_add_i32 m0, s54, 0x2000
	s_add_u32 s50, s50, 0x100080
	v_lshl_add_u64 v[218:219], v[220:221], 0, s[18:19]
	s_addc_u32 s51, s51, 0
	s_add_i32 s54, s66, s11
	global_load_lds_dwordx4 v[218:219], off
	v_lshl_add_u64 v[218:219], s[50:51], 0, v[130:131]
	s_mov_b32 m0, s54
	s_nop 0
	global_load_lds_dwordx4 v[218:219], off
	v_lshl_add_u64 v[218:219], s[50:51], 0, v[134:135]
	s_add_i32 m0, s54, 0x2000
	s_nop 0
	global_load_lds_dwordx4 v[218:219], off
	v_lshl_add_u64 v[218:219], v[222:223], 0, s[18:19]
	s_mov_b32 m0, s56
	s_nop 0
	global_load_lds_dwordx4 v[218:219], off
	v_lshl_add_u64 v[218:219], v[224:225], 0, s[18:19]
	s_mov_b32 m0, s57
	s_nop 0
	global_load_lds_dwordx4 v[218:219], off
	s_waitcnt vmcnt(8)
	s_waitcnt lgkmcnt(0)
	s_barrier
	s_setprio 1
	s_waitcnt lgkmcnt(0)
	v_mfma_f32_16x16x32_bf16 v[60:63], v[144:147], v[182:185], v[60:63]
	v_mfma_f32_16x16x32_bf16 v[56:59], v[158:161], v[182:185], v[56:59]
	v_mfma_f32_16x16x32_bf16 v[44:47], v[144:147], v[190:193], v[44:47]
	v_mfma_f32_16x16x32_bf16 v[40:43], v[158:161], v[190:193], v[40:43]
	v_mfma_f32_16x16x32_bf16 v[28:31], v[144:147], v[198:201], v[28:31]
	v_mfma_f32_16x16x32_bf16 v[24:27], v[158:161], v[198:201], v[24:27]
	v_mfma_f32_16x16x32_bf16 v[12:15], v[144:147], v[206:209], v[12:15]
	v_mfma_f32_16x16x32_bf16 v[8:11], v[158:161], v[206:209], v[8:11]
	v_mfma_f32_16x16x32_bf16 v[60:63], v[154:157], v[186:189], v[60:63]
	v_mfma_f32_16x16x32_bf16 v[56:59], v[162:165], v[186:189], v[56:59]
	v_mfma_f32_16x16x32_bf16 v[44:47], v[154:157], v[194:197], v[44:47]
	v_mfma_f32_16x16x32_bf16 v[40:43], v[162:165], v[194:197], v[40:43]
	v_mfma_f32_16x16x32_bf16 v[28:31], v[154:157], v[202:205], v[28:31]
	v_mfma_f32_16x16x32_bf16 v[24:27], v[162:165], v[202:205], v[24:27]
	v_mfma_f32_16x16x32_bf16 v[12:15], v[154:157], v[210:213], v[12:15]
	v_mfma_f32_16x16x32_bf16 v[8:11], v[162:165], v[210:213], v[8:11]
	s_setprio 0
	s_setprio 1
	v_mfma_f32_16x16x32_bf16 v[52:55], v[166:169], v[182:185], v[52:55]
	v_mfma_f32_16x16x32_bf16 v[48:51], v[174:177], v[182:185], v[48:51]
	v_mfma_f32_16x16x32_bf16 v[36:39], v[166:169], v[190:193], v[36:39]
	v_mfma_f32_16x16x32_bf16 v[32:35], v[174:177], v[190:193], v[32:35]
	v_mfma_f32_16x16x32_bf16 v[20:23], v[166:169], v[198:201], v[20:23]
	v_mfma_f32_16x16x32_bf16 v[16:19], v[174:177], v[198:201], v[16:19]
	v_mfma_f32_16x16x32_bf16 v[4:7], v[166:169], v[206:209], v[4:7]
	v_mfma_f32_16x16x32_bf16 v[0:3], v[174:177], v[206:209], v[0:3]
	v_mfma_f32_16x16x32_bf16 v[52:55], v[170:173], v[186:189], v[52:55]
	v_mfma_f32_16x16x32_bf16 v[48:51], v[178:181], v[186:189], v[48:51]
	v_mfma_f32_16x16x32_bf16 v[36:39], v[170:173], v[194:197], v[36:39]
	v_mfma_f32_16x16x32_bf16 v[32:35], v[178:181], v[194:197], v[32:35]
	v_mfma_f32_16x16x32_bf16 v[20:23], v[170:173], v[202:205], v[20:23]
	v_mfma_f32_16x16x32_bf16 v[16:19], v[178:181], v[202:205], v[16:19]
	v_mfma_f32_16x16x32_bf16 v[4:7], v[170:173], v[210:213], v[4:7]
	v_mfma_f32_16x16x32_bf16 v[0:3], v[178:181], v[210:213], v[0:3]
	s_setprio 0
	s_barrier
	s_add_i32 s64, s64, 2
	s_add_u32 s48, s48, 0x100
	s_addc_u32 s49, s49, 0
	s_add_u32 s45, s45, 0x100
	s_addc_u32 s63, s63, 0
	s_cmp_gt_u32 s64, 61
	s_cbranch_scc0 .LBB0_856
	s_and_b64 vcc, exec, s[20:21]
	s_cbranch_vccz .LBB0_859
	s_barrier
.LBB0_859:
	s_mov_b64 s[100:101], -1
	v_lshl_add_u32 v146, s46, 8, v148
	v_ashrrev_i32_e32 v147, 31, v146
	v_lshl_or_b32 v144, s44, 8, v150
	v_lshlrev_b64 v[154:155], 11, v[146:147]
	v_ashrrev_i32_e32 v145, 31, v144
	v_lshl_add_u64 v[154:155], s[14:15], 0, v[154:155]
	v_lshl_add_u64 v[162:163], v[144:145], 1, v[154:155]
	global_load_dwordx4 v[172:175], v[162:163], off nt
	global_load_dwordx4 v[176:179], v[162:163], off offset:256 nt
	s_mov_b32 s99, 0
	s_mov_b32 s98, 0x8000
	v_lshl_add_u64 v[212:213], v[162:163], 0, s[98:99]
	global_load_dwordx4 v[180:183], v[212:213], off nt
	global_load_dwordx4 v[184:187], v[212:213], off offset:256 nt
	s_mov_b32 s98, 0x10000
	v_lshl_add_u64 v[212:213], v[162:163], 0, s[98:99]
	global_load_dwordx4 v[188:191], v[212:213], off nt
	global_load_dwordx4 v[192:195], v[212:213], off offset:256 nt
	s_mov_b32 s98, 0x18000
	v_lshl_add_u64 v[212:213], v[162:163], 0, s[98:99]
	global_load_dwordx4 v[196:199], v[212:213], off nt
	global_load_dwordx4 v[200:203], v[212:213], off offset:256 nt
	s_mov_b32 s98, 0x40000
	v_lshl_add_u64 v[212:213], v[162:163], 0, s[98:99]
	global_load_dwordx4 v[204:207], v[212:213], off nt
	global_load_dwordx4 v[208:211], v[212:213], off offset:256 nt
	s_mov_b32 s98, 0x48000
	v_lshl_add_u64 v[212:213], v[162:163], 0, s[98:99]
	global_load_dwordx4 v[228:231], v[212:213], off nt
	global_load_dwordx4 v[232:235], v[212:213], off offset:256 nt
	s_mov_b32 s98, 0x50000
	v_lshl_add_u64 v[212:213], v[162:163], 0, s[98:99]
	global_load_dwordx4 v[236:239], v[212:213], off nt
	global_load_dwordx4 v[240:243], v[212:213], off offset:256 nt
	s_mov_b32 s98, 0x58000
	v_lshl_add_u64 v[212:213], v[162:163], 0, s[98:99]
	global_load_dwordx4 v[244:247], v[212:213], off nt
	global_load_dwordx4 v[248:251], v[212:213], off offset:256 nt
	s_waitcnt vmcnt(14)
; __device__ __forceinline__ float bflo(unsigned w) { return __uint_as_float(w << 16); }
; __device__ __forceinline__ float bfhi(unsigned w) { return __uint_as_float(w & 0xffff0000u); }
; __device__ __forceinline__ u32x4 pk8(const f32x4 a, const f32x4 b) { u32x4 w; w.x = pkbf(a[0], a[1]); w.y = pkbf(a[2], a[3]); w.z = pkbf(b[0], b[1]); w.w = pkbf(b[2], b[3]); return w; }
; __device__ __forceinline__ float sumsq4(const f32x4 a) { return (a[0] * a[0] + a[1] * a[1]) + (a[2] * a[2] + a[3] * a[3]); }
;     __device__ __forceinline__ void operator()(const f32x4 (&acc)[2][2][4][2], const Unit& u, int wr, int wc, int fr, int fq) const {
;     ...
;             for (int m = 0; m < 4; ++m) { const size_t row = (size_t)(row0 + ai * HALF + m * 16); float s = 0.f;
; #pragma unroll
;                 for (int bj = 0; bj < 2; ++bj) { const size_t off = row * 1024 + col0 + bj * HALF; const u32x4 h = __builtin_nontemporal_load((const u32x4*)(HB + off));
;                     f32x4 a = acc[ai][bj][m][0], b = acc[ai][bj][m][1];
;                     a[0] += bflo(h.x); a[1] += bfhi(h.x); a[2] += bflo(h.y); a[3] += bfhi(h.y); b[0] += bflo(h.z); b[1] += bfhi(h.z); b[2] += bflo(h.w); b[3] += bfhi(h.w);
;                     s += sumsq4(a) + sumsq4(b); *(u32x4*)(HO + off) = pk8(a, b); }
;                 s += __shfl_xor(s, 16); s += __shfl_xor(s, 32);
;                 if (fq == 0) unsafeAtomicAdd(ss + row, s); }
	v_mov_b32_e32 v154, v172
	v_mov_b32_e32 v155, v173
	v_mov_b32_e32 v156, v174
	v_mov_b32_e32 v157, v175
	v_mov_b32_e32 v158, v176
	v_mov_b32_e32 v159, v177
	v_mov_b32_e32 v160, v178
	v_mov_b32_e32 v161, v179
	v_lshlrev_b32_e32 v164, 16, v154
	v_and_b32_e32 v165, 0xffff0000, v154
	v_lshlrev_b32_e32 v154, 16, v155
	v_and_b32_e32 v155, 0xffff0000, v155
	v_lshlrev_b32_e32 v166, 16, v156
	v_and_b32_e32 v167, 0xffff0000, v156
	v_lshlrev_b32_e32 v156, 16, v157
	v_and_b32_e32 v157, 0xffff0000, v157
	v_lshlrev_b32_e32 v168, 16, v158
	v_and_b32_e32 v169, 0xffff0000, v158
	v_lshlrev_b32_e32 v158, 16, v159
	v_and_b32_e32 v159, 0xffff0000, v159
	v_lshlrev_b32_e32 v170, 16, v160
	v_and_b32_e32 v171, 0xffff0000, v160
	v_lshlrev_b32_e32 v160, 16, v161
	v_and_b32_e32 v161, 0xffff0000, v161
	v_pk_add_f32 v[124:125], v[124:125], v[164:165]
	v_pk_add_f32 v[126:127], v[126:127], v[154:155]
	v_pk_add_f32 v[120:121], v[120:121], v[166:167]
	v_pk_add_f32 v[122:123], v[122:123], v[156:157]
	v_pk_add_f32 v[116:117], v[116:117], v[168:169]
	v_pk_add_f32 v[118:119], v[118:119], v[158:159]
	v_pk_add_f32 v[154:155], v[112:113], v[170:171]
	v_pk_add_f32 v[156:157], v[114:115], v[160:161]
	v_pk_mul_f32 v[114:115], v[124:125], v[124:125]
	v_pk_mul_f32 v[158:159], v[126:127], v[126:127]
	v_pk_mul_f32 v[160:161], v[120:121], v[120:121]
	v_pk_mul_f32 v[164:165], v[122:123], v[122:123]
	v_cvt_pk_bf16_f32 v112, v124, v125
	v_cvt_pk_bf16_f32 v113, v126, v127
	v_pk_mul_f32 v[124:125], v[116:117], v[116:117]
	v_pk_mul_f32 v[126:127], v[118:119], v[118:119]
	v_pk_mul_f32 v[166:167], v[154:155], v[154:155]
	v_pk_mul_f32 v[168:169], v[156:157], v[156:157]
	v_add_f32_e32 v166, v166, v167
	v_add_f32_e32 v168, v168, v169
	v_add_f32_e32 v126, v126, v127
	v_add_f32_e32 v124, v124, v125
	v_add_f32_e32 v125, v164, v165
	v_add_f32_e32 v127, v160, v161
	v_add_f32_e32 v158, v158, v159
	v_add_f32_e32 v114, v114, v115
	v_add_f32_e32 v115, v166, v168
	v_add_f32_e32 v124, v124, v126
	v_add_f32_e32 v125, v127, v125
	v_add_f32_e32 v114, v114, v158
	v_add_f32_e32 v115, v124, v115
	v_add_f32_e32 v114, v114, v125
	v_add_f32_e32 v124, v114, v115
	v_mov_b32_e32 v125, v124
	s_nop 1
	v_permlane16_swap_b32_e32 v125, v124
	v_cvt_pk_bf16_f32 v114, v120, v121
	v_cvt_pk_bf16_f32 v115, v122, v123
	global_store_dwordx4 v[162:163], v[112:115], off
	s_waitcnt lgkmcnt(0)
	s_nop 0
	v_add_f32_e32 v112, v124, v125
	v_mov_b32_e32 v113, v112
	s_nop 1
	v_permlane32_swap_b32_e32 v113, v112
	v_cvt_pk_bf16_f32 v114, v116, v117
	v_cvt_pk_bf16_f32 v115, v118, v119
	v_cvt_pk_bf16_f32 v116, v154, v155
	v_cvt_pk_bf16_f32 v117, v156, v157
	global_store_dwordx4 v[162:163], v[114:117], off offset:256
	s_and_saveexec_b64 s[44:45], s[2:3]
	s_cbranch_execz .LBB0_861
	v_lshl_add_u64 v[114:115], v[146:147], 2, s[0:1]
	s_waitcnt lgkmcnt(0)
	v_add_f32_e32 v112, v112, v113
	global_atomic_add_f32 v[114:115], v112, off
.LBB0_861:
	s_or_b64 exec, exec, s[44:45]
	v_or_b32_e32 v112, 16, v146
	s_waitcnt lgkmcnt(0)
	v_ashrrev_i32_e32 v113, 31, v112
	v_lshlrev_b64 v[114:115], 11, v[112:113]
	v_lshl_add_u64 v[114:115], s[14:15], 0, v[114:115]
	v_lshl_add_u64 v[122:123], v[144:145], 1, v[114:115]
	s_waitcnt vmcnt(14)
	v_mov_b32_e32 v114, v180
	v_mov_b32_e32 v115, v181
	v_mov_b32_e32 v116, v182
	v_mov_b32_e32 v117, v183
	v_mov_b32_e32 v118, v184
	v_mov_b32_e32 v119, v185
	v_mov_b32_e32 v120, v186
	v_mov_b32_e32 v121, v187
	v_lshlrev_b32_e32 v124, 16, v114
	v_and_b32_e32 v125, 0xffff0000, v114
	v_lshlrev_b32_e32 v114, 16, v115
	v_and_b32_e32 v115, 0xffff0000, v115
	v_lshlrev_b32_e32 v126, 16, v116
	v_and_b32_e32 v127, 0xffff0000, v116
	v_lshlrev_b32_e32 v116, 16, v117
	v_and_b32_e32 v117, 0xffff0000, v117
	s_waitcnt vmcnt(14)
	v_lshlrev_b32_e32 v154, 16, v118
	v_and_b32_e32 v155, 0xffff0000, v118
	v_lshlrev_b32_e32 v118, 16, v119
	v_and_b32_e32 v119, 0xffff0000, v119
	v_lshlrev_b32_e32 v156, 16, v120
	v_and_b32_e32 v157, 0xffff0000, v120
	v_lshlrev_b32_e32 v120, 16, v121
	v_and_b32_e32 v121, 0xffff0000, v121
	v_pk_add_f32 v[108:109], v[108:109], v[124:125]
	v_pk_add_f32 v[110:111], v[110:111], v[114:115]
	v_pk_add_f32 v[104:105], v[104:105], v[126:127]
	v_pk_add_f32 v[106:107], v[106:107], v[116:117]
	v_pk_add_f32 v[100:101], v[100:101], v[154:155]
	v_pk_add_f32 v[102:103], v[102:103], v[118:119]
	v_pk_add_f32 v[114:115], v[96:97], v[156:157]
	v_pk_add_f32 v[116:117], v[98:99], v[120:121]
	v_pk_mul_f32 v[98:99], v[108:109], v[108:109]
	v_pk_mul_f32 v[118:119], v[110:111], v[110:111]
	v_pk_mul_f32 v[120:121], v[104:105], v[104:105]
	v_pk_mul_f32 v[124:125], v[106:107], v[106:107]
	v_cvt_pk_bf16_f32 v96, v108, v109
	v_cvt_pk_bf16_f32 v97, v110, v111
	v_pk_mul_f32 v[108:109], v[100:101], v[100:101]
	v_pk_mul_f32 v[110:111], v[102:103], v[102:103]
	v_pk_mul_f32 v[126:127], v[114:115], v[114:115]
	v_pk_mul_f32 v[154:155], v[116:117], v[116:117]
	v_add_f32_e32 v126, v126, v127
	v_add_f32_e32 v147, v154, v155
	v_add_f32_e32 v110, v110, v111
	v_add_f32_e32 v108, v108, v109
	v_add_f32_e32 v109, v124, v125
	v_add_f32_e32 v111, v120, v121
	v_add_f32_e32 v118, v118, v119
	v_add_f32_e32 v98, v98, v99
	v_add_f32_e32 v99, v126, v147
	v_add_f32_e32 v108, v108, v110
	v_add_f32_e32 v109, v111, v109
	v_add_f32_e32 v98, v98, v118
	v_add_f32_e32 v99, v108, v99
	v_add_f32_e32 v98, v98, v109
	v_add_f32_e32 v108, v98, v99
	v_mov_b32_e32 v109, v108
	s_nop 1
	v_permlane16_swap_b32_e32 v109, v108
	v_cvt_pk_bf16_f32 v98, v104, v105
	v_cvt_pk_bf16_f32 v99, v106, v107
	global_store_dwordx4 v[122:123], v[96:99], off
	s_waitcnt lgkmcnt(0)
	s_nop 0
	v_add_f32_e32 v96, v108, v109
	v_mov_b32_e32 v97, v96
	s_nop 1
	v_permlane32_swap_b32_e32 v97, v96
	v_cvt_pk_bf16_f32 v98, v100, v101
	v_cvt_pk_bf16_f32 v99, v102, v103
	v_cvt_pk_bf16_f32 v100, v114, v115
	v_cvt_pk_bf16_f32 v101, v116, v117
	global_store_dwordx4 v[122:123], v[98:101], off offset:256
	s_and_saveexec_b64 s[44:45], s[2:3]
	s_cbranch_execz .LBB0_863
	v_lshl_add_u64 v[98:99], v[112:113], 2, s[0:1]
	s_waitcnt lgkmcnt(0)
	v_add_f32_e32 v96, v96, v97
	global_atomic_add_f32 v[98:99], v96, off
; __device__ __forceinline__ float bflo(unsigned w) { return __uint_as_float(w << 16); }
; __device__ __forceinline__ float bfhi(unsigned w) { return __uint_as_float(w & 0xffff0000u); }
; __device__ __forceinline__ u32x4 pk8(const f32x4 a, const f32x4 b) { u32x4 w; w.x = pkbf(a[0], a[1]); w.y = pkbf(a[2], a[3]); w.z = pkbf(b[0], b[1]); w.w = pkbf(b[2], b[3]); return w; }
; __device__ __forceinline__ float sumsq4(const f32x4 a) { return (a[0] * a[0] + a[1] * a[1]) + (a[2] * a[2] + a[3] * a[3]); }
;     __device__ __forceinline__ void operator()(const f32x4 (&acc)[2][2][4][2], const Unit& u, int wr, int wc, int fr, int fq) const {
;     ...
;             for (int m = 0; m < 4; ++m) { const size_t row = (size_t)(row0 + ai * HALF + m * 16); float s = 0.f;
; #pragma unroll
;                 for (int bj = 0; bj < 2; ++bj) { const size_t off = row * 1024 + col0 + bj * HALF; const u32x4 h = __builtin_nontemporal_load((const u32x4*)(HB + off));
;                     f32x4 a = acc[ai][bj][m][0], b = acc[ai][bj][m][1];
;                     a[0] += bflo(h.x); a[1] += bfhi(h.x); a[2] += bflo(h.y); a[3] += bfhi(h.y); b[0] += bflo(h.z); b[1] += bfhi(h.z); b[2] += bflo(h.w); b[3] += bfhi(h.w);
;                     s += sumsq4(a) + sumsq4(b); *(u32x4*)(HO + off) = pk8(a, b); }
;                 s += __shfl_xor(s, 16); s += __shfl_xor(s, 32);
;                 if (fq == 0) unsafeAtomicAdd(ss + row, s); }
.LBB0_863:
	s_or_b64 exec, exec, s[44:45]
	v_or_b32_e32 v96, 32, v146
	s_waitcnt lgkmcnt(0)
	v_ashrrev_i32_e32 v97, 31, v96
	v_lshlrev_b64 v[98:99], 11, v[96:97]
	v_lshl_add_u64 v[98:99], s[14:15], 0, v[98:99]
	v_lshl_add_u64 v[106:107], v[144:145], 1, v[98:99]
	s_waitcnt vmcnt(14)
	v_mov_b32_e32 v98, v188
	v_mov_b32_e32 v99, v189
	v_mov_b32_e32 v100, v190
	v_mov_b32_e32 v101, v191
	v_mov_b32_e32 v102, v192
	v_mov_b32_e32 v103, v193
	v_mov_b32_e32 v104, v194
	v_mov_b32_e32 v105, v195
	v_lshlrev_b32_e32 v108, 16, v98
	v_and_b32_e32 v109, 0xffff0000, v98
	v_lshlrev_b32_e32 v98, 16, v99
	v_and_b32_e32 v99, 0xffff0000, v99
	v_lshlrev_b32_e32 v110, 16, v100
	v_and_b32_e32 v111, 0xffff0000, v100
	v_lshlrev_b32_e32 v100, 16, v101
	v_and_b32_e32 v101, 0xffff0000, v101
	s_waitcnt vmcnt(14)
	v_lshlrev_b32_e32 v112, 16, v102
	v_and_b32_e32 v113, 0xffff0000, v102
	v_lshlrev_b32_e32 v102, 16, v103
	v_and_b32_e32 v103, 0xffff0000, v103
	v_lshlrev_b32_e32 v114, 16, v104
	v_and_b32_e32 v115, 0xffff0000, v104
	v_lshlrev_b32_e32 v104, 16, v105
	v_and_b32_e32 v105, 0xffff0000, v105
	v_pk_add_f32 v[92:93], v[92:93], v[108:109]
	v_pk_add_f32 v[94:95], v[94:95], v[98:99]
	v_pk_add_f32 v[88:89], v[88:89], v[110:111]
	v_pk_add_f32 v[90:91], v[90:91], v[100:101]
	v_pk_add_f32 v[84:85], v[84:85], v[112:113]
	v_pk_add_f32 v[86:87], v[86:87], v[102:103]
	v_pk_add_f32 v[98:99], v[80:81], v[114:115]
	v_pk_add_f32 v[100:101], v[82:83], v[104:105]
	v_pk_mul_f32 v[82:83], v[92:93], v[92:93]
	v_pk_mul_f32 v[102:103], v[94:95], v[94:95]
	v_pk_mul_f32 v[104:105], v[88:89], v[88:89]
	v_pk_mul_f32 v[108:109], v[90:91], v[90:91]
	v_cvt_pk_bf16_f32 v80, v92, v93
	v_cvt_pk_bf16_f32 v81, v94, v95
	v_pk_mul_f32 v[92:93], v[84:85], v[84:85]
	v_pk_mul_f32 v[94:95], v[86:87], v[86:87]
	v_pk_mul_f32 v[110:111], v[98:99], v[98:99]
	v_pk_mul_f32 v[112:113], v[100:101], v[100:101]
	v_add_f32_e32 v110, v110, v111
	v_add_f32_e32 v112, v112, v113
	v_add_f32_e32 v94, v94, v95
	v_add_f32_e32 v92, v92, v93
	v_add_f32_e32 v93, v108, v109
	v_add_f32_e32 v95, v104, v105
	v_add_f32_e32 v102, v102, v103
	v_add_f32_e32 v82, v82, v83
	v_add_f32_e32 v83, v110, v112
	v_add_f32_e32 v92, v92, v94
	v_add_f32_e32 v93, v95, v93
	v_add_f32_e32 v82, v82, v102
	v_add_f32_e32 v83, v92, v83
	v_add_f32_e32 v82, v82, v93
	v_add_f32_e32 v92, v82, v83
	v_mov_b32_e32 v93, v92
	s_nop 1
	v_permlane16_swap_b32_e32 v93, v92
	v_cvt_pk_bf16_f32 v82, v88, v89
	v_cvt_pk_bf16_f32 v83, v90, v91
	global_store_dwordx4 v[106:107], v[80:83], off
	s_waitcnt lgkmcnt(0)
	s_nop 0
	v_add_f32_e32 v80, v92, v93
	v_mov_b32_e32 v81, v80
	s_nop 1
	v_permlane32_swap_b32_e32 v81, v80
	v_cvt_pk_bf16_f32 v82, v84, v85
	v_cvt_pk_bf16_f32 v83, v86, v87
	v_cvt_pk_bf16_f32 v84, v98, v99
	v_cvt_pk_bf16_f32 v85, v100, v101
	global_store_dwordx4 v[106:107], v[82:85], off offset:256
	s_and_saveexec_b64 s[44:45], s[2:3]
	s_cbranch_execz .LBB0_865
	v_lshl_add_u64 v[82:83], v[96:97], 2, s[0:1]
	s_waitcnt lgkmcnt(0)
	v_add_f32_e32 v80, v80, v81
	global_atomic_add_f32 v[82:83], v80, off
.LBB0_865:
	s_or_b64 exec, exec, s[44:45]
	v_or_b32_e32 v80, 48, v146
	s_waitcnt lgkmcnt(0)
	v_ashrrev_i32_e32 v81, 31, v80
	v_lshlrev_b64 v[82:83], 11, v[80:81]
	v_lshl_add_u64 v[82:83], s[14:15], 0, v[82:83]
	v_lshl_add_u64 v[90:91], v[144:145], 1, v[82:83]
	s_waitcnt vmcnt(14)
	v_mov_b32_e32 v82, v196
	v_mov_b32_e32 v83, v197
	v_mov_b32_e32 v84, v198
	v_mov_b32_e32 v85, v199
	v_mov_b32_e32 v86, v200
	v_mov_b32_e32 v87, v201
	v_mov_b32_e32 v88, v202
	v_mov_b32_e32 v89, v203
	v_lshlrev_b32_e32 v92, 16, v82
	v_and_b32_e32 v93, 0xffff0000, v82
	v_lshlrev_b32_e32 v82, 16, v83
	v_and_b32_e32 v83, 0xffff0000, v83
	v_lshlrev_b32_e32 v94, 16, v84
	v_and_b32_e32 v95, 0xffff0000, v84
	v_lshlrev_b32_e32 v84, 16, v85
	v_and_b32_e32 v85, 0xffff0000, v85
	s_waitcnt vmcnt(14)
	v_lshlrev_b32_e32 v96, 16, v86
	v_and_b32_e32 v97, 0xffff0000, v86
	v_lshlrev_b32_e32 v86, 16, v87
	v_and_b32_e32 v87, 0xffff0000, v87
	v_lshlrev_b32_e32 v98, 16, v88
	v_and_b32_e32 v99, 0xffff0000, v88
	v_lshlrev_b32_e32 v88, 16, v89
	v_and_b32_e32 v89, 0xffff0000, v89
	v_pk_add_f32 v[76:77], v[76:77], v[92:93]
	v_pk_add_f32 v[78:79], v[78:79], v[82:83]
	v_pk_add_f32 v[72:73], v[72:73], v[94:95]
	v_pk_add_f32 v[74:75], v[74:75], v[84:85]
	v_pk_add_f32 v[68:69], v[68:69], v[96:97]
	v_pk_add_f32 v[70:71], v[70:71], v[86:87]
	v_pk_add_f32 v[82:83], v[64:65], v[98:99]
	v_pk_add_f32 v[84:85], v[66:67], v[88:89]
	v_pk_mul_f32 v[66:67], v[76:77], v[76:77]
	v_pk_mul_f32 v[86:87], v[78:79], v[78:79]
	v_pk_mul_f32 v[88:89], v[72:73], v[72:73]
	v_pk_mul_f32 v[92:93], v[74:75], v[74:75]
	v_cvt_pk_bf16_f32 v64, v76, v77
	v_cvt_pk_bf16_f32 v65, v78, v79
	v_pk_mul_f32 v[76:77], v[68:69], v[68:69]
	v_pk_mul_f32 v[78:79], v[70:71], v[70:71]
	v_pk_mul_f32 v[94:95], v[82:83], v[82:83]
	v_pk_mul_f32 v[96:97], v[84:85], v[84:85]
	v_add_f32_e32 v94, v94, v95
	v_add_f32_e32 v96, v96, v97
	v_add_f32_e32 v78, v78, v79
	v_add_f32_e32 v76, v76, v77
	v_add_f32_e32 v77, v92, v93
	v_add_f32_e32 v79, v88, v89
	v_add_f32_e32 v86, v86, v87
	v_add_f32_e32 v66, v66, v67
	v_add_f32_e32 v67, v94, v96
	v_add_f32_e32 v76, v76, v78
	v_add_f32_e32 v77, v79, v77
	v_add_f32_e32 v66, v66, v86
	v_add_f32_e32 v67, v76, v67
	v_add_f32_e32 v66, v66, v77
	v_add_f32_e32 v76, v66, v67
	v_mov_b32_e32 v77, v76
	s_nop 1
	v_permlane16_swap_b32_e32 v77, v76
	v_cvt_pk_bf16_f32 v66, v72, v73
	v_cvt_pk_bf16_f32 v67, v74, v75
	global_store_dwordx4 v[90:91], v[64:67], off
	s_waitcnt lgkmcnt(0)
	s_nop 0
	v_add_f32_e32 v64, v76, v77
	v_mov_b32_e32 v65, v64
	s_nop 1
	v_permlane32_swap_b32_e32 v65, v64
	v_cvt_pk_bf16_f32 v66, v68, v69
	v_cvt_pk_bf16_f32 v67, v70, v71
	v_cvt_pk_bf16_f32 v68, v82, v83
	v_cvt_pk_bf16_f32 v69, v84, v85
	global_store_dwordx4 v[90:91], v[66:69], off offset:256
	s_and_saveexec_b64 s[44:45], s[2:3]
	s_cbranch_execz .LBB0_867
	v_lshl_add_u64 v[66:67], v[80:81], 2, s[0:1]
	s_waitcnt lgkmcnt(0)
	v_add_f32_e32 v64, v64, v65
	global_atomic_add_f32 v[66:67], v64, off
; __device__ __forceinline__ float bflo(unsigned w) { return __uint_as_float(w << 16); }
; __device__ __forceinline__ float bfhi(unsigned w) { return __uint_as_float(w & 0xffff0000u); }
; __device__ __forceinline__ u32x4 pk8(const f32x4 a, const f32x4 b) { u32x4 w; w.x = pkbf(a[0], a[1]); w.y = pkbf(a[2], a[3]); w.z = pkbf(b[0], b[1]); w.w = pkbf(b[2], b[3]); return w; }
; __device__ __forceinline__ float sumsq4(const f32x4 a) { return (a[0] * a[0] + a[1] * a[1]) + (a[2] * a[2] + a[3] * a[3]); }
;     __device__ __forceinline__ void operator()(const f32x4 (&acc)[2][2][4][2], const Unit& u, int wr, int wc, int fr, int fq) const {
;     ...
;             for (int m = 0; m < 4; ++m) { const size_t row = (size_t)(row0 + ai * HALF + m * 16); float s = 0.f;
; #pragma unroll
;                 for (int bj = 0; bj < 2; ++bj) { const size_t off = row * 1024 + col0 + bj * HALF; const u32x4 h = __builtin_nontemporal_load((const u32x4*)(HB + off));
;                     f32x4 a = acc[ai][bj][m][0], b = acc[ai][bj][m][1];
;                     a[0] += bflo(h.x); a[1] += bfhi(h.x); a[2] += bflo(h.y); a[3] += bfhi(h.y); b[0] += bflo(h.z); b[1] += bfhi(h.z); b[2] += bflo(h.w); b[3] += bfhi(h.w);
;                     s += sumsq4(a) + sumsq4(b); *(u32x4*)(HO + off) = pk8(a, b); }
;                 s += __shfl_xor(s, 16); s += __shfl_xor(s, 32);
;                 if (fq == 0) unsafeAtomicAdd(ss + row, s); }
.LBB0_867:
	s_or_b64 exec, exec, s[44:45]
	v_add_u32_e32 v64, 0x80, v146
	s_waitcnt lgkmcnt(0)
	v_ashrrev_i32_e32 v65, 31, v64
	v_lshlrev_b64 v[66:67], 11, v[64:65]
	v_lshl_add_u64 v[66:67], s[14:15], 0, v[66:67]
	v_lshl_add_u64 v[74:75], v[144:145], 1, v[66:67]
	s_waitcnt vmcnt(14)
	v_mov_b32_e32 v66, v204
	v_mov_b32_e32 v67, v205
	v_mov_b32_e32 v68, v206
	v_mov_b32_e32 v69, v207
	v_mov_b32_e32 v70, v208
	v_mov_b32_e32 v71, v209
	v_mov_b32_e32 v72, v210
	v_mov_b32_e32 v73, v211
	v_lshlrev_b32_e32 v76, 16, v66
	v_and_b32_e32 v77, 0xffff0000, v66
	v_lshlrev_b32_e32 v66, 16, v67
	v_and_b32_e32 v67, 0xffff0000, v67
	v_lshlrev_b32_e32 v78, 16, v68
	v_and_b32_e32 v79, 0xffff0000, v68
	v_lshlrev_b32_e32 v68, 16, v69
	v_and_b32_e32 v69, 0xffff0000, v69
	s_waitcnt vmcnt(14)
	v_lshlrev_b32_e32 v80, 16, v70
	v_and_b32_e32 v81, 0xffff0000, v70
	v_lshlrev_b32_e32 v70, 16, v71
	v_and_b32_e32 v71, 0xffff0000, v71
	v_lshlrev_b32_e32 v82, 16, v72
	v_and_b32_e32 v83, 0xffff0000, v72
	v_lshlrev_b32_e32 v72, 16, v73
	v_and_b32_e32 v73, 0xffff0000, v73
	v_pk_add_f32 v[60:61], v[60:61], v[76:77]
	v_pk_add_f32 v[62:63], v[62:63], v[66:67]
	v_pk_add_f32 v[56:57], v[56:57], v[78:79]
	v_pk_add_f32 v[58:59], v[58:59], v[68:69]
	v_pk_add_f32 v[52:53], v[52:53], v[80:81]
	v_pk_add_f32 v[54:55], v[54:55], v[70:71]
	v_pk_add_f32 v[66:67], v[48:49], v[82:83]
	v_pk_add_f32 v[68:69], v[50:51], v[72:73]
	v_pk_mul_f32 v[50:51], v[60:61], v[60:61]
	v_pk_mul_f32 v[70:71], v[62:63], v[62:63]
	v_pk_mul_f32 v[72:73], v[56:57], v[56:57]
	v_pk_mul_f32 v[76:77], v[58:59], v[58:59]
	v_cvt_pk_bf16_f32 v48, v60, v61
	v_cvt_pk_bf16_f32 v49, v62, v63
	v_pk_mul_f32 v[60:61], v[52:53], v[52:53]
	v_pk_mul_f32 v[62:63], v[54:55], v[54:55]
	v_pk_mul_f32 v[78:79], v[66:67], v[66:67]
	v_pk_mul_f32 v[80:81], v[68:69], v[68:69]
	v_add_f32_e32 v78, v78, v79
	v_add_f32_e32 v80, v80, v81
	v_add_f32_e32 v62, v62, v63
	v_add_f32_e32 v60, v60, v61
	v_add_f32_e32 v61, v76, v77
	v_add_f32_e32 v63, v72, v73
	v_add_f32_e32 v70, v70, v71
	v_add_f32_e32 v50, v50, v51
	v_add_f32_e32 v51, v78, v80
	v_add_f32_e32 v60, v60, v62
	v_add_f32_e32 v61, v63, v61
	v_add_f32_e32 v50, v50, v70
	v_add_f32_e32 v51, v60, v51
	v_add_f32_e32 v50, v50, v61
	v_add_f32_e32 v60, v50, v51
	v_mov_b32_e32 v61, v60
	s_nop 1
	v_permlane16_swap_b32_e32 v61, v60
	v_cvt_pk_bf16_f32 v50, v56, v57
	v_cvt_pk_bf16_f32 v51, v58, v59
	global_store_dwordx4 v[74:75], v[48:51], off
	s_waitcnt lgkmcnt(0)
	s_nop 0
	v_add_f32_e32 v48, v60, v61
	v_mov_b32_e32 v49, v48
	s_nop 1
	v_permlane32_swap_b32_e32 v49, v48
	v_cvt_pk_bf16_f32 v50, v52, v53
	v_cvt_pk_bf16_f32 v51, v54, v55
	v_cvt_pk_bf16_f32 v52, v66, v67
	v_cvt_pk_bf16_f32 v53, v68, v69
	global_store_dwordx4 v[74:75], v[50:53], off offset:256
	s_and_saveexec_b64 s[44:45], s[2:3]
	s_cbranch_execz .LBB0_869
	v_lshl_add_u64 v[50:51], v[64:65], 2, s[0:1]
	s_waitcnt lgkmcnt(0)
	v_add_f32_e32 v48, v48, v49
	global_atomic_add_f32 v[50:51], v48, off
.LBB0_869:
	s_or_b64 exec, exec, s[44:45]
	v_add_u32_e32 v48, 0x90, v146
	s_waitcnt lgkmcnt(0)
	v_ashrrev_i32_e32 v49, 31, v48
	v_lshlrev_b64 v[50:51], 11, v[48:49]
	v_lshl_add_u64 v[50:51], s[14:15], 0, v[50:51]
	v_lshl_add_u64 v[58:59], v[144:145], 1, v[50:51]
	s_waitcnt vmcnt(14)
	v_mov_b32_e32 v50, v228
	v_mov_b32_e32 v51, v229
	v_mov_b32_e32 v52, v230
	v_mov_b32_e32 v53, v231
	v_mov_b32_e32 v54, v232
	v_mov_b32_e32 v55, v233
	v_mov_b32_e32 v56, v234
	v_mov_b32_e32 v57, v235
	v_lshlrev_b32_e32 v60, 16, v50
	v_and_b32_e32 v61, 0xffff0000, v50
	v_lshlrev_b32_e32 v50, 16, v51
	v_and_b32_e32 v51, 0xffff0000, v51
	v_lshlrev_b32_e32 v62, 16, v52
	v_and_b32_e32 v63, 0xffff0000, v52
	v_lshlrev_b32_e32 v52, 16, v53
	v_and_b32_e32 v53, 0xffff0000, v53
	s_waitcnt vmcnt(14)
	v_lshlrev_b32_e32 v64, 16, v54
	v_and_b32_e32 v65, 0xffff0000, v54
	v_lshlrev_b32_e32 v54, 16, v55
	v_and_b32_e32 v55, 0xffff0000, v55
	v_lshlrev_b32_e32 v66, 16, v56
	v_and_b32_e32 v67, 0xffff0000, v56
	v_lshlrev_b32_e32 v56, 16, v57
	v_and_b32_e32 v57, 0xffff0000, v57
	v_pk_add_f32 v[44:45], v[44:45], v[60:61]
	v_pk_add_f32 v[46:47], v[46:47], v[50:51]
	v_pk_add_f32 v[40:41], v[40:41], v[62:63]
	v_pk_add_f32 v[42:43], v[42:43], v[52:53]
	v_pk_add_f32 v[36:37], v[36:37], v[64:65]
	v_pk_add_f32 v[38:39], v[38:39], v[54:55]
	v_pk_add_f32 v[50:51], v[32:33], v[66:67]
	v_pk_add_f32 v[52:53], v[34:35], v[56:57]
	v_pk_mul_f32 v[34:35], v[44:45], v[44:45]
	v_pk_mul_f32 v[54:55], v[46:47], v[46:47]
	v_pk_mul_f32 v[56:57], v[40:41], v[40:41]
	v_pk_mul_f32 v[60:61], v[42:43], v[42:43]
	v_cvt_pk_bf16_f32 v32, v44, v45
	v_cvt_pk_bf16_f32 v33, v46, v47
	v_pk_mul_f32 v[44:45], v[36:37], v[36:37]
	v_pk_mul_f32 v[46:47], v[38:39], v[38:39]
	v_pk_mul_f32 v[62:63], v[50:51], v[50:51]
	v_pk_mul_f32 v[64:65], v[52:53], v[52:53]
	v_add_f32_e32 v62, v62, v63
	v_add_f32_e32 v64, v64, v65
	v_add_f32_e32 v46, v46, v47
	v_add_f32_e32 v44, v44, v45
	v_add_f32_e32 v45, v60, v61
	v_add_f32_e32 v47, v56, v57
	v_add_f32_e32 v54, v54, v55
	v_add_f32_e32 v34, v34, v35
	v_add_f32_e32 v35, v62, v64
	v_add_f32_e32 v44, v44, v46
	v_add_f32_e32 v45, v47, v45
	v_add_f32_e32 v34, v34, v54
	v_add_f32_e32 v35, v44, v35
	v_add_f32_e32 v34, v34, v45
	v_add_f32_e32 v44, v34, v35
	v_mov_b32_e32 v45, v44
	s_nop 1
	v_permlane16_swap_b32_e32 v45, v44
	v_cvt_pk_bf16_f32 v34, v40, v41
	v_cvt_pk_bf16_f32 v35, v42, v43
	global_store_dwordx4 v[58:59], v[32:35], off
	s_waitcnt lgkmcnt(0)
	s_nop 0
	v_add_f32_e32 v32, v44, v45
	v_mov_b32_e32 v33, v32
	s_nop 1
	v_permlane32_swap_b32_e32 v33, v32
	v_cvt_pk_bf16_f32 v34, v36, v37
	v_cvt_pk_bf16_f32 v35, v38, v39
	v_cvt_pk_bf16_f32 v36, v50, v51
	v_cvt_pk_bf16_f32 v37, v52, v53
	global_store_dwordx4 v[58:59], v[34:37], off offset:256
	s_and_saveexec_b64 s[44:45], s[2:3]
	s_cbranch_execz .LBB0_871
	v_lshl_add_u64 v[34:35], v[48:49], 2, s[0:1]
	s_waitcnt lgkmcnt(0)
	v_add_f32_e32 v32, v32, v33
	global_atomic_add_f32 v[34:35], v32, off
; __device__ __forceinline__ float bflo(unsigned w) { return __uint_as_float(w << 16); }
; __device__ __forceinline__ float bfhi(unsigned w) { return __uint_as_float(w & 0xffff0000u); }
; __device__ __forceinline__ u32x4 pk8(const f32x4 a, const f32x4 b) { u32x4 w; w.x = pkbf(a[0], a[1]); w.y = pkbf(a[2], a[3]); w.z = pkbf(b[0], b[1]); w.w = pkbf(b[2], b[3]); return w; }
; __device__ __forceinline__ float sumsq4(const f32x4 a) { return (a[0] * a[0] + a[1] * a[1]) + (a[2] * a[2] + a[3] * a[3]); }
;     __device__ __forceinline__ void operator()(const f32x4 (&acc)[2][2][4][2], const Unit& u, int wr, int wc, int fr, int fq) const {
;     ...
;             for (int m = 0; m < 4; ++m) { const size_t row = (size_t)(row0 + ai * HALF + m * 16); float s = 0.f;
; #pragma unroll
;                 for (int bj = 0; bj < 2; ++bj) { const size_t off = row * 1024 + col0 + bj * HALF; const u32x4 h = __builtin_nontemporal_load((const u32x4*)(HB + off));
;                     f32x4 a = acc[ai][bj][m][0], b = acc[ai][bj][m][1];
;                     a[0] += bflo(h.x); a[1] += bfhi(h.x); a[2] += bflo(h.y); a[3] += bfhi(h.y); b[0] += bflo(h.z); b[1] += bfhi(h.z); b[2] += bflo(h.w); b[3] += bfhi(h.w);
;                     s += sumsq4(a) + sumsq4(b); *(u32x4*)(HO + off) = pk8(a, b); }
;                 s += __shfl_xor(s, 16); s += __shfl_xor(s, 32);
;                 if (fq == 0) unsafeAtomicAdd(ss + row, s); }
.LBB0_871:
	s_or_b64 exec, exec, s[44:45]
	v_add_u32_e32 v32, 0xa0, v146
	s_waitcnt lgkmcnt(0)
	v_ashrrev_i32_e32 v33, 31, v32
	v_lshlrev_b64 v[34:35], 11, v[32:33]
	v_lshl_add_u64 v[34:35], s[14:15], 0, v[34:35]
	v_lshl_add_u64 v[42:43], v[144:145], 1, v[34:35]
	s_waitcnt vmcnt(14)
	v_mov_b32_e32 v34, v236
	v_mov_b32_e32 v35, v237
	v_mov_b32_e32 v36, v238
	v_mov_b32_e32 v37, v239
	v_mov_b32_e32 v38, v240
	v_mov_b32_e32 v39, v241
	v_mov_b32_e32 v40, v242
	v_mov_b32_e32 v41, v243
	v_lshlrev_b32_e32 v44, 16, v34
	v_and_b32_e32 v45, 0xffff0000, v34
	v_lshlrev_b32_e32 v34, 16, v35
	v_and_b32_e32 v35, 0xffff0000, v35
	v_lshlrev_b32_e32 v46, 16, v36
	v_and_b32_e32 v47, 0xffff0000, v36
	v_lshlrev_b32_e32 v36, 16, v37
	v_and_b32_e32 v37, 0xffff0000, v37
	s_waitcnt vmcnt(14)
	v_lshlrev_b32_e32 v48, 16, v38
	v_and_b32_e32 v49, 0xffff0000, v38
	v_lshlrev_b32_e32 v38, 16, v39
	v_and_b32_e32 v39, 0xffff0000, v39
	v_lshlrev_b32_e32 v50, 16, v40
	v_and_b32_e32 v51, 0xffff0000, v40
	v_lshlrev_b32_e32 v40, 16, v41
	v_and_b32_e32 v41, 0xffff0000, v41
	v_pk_add_f32 v[28:29], v[28:29], v[44:45]
	v_pk_add_f32 v[30:31], v[30:31], v[34:35]
	v_pk_add_f32 v[24:25], v[24:25], v[46:47]
	v_pk_add_f32 v[26:27], v[26:27], v[36:37]
	v_pk_add_f32 v[20:21], v[20:21], v[48:49]
	v_pk_add_f32 v[22:23], v[22:23], v[38:39]
	v_pk_add_f32 v[34:35], v[16:17], v[50:51]
	v_pk_add_f32 v[36:37], v[18:19], v[40:41]
	v_pk_mul_f32 v[18:19], v[28:29], v[28:29]
	v_pk_mul_f32 v[38:39], v[30:31], v[30:31]
	v_pk_mul_f32 v[40:41], v[24:25], v[24:25]
	v_pk_mul_f32 v[44:45], v[26:27], v[26:27]
	v_cvt_pk_bf16_f32 v16, v28, v29
	v_cvt_pk_bf16_f32 v17, v30, v31
	v_pk_mul_f32 v[28:29], v[20:21], v[20:21]
	v_pk_mul_f32 v[30:31], v[22:23], v[22:23]
	v_pk_mul_f32 v[46:47], v[34:35], v[34:35]
	v_pk_mul_f32 v[48:49], v[36:37], v[36:37]
	v_add_f32_e32 v46, v46, v47
	v_add_f32_e32 v48, v48, v49
	v_add_f32_e32 v30, v30, v31
	v_add_f32_e32 v28, v28, v29
	v_add_f32_e32 v29, v44, v45
	v_add_f32_e32 v31, v40, v41
	v_add_f32_e32 v38, v38, v39
	v_add_f32_e32 v18, v18, v19
	v_add_f32_e32 v19, v46, v48
	v_add_f32_e32 v28, v28, v30
	v_add_f32_e32 v29, v31, v29
	v_add_f32_e32 v18, v18, v38
	v_add_f32_e32 v19, v28, v19
	v_add_f32_e32 v18, v18, v29
	v_add_f32_e32 v28, v18, v19
	v_mov_b32_e32 v29, v28
	s_nop 1
	v_permlane16_swap_b32_e32 v29, v28
	v_cvt_pk_bf16_f32 v18, v24, v25
	v_cvt_pk_bf16_f32 v19, v26, v27
	global_store_dwordx4 v[42:43], v[16:19], off
	s_waitcnt lgkmcnt(0)
	s_nop 0
	v_add_f32_e32 v16, v28, v29
	v_mov_b32_e32 v17, v16
	s_nop 1
	v_permlane32_swap_b32_e32 v17, v16
	v_cvt_pk_bf16_f32 v18, v20, v21
	v_cvt_pk_bf16_f32 v19, v22, v23
	v_cvt_pk_bf16_f32 v20, v34, v35
	v_cvt_pk_bf16_f32 v21, v36, v37
	global_store_dwordx4 v[42:43], v[18:21], off offset:256
	s_and_saveexec_b64 s[44:45], s[2:3]
	s_cbranch_execz .LBB0_873
	v_lshl_add_u64 v[18:19], v[32:33], 2, s[0:1]
	s_waitcnt lgkmcnt(0)
	v_add_f32_e32 v16, v16, v17
	global_atomic_add_f32 v[18:19], v16, off
.LBB0_873:
	s_or_b64 exec, exec, s[44:45]
	v_add_u32_e32 v16, 0xb0, v146
	s_waitcnt lgkmcnt(0)
	v_ashrrev_i32_e32 v17, 31, v16
	v_lshlrev_b64 v[18:19], 11, v[16:17]
	v_lshl_add_u64 v[18:19], s[14:15], 0, v[18:19]
	v_lshl_add_u64 v[26:27], v[144:145], 1, v[18:19]
	s_waitcnt vmcnt(14)
	v_mov_b32_e32 v18, v244
	v_mov_b32_e32 v19, v245
	v_mov_b32_e32 v20, v246
	v_mov_b32_e32 v21, v247
	v_mov_b32_e32 v22, v248
	v_mov_b32_e32 v23, v249
	v_mov_b32_e32 v24, v250
	v_mov_b32_e32 v25, v251
	v_lshlrev_b32_e32 v28, 16, v18
	v_and_b32_e32 v29, 0xffff0000, v18
	v_lshlrev_b32_e32 v18, 16, v19
	v_and_b32_e32 v19, 0xffff0000, v19
	v_lshlrev_b32_e32 v30, 16, v20
	v_and_b32_e32 v31, 0xffff0000, v20
	v_lshlrev_b32_e32 v20, 16, v21
	v_and_b32_e32 v21, 0xffff0000, v21
	s_waitcnt vmcnt(14)
	v_lshlrev_b32_e32 v32, 16, v22
	v_and_b32_e32 v33, 0xffff0000, v22
	v_lshlrev_b32_e32 v22, 16, v23
	v_and_b32_e32 v23, 0xffff0000, v23
	v_lshlrev_b32_e32 v34, 16, v24
	v_and_b32_e32 v35, 0xffff0000, v24
	v_lshlrev_b32_e32 v24, 16, v25
	v_and_b32_e32 v25, 0xffff0000, v25
	v_pk_add_f32 v[12:13], v[12:13], v[28:29]
	v_pk_add_f32 v[14:15], v[14:15], v[18:19]
	v_pk_add_f32 v[8:9], v[8:9], v[30:31]
	v_pk_add_f32 v[10:11], v[10:11], v[20:21]
	v_pk_add_f32 v[4:5], v[4:5], v[32:33]
	v_pk_add_f32 v[6:7], v[6:7], v[22:23]
	v_pk_add_f32 v[18:19], v[0:1], v[34:35]
	v_pk_add_f32 v[20:21], v[2:3], v[24:25]
	v_pk_mul_f32 v[2:3], v[12:13], v[12:13]
	v_pk_mul_f32 v[22:23], v[14:15], v[14:15]
	v_pk_mul_f32 v[24:25], v[8:9], v[8:9]
	v_pk_mul_f32 v[28:29], v[10:11], v[10:11]
	v_cvt_pk_bf16_f32 v0, v12, v13
	v_cvt_pk_bf16_f32 v1, v14, v15
	v_pk_mul_f32 v[12:13], v[4:5], v[4:5]
	v_pk_mul_f32 v[14:15], v[6:7], v[6:7]
	v_pk_mul_f32 v[30:31], v[18:19], v[18:19]
	v_pk_mul_f32 v[32:33], v[20:21], v[20:21]
	v_add_f32_e32 v30, v30, v31
	v_add_f32_e32 v32, v32, v33
	v_add_f32_e32 v14, v14, v15
	v_add_f32_e32 v12, v12, v13
	v_add_f32_e32 v13, v28, v29
	v_add_f32_e32 v15, v24, v25
	v_add_f32_e32 v22, v22, v23
	v_add_f32_e32 v2, v2, v3
	v_add_f32_e32 v3, v30, v32
	v_add_f32_e32 v12, v12, v14
	v_add_f32_e32 v13, v15, v13
	v_add_f32_e32 v2, v2, v22
	v_add_f32_e32 v3, v12, v3
	v_add_f32_e32 v2, v2, v13
	v_add_f32_e32 v12, v2, v3
	v_mov_b32_e32 v13, v12
	s_nop 1
	v_permlane16_swap_b32_e32 v13, v12
	v_cvt_pk_bf16_f32 v2, v8, v9
	v_cvt_pk_bf16_f32 v3, v10, v11
	global_store_dwordx4 v[26:27], v[0:3], off
	s_waitcnt lgkmcnt(0)
	s_nop 0
	v_add_f32_e32 v0, v12, v13
	v_mov_b32_e32 v1, v0
	s_nop 1
	v_permlane32_swap_b32_e32 v1, v0
	v_cvt_pk_bf16_f32 v2, v4, v5
	v_cvt_pk_bf16_f32 v3, v6, v7
	v_cvt_pk_bf16_f32 v4, v18, v19
	v_cvt_pk_bf16_f32 v5, v20, v21
	global_store_dwordx4 v[26:27], v[2:5], off offset:256
	s_and_saveexec_b64 s[44:45], s[2:3]
	s_cbranch_execz .LBB0_875
	v_lshl_add_u64 v[2:3], v[16:17], 2, s[0:1]
	s_waitcnt lgkmcnt(0)
	v_add_f32_e32 v0, v0, v1
	global_atomic_add_f32 v[2:3], v0, off

; __global__ void __launch_bounds__(NWAVES * 64, 2) fwd_kernel(Args args) {
	.amdhsa_kernel _Z10fwd_kernel4Args
		.amdhsa_group_segment_fixed_size 0
		.amdhsa_private_segment_fixed_size 0
		.amdhsa_kernarg_size 392
		.amdhsa_user_sgpr_count 2
		.amdhsa_user_sgpr_dispatch_ptr 0
		.amdhsa_user_sgpr_queue_ptr 0
		.amdhsa_user_sgpr_kernarg_segment_ptr 1
		.amdhsa_user_sgpr_dispatch_id 0
		.amdhsa_user_sgpr_kernarg_preload_length 0
		.amdhsa_user_sgpr_kernarg_preload_offset 0
		.amdhsa_user_sgpr_private_segment_size 0
		.amdhsa_uses_dynamic_stack 0
		.amdhsa_enable_private_segment 0
		.amdhsa_system_sgpr_workgroup_id_x 1
		.amdhsa_system_sgpr_workgroup_id_y 0
		.amdhsa_system_sgpr_workgroup_id_z 0
		.amdhsa_system_sgpr_workgroup_info 0
		.amdhsa_system_vgpr_workitem_id 2
		.amdhsa_next_free_vgpr 256
		.amdhsa_next_free_sgpr 102
		.amdhsa_accum_offset 256
		.amdhsa_reserve_vcc 1
		.amdhsa_float_round_mode_32 0
		.amdhsa_float_round_mode_16_64 0
		.amdhsa_float_denorm_mode_32 3
		.amdhsa_float_denorm_mode_16_64 3
		.amdhsa_dx10_clamp 1
		.amdhsa_ieee_mode 1
		.amdhsa_fp16_overflow 0
		.amdhsa_tg_split 0
		.amdhsa_exception_fp_ieee_invalid_op 0
		.amdhsa_exception_fp_denorm_src 0
		.amdhsa_exception_fp_ieee_div_zero 0
		.amdhsa_exception_fp_ieee_overflow 0
		.amdhsa_exception_fp_ieee_underflow 0
		.amdhsa_exception_fp_ieee_inexact 0
		.amdhsa_exception_int_div_zero 0
	.end_amdhsa_kernel

; __global__ void __launch_bounds__(NWAVES * 64, 2) fwd_kernel(Args args) {
amdhsa.kernels:
  - .agpr_count:     0
    .args:
      - .offset:         0
        .size:           136
        .value_kind:     by_value
      - .offset:         136
        .size:           4
        .value_kind:     hidden_block_count_x
      - .offset:         140
        .size:           4
        .value_kind:     hidden_block_count_y
      - .offset:         144
        .size:           4
        .value_kind:     hidden_block_count_z
      - .offset:         148
        .size:           2
        .value_kind:     hidden_group_size_x
      - .offset:         150
        .size:           2
        .value_kind:     hidden_group_size_y
      - .offset:         152
        .size:           2
        .value_kind:     hidden_group_size_z
      - .offset:         154
        .size:           2
        .value_kind:     hidden_remainder_x
      - .offset:         156
        .size:           2
        .value_kind:     hidden_remainder_y
      - .offset:         158
        .size:           2
        .value_kind:     hidden_remainder_z
      - .offset:         176
        .size:           8
        .value_kind:     hidden_global_offset_x
      - .offset:         184
        .size:           8
        .value_kind:     hidden_global_offset_y
      - .offset:         192
        .size:           8
        .value_kind:     hidden_global_offset_z
      - .offset:         200
        .size:           2
        .value_kind:     hidden_grid_dims
      - .offset:         224
        .size:           8
        .value_kind:     hidden_multigrid_sync_arg
      - .offset:         256
        .size:           4
        .value_kind:     hidden_dynamic_lds_size
    .group_segment_fixed_size: 0
    .kernarg_segment_align: 8
    .kernarg_segment_size: 392
    .language:       OpenCL C
    .language_version:
      - 2
      - 0
    .max_flat_workgroup_size: 512
    .name:           _Z10fwd_kernel4Args
    .private_segment_fixed_size: 0
    .sgpr_count:     108
    .sgpr_spill_count: 7
    .symbol:         _Z10fwd_kernel4Args.kd
    .uniform_work_group_size: 1
    .uses_dynamic_stack: false
    .vgpr_count:     256
    .vgpr_spill_count: 0
    .wavefront_size: 64
